# K-loops: one static priority raise for the trailing wave half instead of per-cluster raise and lower in both halves
# speedup vs baseline: 1.0013x; 1.0013x over previous
.LBB0_165:
	s_add_u32 s16, s14, 0xfff80080
	s_addc_u32 s17, s15, -1
	s_cmp_eq_u32 s64, 28
	s_cselect_b32 s19, s1, s17
	s_cselect_b32 s18, s4, s16
	s_cselect_b32 s17, s11, s21
	s_cselect_b32 s16, s13, s20
	s_and_b64 vcc, exec, s[36:37]
	s_cbranch_vccz .Lk64_trail_p1
	s_sub_u32 vcc_lo, s20, 0x80
	s_subb_u32 vcc_hi, s21, 0
	s_add_i32 m0, s23, 0x18000
	s_nop 0
	global_load_lds_dwordx4 v130, vcc
	s_add_i32 m0, s23, 0x1a000
	s_nop 0
	global_load_lds_dwordx4 v134, vcc
	s_add_u32 vcc_lo, vcc_lo, 0x20000
	s_addc_u32 vcc_hi, vcc_hi, 0
	s_add_i32 m0, s23, 0x19000
	s_nop 0
	global_load_lds_dwordx4 v130, vcc
	s_add_i32 m0, s23, 0x1b000
	s_nop 0
	global_load_lds_dwordx4 v134, vcc
	s_add_u32 vcc_lo, vcc_lo, 0x60000
	s_addc_u32 vcc_hi, vcc_hi, 0
	s_add_i32 m0, s23, 0x1c000
	s_nop 0
	global_load_lds_dwordx4 v130, vcc
	s_add_i32 m0, s23, 0x1e000
	s_nop 0
	global_load_lds_dwordx4 v134, vcc
	s_add_u32 vcc_lo, vcc_lo, 0x20000
	s_addc_u32 vcc_hi, vcc_hi, 0
	s_add_i32 m0, s23, 0x1d000
	s_nop 0
	global_load_lds_dwordx4 v130, vcc
	s_add_i32 m0, s23, 0x1f000
	s_nop 0
	global_load_lds_dwordx4 v134, vcc
	ds_read_b128 v[148:151], v168 offset:0
	ds_read_b128 v[152:155], v168 offset:1024
	ds_read_b128 v[156:159], v168 offset:2048
	ds_read_b128 v[172:175], v168 offset:3072
	ds_read_b128 v[176:179], v169 offset:0
	ds_read_b128 v[180:183], v169 offset:1024
	ds_read_b128 v[184:187], v169 offset:2048
	ds_read_b128 v[188:191], v169 offset:3072
	ds_read_b128 v[192:195], v170 offset:0
	ds_read_b128 v[196:199], v170 offset:1024
	ds_read_b128 v[200:203], v170 offset:2048
	ds_read_b128 v[204:207], v170 offset:3072
	ds_read_b128 v[208:211], v170 offset:4096
	ds_read_b128 v[212:215], v170 offset:5120
	ds_read_b128 v[216:219], v170 offset:6144
	ds_read_b128 v[220:223], v170 offset:7168
	ds_read_b128 v[142:145], v170 offset:16384
	ds_read_b128 v[224:227], v170 offset:17408
	ds_read_b128 v[228:231], v170 offset:18432
	ds_read_b128 v[232:235], v170 offset:19456
	ds_read_b128 v[236:239], v170 offset:20480
	ds_read_b128 v[240:243], v170 offset:21504
	ds_read_b128 v[244:247], v170 offset:22528
	ds_read_b128 v[248:251], v170 offset:23552
	s_nop 15
	s_nop 15
	s_waitcnt lgkmcnt(0)
	s_barrier
	v_mfma_f32_16x16x32_bf16 v[124:127], v[148:151], v[192:195], v[124:127]
	v_mfma_f32_16x16x32_bf16 v[120:123], v[156:159], v[192:195], v[120:123]
	v_mfma_f32_16x16x32_bf16 v[116:119], v[148:151], v[200:203], v[116:119]
	v_mfma_f32_16x16x32_bf16 v[112:115], v[156:159], v[200:203], v[112:115]
	v_mfma_f32_16x16x32_bf16 v[100:103], v[148:151], v[208:211], v[100:103]
	v_mfma_f32_16x16x32_bf16 v[96:99], v[156:159], v[208:211], v[96:99]
	v_mfma_f32_16x16x32_bf16 v[84:87], v[148:151], v[216:219], v[84:87]
	v_mfma_f32_16x16x32_bf16 v[80:83], v[156:159], v[216:219], v[80:83]
	v_mfma_f32_16x16x32_bf16 v[124:127], v[152:155], v[196:199], v[124:127]
	v_mfma_f32_16x16x32_bf16 v[120:123], v[172:175], v[196:199], v[120:123]
	v_mfma_f32_16x16x32_bf16 v[116:119], v[152:155], v[204:207], v[116:119]
	v_mfma_f32_16x16x32_bf16 v[112:115], v[172:175], v[204:207], v[112:115]
	v_mfma_f32_16x16x32_bf16 v[100:103], v[152:155], v[212:215], v[100:103]
	v_mfma_f32_16x16x32_bf16 v[96:99], v[172:175], v[212:215], v[96:99]
	v_mfma_f32_16x16x32_bf16 v[84:87], v[152:155], v[220:223], v[84:87]
	v_mfma_f32_16x16x32_bf16 v[80:83], v[172:175], v[220:223], v[80:83]
	v_mfma_f32_16x16x32_bf16 v[108:111], v[176:179], v[192:195], v[108:111]
	v_mfma_f32_16x16x32_bf16 v[104:107], v[184:187], v[192:195], v[104:107]
	v_mfma_f32_16x16x32_bf16 v[92:95], v[176:179], v[200:203], v[92:95]
	v_mfma_f32_16x16x32_bf16 v[88:91], v[184:187], v[200:203], v[88:91]
	v_mfma_f32_16x16x32_bf16 v[76:79], v[176:179], v[208:211], v[76:79]
	v_mfma_f32_16x16x32_bf16 v[72:75], v[184:187], v[208:211], v[72:75]
	v_mfma_f32_16x16x32_bf16 v[68:71], v[176:179], v[216:219], v[68:71]
	v_mfma_f32_16x16x32_bf16 v[64:67], v[184:187], v[216:219], v[64:67]
	v_mfma_f32_16x16x32_bf16 v[108:111], v[180:183], v[196:199], v[108:111]
	v_mfma_f32_16x16x32_bf16 v[104:107], v[188:191], v[196:199], v[104:107]
	v_mfma_f32_16x16x32_bf16 v[92:95], v[180:183], v[204:207], v[92:95]
	v_mfma_f32_16x16x32_bf16 v[88:91], v[188:191], v[204:207], v[88:91]
	v_mfma_f32_16x16x32_bf16 v[76:79], v[180:183], v[212:215], v[76:79]
	v_mfma_f32_16x16x32_bf16 v[72:75], v[188:191], v[212:215], v[72:75]
	v_mfma_f32_16x16x32_bf16 v[68:71], v[180:183], v[220:223], v[68:71]
	v_mfma_f32_16x16x32_bf16 v[64:67], v[188:191], v[220:223], v[64:67]
	v_mfma_f32_16x16x32_bf16 v[60:63], v[148:151], v[142:145], v[60:63]
	v_mfma_f32_16x16x32_bf16 v[56:59], v[156:159], v[142:145], v[56:59]
	v_mfma_f32_16x16x32_bf16 v[52:55], v[148:151], v[228:231], v[52:55]
	v_mfma_f32_16x16x32_bf16 v[48:51], v[156:159], v[228:231], v[48:51]
	v_mfma_f32_16x16x32_bf16 v[36:39], v[148:151], v[236:239], v[36:39]
	v_mfma_f32_16x16x32_bf16 v[32:35], v[156:159], v[236:239], v[32:35]
	v_mfma_f32_16x16x32_bf16 v[20:23], v[148:151], v[244:247], v[20:23]
	v_mfma_f32_16x16x32_bf16 v[16:19], v[156:159], v[244:247], v[16:19]
	v_mfma_f32_16x16x32_bf16 v[60:63], v[152:155], v[224:227], v[60:63]
	v_mfma_f32_16x16x32_bf16 v[56:59], v[172:175], v[224:227], v[56:59]
	v_mfma_f32_16x16x32_bf16 v[52:55], v[152:155], v[232:235], v[52:55]
	v_mfma_f32_16x16x32_bf16 v[48:51], v[172:175], v[232:235], v[48:51]
	v_mfma_f32_16x16x32_bf16 v[36:39], v[152:155], v[240:243], v[36:39]
	v_mfma_f32_16x16x32_bf16 v[32:35], v[172:175], v[240:243], v[32:35]
	v_mfma_f32_16x16x32_bf16 v[20:23], v[152:155], v[248:251], v[20:23]
	v_mfma_f32_16x16x32_bf16 v[16:19], v[172:175], v[248:251], v[16:19]
	v_mfma_f32_16x16x32_bf16 v[44:47], v[176:179], v[142:145], v[44:47]
	v_mfma_f32_16x16x32_bf16 v[40:43], v[184:187], v[142:145], v[40:43]
	v_mfma_f32_16x16x32_bf16 v[28:31], v[176:179], v[228:231], v[28:31]
	v_mfma_f32_16x16x32_bf16 v[24:27], v[184:187], v[228:231], v[24:27]
	v_mfma_f32_16x16x32_bf16 v[12:15], v[176:179], v[236:239], v[12:15]
	v_mfma_f32_16x16x32_bf16 v[8:11], v[184:187], v[236:239], v[8:11]
	v_mfma_f32_16x16x32_bf16 v[4:7], v[176:179], v[244:247], v[4:7]
	v_mfma_f32_16x16x32_bf16 v[0:3], v[184:187], v[244:247], v[0:3]
	v_mfma_f32_16x16x32_bf16 v[44:47], v[180:183], v[224:227], v[44:47]
	v_mfma_f32_16x16x32_bf16 v[40:43], v[188:191], v[224:227], v[40:43]
	v_mfma_f32_16x16x32_bf16 v[28:31], v[180:183], v[232:235], v[28:31]
	v_mfma_f32_16x16x32_bf16 v[24:27], v[188:191], v[232:235], v[24:27]
	v_mfma_f32_16x16x32_bf16 v[12:15], v[180:183], v[240:243], v[12:15]
	v_mfma_f32_16x16x32_bf16 v[8:11], v[188:191], v[240:243], v[8:11]
	v_mfma_f32_16x16x32_bf16 v[4:7], v[180:183], v[248:251], v[4:7]
	v_mfma_f32_16x16x32_bf16 v[0:3], v[188:191], v[248:251], v[0:3]
	s_waitcnt vmcnt(0)
	s_barrier
	s_add_u32 vcc_lo, s16, 0x0
	s_addc_u32 vcc_hi, s17, 0
	s_add_i32 m0, s23, 0x10000
	s_nop 0
	global_load_lds_dwordx4 v130, vcc
	s_add_i32 m0, s23, 0x12000
	s_nop 0
	global_load_lds_dwordx4 v134, vcc
	s_add_u32 vcc_lo, vcc_lo, 0x20000
	s_addc_u32 vcc_hi, vcc_hi, 0
	s_add_i32 m0, s23, 0x11000
	s_nop 0
	global_load_lds_dwordx4 v130, vcc
	s_add_i32 m0, s23, 0x13000
	s_nop 0
	global_load_lds_dwordx4 v134, vcc
	s_add_u32 vcc_lo, vcc_lo, 0x60000
	s_addc_u32 vcc_hi, vcc_hi, 0
	s_add_i32 m0, s23, 0x14000
	s_nop 0
	global_load_lds_dwordx4 v130, vcc
	s_add_i32 m0, s23, 0x16000
	s_nop 0
	global_load_lds_dwordx4 v134, vcc
	s_add_u32 vcc_lo, vcc_lo, 0x20000
	s_addc_u32 vcc_hi, vcc_hi, 0
	s_add_i32 m0, s23, 0x15000
	s_nop 0
	global_load_lds_dwordx4 v130, vcc
	s_add_i32 m0, s23, 0x17000
	s_nop 0
	global_load_lds_dwordx4 v134, vcc
	ds_read_b128 v[148:151], v168 offset:32768
	ds_read_b128 v[152:155], v168 offset:33792
	ds_read_b128 v[156:159], v168 offset:34816
	ds_read_b128 v[172:175], v168 offset:35840
	ds_read_b128 v[176:179], v169 offset:32768
	ds_read_b128 v[180:183], v169 offset:33792
	ds_read_b128 v[184:187], v169 offset:34816
	ds_read_b128 v[188:191], v169 offset:35840
	ds_read_b128 v[192:195], v170 offset:32768
	ds_read_b128 v[196:199], v170 offset:33792
	ds_read_b128 v[200:203], v170 offset:34816
	ds_read_b128 v[204:207], v170 offset:35840
	ds_read_b128 v[208:211], v170 offset:36864
	ds_read_b128 v[212:215], v170 offset:37888
	ds_read_b128 v[216:219], v170 offset:38912
	ds_read_b128 v[220:223], v170 offset:39936
	ds_read_b128 v[142:145], v170 offset:49152
	ds_read_b128 v[224:227], v170 offset:50176
	ds_read_b128 v[228:231], v170 offset:51200
	ds_read_b128 v[232:235], v170 offset:52224
	ds_read_b128 v[236:239], v170 offset:53248
	ds_read_b128 v[240:243], v170 offset:54272
	ds_read_b128 v[244:247], v170 offset:55296
	ds_read_b128 v[248:251], v170 offset:56320
	s_nop 15
	s_nop 15
	s_waitcnt lgkmcnt(0)
	s_barrier
	v_mfma_f32_16x16x32_bf16 v[124:127], v[148:151], v[192:195], v[124:127]
	v_mfma_f32_16x16x32_bf16 v[120:123], v[156:159], v[192:195], v[120:123]
	v_mfma_f32_16x16x32_bf16 v[116:119], v[148:151], v[200:203], v[116:119]
	v_mfma_f32_16x16x32_bf16 v[112:115], v[156:159], v[200:203], v[112:115]
	v_mfma_f32_16x16x32_bf16 v[100:103], v[148:151], v[208:211], v[100:103]
	v_mfma_f32_16x16x32_bf16 v[96:99], v[156:159], v[208:211], v[96:99]
	v_mfma_f32_16x16x32_bf16 v[84:87], v[148:151], v[216:219], v[84:87]
	v_mfma_f32_16x16x32_bf16 v[80:83], v[156:159], v[216:219], v[80:83]
	v_mfma_f32_16x16x32_bf16 v[124:127], v[152:155], v[196:199], v[124:127]
	v_mfma_f32_16x16x32_bf16 v[120:123], v[172:175], v[196:199], v[120:123]
	v_mfma_f32_16x16x32_bf16 v[116:119], v[152:155], v[204:207], v[116:119]
	v_mfma_f32_16x16x32_bf16 v[112:115], v[172:175], v[204:207], v[112:115]
	v_mfma_f32_16x16x32_bf16 v[100:103], v[152:155], v[212:215], v[100:103]
	v_mfma_f32_16x16x32_bf16 v[96:99], v[172:175], v[212:215], v[96:99]
	v_mfma_f32_16x16x32_bf16 v[84:87], v[152:155], v[220:223], v[84:87]
	v_mfma_f32_16x16x32_bf16 v[80:83], v[172:175], v[220:223], v[80:83]
	v_mfma_f32_16x16x32_bf16 v[108:111], v[176:179], v[192:195], v[108:111]
	v_mfma_f32_16x16x32_bf16 v[104:107], v[184:187], v[192:195], v[104:107]
	v_mfma_f32_16x16x32_bf16 v[92:95], v[176:179], v[200:203], v[92:95]
	v_mfma_f32_16x16x32_bf16 v[88:91], v[184:187], v[200:203], v[88:91]
	v_mfma_f32_16x16x32_bf16 v[76:79], v[176:179], v[208:211], v[76:79]
	v_mfma_f32_16x16x32_bf16 v[72:75], v[184:187], v[208:211], v[72:75]
	v_mfma_f32_16x16x32_bf16 v[68:71], v[176:179], v[216:219], v[68:71]
	v_mfma_f32_16x16x32_bf16 v[64:67], v[184:187], v[216:219], v[64:67]
	v_mfma_f32_16x16x32_bf16 v[108:111], v[180:183], v[196:199], v[108:111]
	v_mfma_f32_16x16x32_bf16 v[104:107], v[188:191], v[196:199], v[104:107]
	v_mfma_f32_16x16x32_bf16 v[92:95], v[180:183], v[204:207], v[92:95]
	v_mfma_f32_16x16x32_bf16 v[88:91], v[188:191], v[204:207], v[88:91]
	v_mfma_f32_16x16x32_bf16 v[76:79], v[180:183], v[212:215], v[76:79]
	v_mfma_f32_16x16x32_bf16 v[72:75], v[188:191], v[212:215], v[72:75]
	v_mfma_f32_16x16x32_bf16 v[68:71], v[180:183], v[220:223], v[68:71]
	v_mfma_f32_16x16x32_bf16 v[64:67], v[188:191], v[220:223], v[64:67]
	v_mfma_f32_16x16x32_bf16 v[60:63], v[148:151], v[142:145], v[60:63]
	v_mfma_f32_16x16x32_bf16 v[56:59], v[156:159], v[142:145], v[56:59]
	v_mfma_f32_16x16x32_bf16 v[52:55], v[148:151], v[228:231], v[52:55]
	v_mfma_f32_16x16x32_bf16 v[48:51], v[156:159], v[228:231], v[48:51]
	v_mfma_f32_16x16x32_bf16 v[36:39], v[148:151], v[236:239], v[36:39]
	v_mfma_f32_16x16x32_bf16 v[32:35], v[156:159], v[236:239], v[32:35]
	v_mfma_f32_16x16x32_bf16 v[20:23], v[148:151], v[244:247], v[20:23]
	v_mfma_f32_16x16x32_bf16 v[16:19], v[156:159], v[244:247], v[16:19]
	v_mfma_f32_16x16x32_bf16 v[60:63], v[152:155], v[224:227], v[60:63]
	v_mfma_f32_16x16x32_bf16 v[56:59], v[172:175], v[224:227], v[56:59]
	v_mfma_f32_16x16x32_bf16 v[52:55], v[152:155], v[232:235], v[52:55]
	v_mfma_f32_16x16x32_bf16 v[48:51], v[172:175], v[232:235], v[48:51]
	v_mfma_f32_16x16x32_bf16 v[36:39], v[152:155], v[240:243], v[36:39]
	v_mfma_f32_16x16x32_bf16 v[32:35], v[172:175], v[240:243], v[32:35]
	v_mfma_f32_16x16x32_bf16 v[20:23], v[152:155], v[248:251], v[20:23]
	v_mfma_f32_16x16x32_bf16 v[16:19], v[172:175], v[248:251], v[16:19]
	v_mfma_f32_16x16x32_bf16 v[44:47], v[176:179], v[142:145], v[44:47]
	v_mfma_f32_16x16x32_bf16 v[40:43], v[184:187], v[142:145], v[40:43]
	v_mfma_f32_16x16x32_bf16 v[28:31], v[176:179], v[228:231], v[28:31]
	v_mfma_f32_16x16x32_bf16 v[24:27], v[184:187], v[228:231], v[24:27]
	v_mfma_f32_16x16x32_bf16 v[12:15], v[176:179], v[236:239], v[12:15]
	v_mfma_f32_16x16x32_bf16 v[8:11], v[184:187], v[236:239], v[8:11]
	v_mfma_f32_16x16x32_bf16 v[4:7], v[176:179], v[244:247], v[4:7]
	v_mfma_f32_16x16x32_bf16 v[0:3], v[184:187], v[244:247], v[0:3]
	v_mfma_f32_16x16x32_bf16 v[44:47], v[180:183], v[224:227], v[44:47]
	v_mfma_f32_16x16x32_bf16 v[40:43], v[188:191], v[224:227], v[40:43]
	v_mfma_f32_16x16x32_bf16 v[28:31], v[180:183], v[232:235], v[28:31]
	v_mfma_f32_16x16x32_bf16 v[24:27], v[188:191], v[232:235], v[24:27]
	v_mfma_f32_16x16x32_bf16 v[12:15], v[180:183], v[240:243], v[12:15]
	v_mfma_f32_16x16x32_bf16 v[8:11], v[188:191], v[240:243], v[8:11]
	v_mfma_f32_16x16x32_bf16 v[4:7], v[180:183], v[248:251], v[4:7]
	v_mfma_f32_16x16x32_bf16 v[0:3], v[188:191], v[248:251], v[0:3]
	s_waitcnt vmcnt(0)
	s_barrier
	s_add_i32 s64, s64, 2
	s_add_u32 s14, s14, 0x100
	s_addc_u32 s15, s15, 0
	s_add_u32 s20, s20, 0x100
	s_addc_u32 s21, s21, 0
	s_cmp_gt_u32 s64, 29
	s_cbranch_scc0 .LBB0_165
	s_branch .Lk64_done_p1
.Lk64_trail_p1:
	s_setprio 1
	s_sub_u32 vcc_lo, s14, 0x80000
	s_subb_u32 vcc_hi, s15, 0
	s_add_i32 m0, s23, 0xa000
	s_nop 0
	global_load_lds_dwordx4 v132, vcc
	s_add_u32 vcc_lo, vcc_lo, 0x20000
	s_addc_u32 vcc_hi, vcc_hi, 0
	s_add_i32 m0, s23, 0x9000
	s_nop 0
	global_load_lds_dwordx4 v128, vcc
	s_add_u32 vcc_lo, vcc_lo, 0x60000
	s_addc_u32 vcc_hi, vcc_hi, 0
	s_add_i32 m0, s23, 0xe000
	s_nop 0
	global_load_lds_dwordx4 v132, vcc
	s_add_u32 vcc_lo, vcc_lo, 0x20000
	s_addc_u32 vcc_hi, vcc_hi, 0
	s_add_i32 m0, s23, 0xd000
	s_nop 0
	global_load_lds_dwordx4 v128, vcc
	s_add_u32 vcc_lo, s18, 0x0
	s_addc_u32 vcc_hi, s19, 0
	s_mov_b32 m0, s23
	s_nop 0
	global_load_lds_dwordx4 v128, vcc
	s_sub_u32 vcc_lo, vcc_lo, 0x20000
	s_subb_u32 vcc_hi, vcc_hi, 0
	s_sub_i32 m0, s23, 0x1000
	s_nop 0
	global_load_lds_dwordx4 v128, vcc
	s_add_u32 vcc_lo, vcc_lo, 0xa0000
	s_addc_u32 vcc_hi, vcc_hi, 0
	s_add_i32 m0, s23, 0x4000
	s_nop 0
	global_load_lds_dwordx4 v128, vcc
	s_sub_u32 vcc_lo, vcc_lo, 0x20000
	s_subb_u32 vcc_hi, vcc_hi, 0
	s_add_i32 m0, s23, 0x3000
	s_nop 0
	global_load_lds_dwordx4 v128, vcc
	ds_read_b128 v[148:151], v168 offset:0
	ds_read_b128 v[152:155], v168 offset:1024
	ds_read_b128 v[156:159], v168 offset:2048
	ds_read_b128 v[172:175], v168 offset:3072
	ds_read_b128 v[176:179], v169 offset:0
	ds_read_b128 v[180:183], v169 offset:1024
	ds_read_b128 v[184:187], v169 offset:2048
	ds_read_b128 v[188:191], v169 offset:3072
	ds_read_b128 v[192:195], v170 offset:0
	ds_read_b128 v[196:199], v170 offset:1024
	ds_read_b128 v[200:203], v170 offset:2048
	ds_read_b128 v[204:207], v170 offset:3072
	ds_read_b128 v[208:211], v170 offset:4096
	ds_read_b128 v[212:215], v170 offset:5120
	ds_read_b128 v[216:219], v170 offset:6144
	ds_read_b128 v[220:223], v170 offset:7168
	ds_read_b128 v[142:145], v170 offset:16384
	ds_read_b128 v[224:227], v170 offset:17408
	ds_read_b128 v[228:231], v170 offset:18432
	ds_read_b128 v[232:235], v170 offset:19456
	ds_read_b128 v[236:239], v170 offset:20480
	ds_read_b128 v[240:243], v170 offset:21504
	ds_read_b128 v[244:247], v170 offset:22528
	ds_read_b128 v[248:251], v170 offset:23552
	s_nop 15
	s_nop 15
	s_waitcnt lgkmcnt(0)
	s_barrier
	v_mfma_f32_16x16x32_bf16 v[124:127], v[148:151], v[192:195], v[124:127]
	v_mfma_f32_16x16x32_bf16 v[120:123], v[156:159], v[192:195], v[120:123]
	v_mfma_f32_16x16x32_bf16 v[116:119], v[148:151], v[200:203], v[116:119]
	v_mfma_f32_16x16x32_bf16 v[112:115], v[156:159], v[200:203], v[112:115]
	v_mfma_f32_16x16x32_bf16 v[100:103], v[148:151], v[208:211], v[100:103]
	v_mfma_f32_16x16x32_bf16 v[96:99], v[156:159], v[208:211], v[96:99]
	v_mfma_f32_16x16x32_bf16 v[84:87], v[148:151], v[216:219], v[84:87]
	v_mfma_f32_16x16x32_bf16 v[80:83], v[156:159], v[216:219], v[80:83]
	v_mfma_f32_16x16x32_bf16 v[124:127], v[152:155], v[196:199], v[124:127]
	v_mfma_f32_16x16x32_bf16 v[120:123], v[172:175], v[196:199], v[120:123]
	v_mfma_f32_16x16x32_bf16 v[116:119], v[152:155], v[204:207], v[116:119]
	v_mfma_f32_16x16x32_bf16 v[112:115], v[172:175], v[204:207], v[112:115]
	v_mfma_f32_16x16x32_bf16 v[100:103], v[152:155], v[212:215], v[100:103]
	v_mfma_f32_16x16x32_bf16 v[96:99], v[172:175], v[212:215], v[96:99]
	v_mfma_f32_16x16x32_bf16 v[84:87], v[152:155], v[220:223], v[84:87]
	v_mfma_f32_16x16x32_bf16 v[80:83], v[172:175], v[220:223], v[80:83]
	v_mfma_f32_16x16x32_bf16 v[108:111], v[176:179], v[192:195], v[108:111]
	v_mfma_f32_16x16x32_bf16 v[104:107], v[184:187], v[192:195], v[104:107]
	v_mfma_f32_16x16x32_bf16 v[92:95], v[176:179], v[200:203], v[92:95]
	v_mfma_f32_16x16x32_bf16 v[88:91], v[184:187], v[200:203], v[88:91]
	v_mfma_f32_16x16x32_bf16 v[76:79], v[176:179], v[208:211], v[76:79]
	v_mfma_f32_16x16x32_bf16 v[72:75], v[184:187], v[208:211], v[72:75]
	v_mfma_f32_16x16x32_bf16 v[68:71], v[176:179], v[216:219], v[68:71]
	v_mfma_f32_16x16x32_bf16 v[64:67], v[184:187], v[216:219], v[64:67]
	v_mfma_f32_16x16x32_bf16 v[108:111], v[180:183], v[196:199], v[108:111]
	v_mfma_f32_16x16x32_bf16 v[104:107], v[188:191], v[196:199], v[104:107]
	v_mfma_f32_16x16x32_bf16 v[92:95], v[180:183], v[204:207], v[92:95]
	v_mfma_f32_16x16x32_bf16 v[88:91], v[188:191], v[204:207], v[88:91]
	v_mfma_f32_16x16x32_bf16 v[76:79], v[180:183], v[212:215], v[76:79]
	v_mfma_f32_16x16x32_bf16 v[72:75], v[188:191], v[212:215], v[72:75]
	v_mfma_f32_16x16x32_bf16 v[68:71], v[180:183], v[220:223], v[68:71]
	v_mfma_f32_16x16x32_bf16 v[64:67], v[188:191], v[220:223], v[64:67]
	v_mfma_f32_16x16x32_bf16 v[60:63], v[148:151], v[142:145], v[60:63]
	v_mfma_f32_16x16x32_bf16 v[56:59], v[156:159], v[142:145], v[56:59]
	v_mfma_f32_16x16x32_bf16 v[52:55], v[148:151], v[228:231], v[52:55]
	v_mfma_f32_16x16x32_bf16 v[48:51], v[156:159], v[228:231], v[48:51]
	v_mfma_f32_16x16x32_bf16 v[36:39], v[148:151], v[236:239], v[36:39]
	v_mfma_f32_16x16x32_bf16 v[32:35], v[156:159], v[236:239], v[32:35]
	v_mfma_f32_16x16x32_bf16 v[20:23], v[148:151], v[244:247], v[20:23]
	v_mfma_f32_16x16x32_bf16 v[16:19], v[156:159], v[244:247], v[16:19]
	v_mfma_f32_16x16x32_bf16 v[60:63], v[152:155], v[224:227], v[60:63]
	v_mfma_f32_16x16x32_bf16 v[56:59], v[172:175], v[224:227], v[56:59]
	v_mfma_f32_16x16x32_bf16 v[52:55], v[152:155], v[232:235], v[52:55]
	v_mfma_f32_16x16x32_bf16 v[48:51], v[172:175], v[232:235], v[48:51]
	v_mfma_f32_16x16x32_bf16 v[36:39], v[152:155], v[240:243], v[36:39]
	v_mfma_f32_16x16x32_bf16 v[32:35], v[172:175], v[240:243], v[32:35]
	v_mfma_f32_16x16x32_bf16 v[20:23], v[152:155], v[248:251], v[20:23]
	v_mfma_f32_16x16x32_bf16 v[16:19], v[172:175], v[248:251], v[16:19]
	v_mfma_f32_16x16x32_bf16 v[44:47], v[176:179], v[142:145], v[44:47]
	v_mfma_f32_16x16x32_bf16 v[40:43], v[184:187], v[142:145], v[40:43]
	v_mfma_f32_16x16x32_bf16 v[28:31], v[176:179], v[228:231], v[28:31]
	v_mfma_f32_16x16x32_bf16 v[24:27], v[184:187], v[228:231], v[24:27]
	v_mfma_f32_16x16x32_bf16 v[12:15], v[176:179], v[236:239], v[12:15]
	v_mfma_f32_16x16x32_bf16 v[8:11], v[184:187], v[236:239], v[8:11]
	v_mfma_f32_16x16x32_bf16 v[4:7], v[176:179], v[244:247], v[4:7]
	v_mfma_f32_16x16x32_bf16 v[0:3], v[184:187], v[244:247], v[0:3]
	v_mfma_f32_16x16x32_bf16 v[44:47], v[180:183], v[224:227], v[44:47]
	v_mfma_f32_16x16x32_bf16 v[40:43], v[188:191], v[224:227], v[40:43]
	v_mfma_f32_16x16x32_bf16 v[28:31], v[180:183], v[232:235], v[28:31]
	v_mfma_f32_16x16x32_bf16 v[24:27], v[188:191], v[232:235], v[24:27]
	v_mfma_f32_16x16x32_bf16 v[12:15], v[180:183], v[240:243], v[12:15]
	v_mfma_f32_16x16x32_bf16 v[8:11], v[188:191], v[240:243], v[8:11]
	v_mfma_f32_16x16x32_bf16 v[4:7], v[180:183], v[248:251], v[4:7]
	v_mfma_f32_16x16x32_bf16 v[0:3], v[188:191], v[248:251], v[0:3]
	s_waitcnt vmcnt(0)
	s_barrier
	s_add_u32 vcc_lo, s18, 0x0
	s_addc_u32 vcc_hi, s19, 0
	s_add_i32 m0, s23, 0x2000
	s_nop 0
	global_load_lds_dwordx4 v132, vcc
	s_add_u32 vcc_lo, vcc_lo, 0x20000
	s_addc_u32 vcc_hi, vcc_hi, 0
	s_add_i32 m0, s23, 0x1000
	s_nop 0
	global_load_lds_dwordx4 v128, vcc
	s_add_u32 vcc_lo, vcc_lo, 0x60000
	s_addc_u32 vcc_hi, vcc_hi, 0
	s_add_i32 m0, s23, 0x6000
	s_nop 0
	global_load_lds_dwordx4 v132, vcc
	s_add_u32 vcc_lo, vcc_lo, 0x20000
	s_addc_u32 vcc_hi, vcc_hi, 0
	s_add_i32 m0, s23, 0x5000
	s_nop 0
	global_load_lds_dwordx4 v128, vcc
	s_add_u32 vcc_lo, s18, 0x80
	s_addc_u32 vcc_hi, s19, 0
	s_add_i32 m0, s23, 0x8000
	s_nop 0
	global_load_lds_dwordx4 v128, vcc
	s_sub_u32 vcc_lo, vcc_lo, 0x20000
	s_subb_u32 vcc_hi, vcc_hi, 0
	s_add_i32 m0, s23, 0x7000
	s_nop 0
	global_load_lds_dwordx4 v128, vcc
	s_add_u32 vcc_lo, vcc_lo, 0xa0000
	s_addc_u32 vcc_hi, vcc_hi, 0
	s_add_i32 m0, s23, 0xc000
	s_nop 0
	global_load_lds_dwordx4 v128, vcc
	s_sub_u32 vcc_lo, vcc_lo, 0x20000
	s_subb_u32 vcc_hi, vcc_hi, 0
	s_add_i32 m0, s23, 0xb000
	s_nop 0
	global_load_lds_dwordx4 v128, vcc
	ds_read_b128 v[148:151], v168 offset:32768
	ds_read_b128 v[152:155], v168 offset:33792
	ds_read_b128 v[156:159], v168 offset:34816
	ds_read_b128 v[172:175], v168 offset:35840
	ds_read_b128 v[176:179], v169 offset:32768
	ds_read_b128 v[180:183], v169 offset:33792
	ds_read_b128 v[184:187], v169 offset:34816
	ds_read_b128 v[188:191], v169 offset:35840
	ds_read_b128 v[192:195], v170 offset:32768
	ds_read_b128 v[196:199], v170 offset:33792
	ds_read_b128 v[200:203], v170 offset:34816
	ds_read_b128 v[204:207], v170 offset:35840
	ds_read_b128 v[208:211], v170 offset:36864
	ds_read_b128 v[212:215], v170 offset:37888
	ds_read_b128 v[216:219], v170 offset:38912
	ds_read_b128 v[220:223], v170 offset:39936
	ds_read_b128 v[142:145], v170 offset:49152
	ds_read_b128 v[224:227], v170 offset:50176
	ds_read_b128 v[228:231], v170 offset:51200
	ds_read_b128 v[232:235], v170 offset:52224
	ds_read_b128 v[236:239], v170 offset:53248
	ds_read_b128 v[240:243], v170 offset:54272
	ds_read_b128 v[244:247], v170 offset:55296
	ds_read_b128 v[248:251], v170 offset:56320
	s_nop 15
	s_nop 15
	s_waitcnt lgkmcnt(0)
	s_barrier
	v_mfma_f32_16x16x32_bf16 v[124:127], v[148:151], v[192:195], v[124:127]
	v_mfma_f32_16x16x32_bf16 v[120:123], v[156:159], v[192:195], v[120:123]
	v_mfma_f32_16x16x32_bf16 v[116:119], v[148:151], v[200:203], v[116:119]
	v_mfma_f32_16x16x32_bf16 v[112:115], v[156:159], v[200:203], v[112:115]
	v_mfma_f32_16x16x32_bf16 v[100:103], v[148:151], v[208:211], v[100:103]
	v_mfma_f32_16x16x32_bf16 v[96:99], v[156:159], v[208:211], v[96:99]
	v_mfma_f32_16x16x32_bf16 v[84:87], v[148:151], v[216:219], v[84:87]
	v_mfma_f32_16x16x32_bf16 v[80:83], v[156:159], v[216:219], v[80:83]
	v_mfma_f32_16x16x32_bf16 v[124:127], v[152:155], v[196:199], v[124:127]
	v_mfma_f32_16x16x32_bf16 v[120:123], v[172:175], v[196:199], v[120:123]
	v_mfma_f32_16x16x32_bf16 v[116:119], v[152:155], v[204:207], v[116:119]
	v_mfma_f32_16x16x32_bf16 v[112:115], v[172:175], v[204:207], v[112:115]
	v_mfma_f32_16x16x32_bf16 v[100:103], v[152:155], v[212:215], v[100:103]
	v_mfma_f32_16x16x32_bf16 v[96:99], v[172:175], v[212:215], v[96:99]
	v_mfma_f32_16x16x32_bf16 v[84:87], v[152:155], v[220:223], v[84:87]
	v_mfma_f32_16x16x32_bf16 v[80:83], v[172:175], v[220:223], v[80:83]
	v_mfma_f32_16x16x32_bf16 v[108:111], v[176:179], v[192:195], v[108:111]
	v_mfma_f32_16x16x32_bf16 v[104:107], v[184:187], v[192:195], v[104:107]
	v_mfma_f32_16x16x32_bf16 v[92:95], v[176:179], v[200:203], v[92:95]
	v_mfma_f32_16x16x32_bf16 v[88:91], v[184:187], v[200:203], v[88:91]
	v_mfma_f32_16x16x32_bf16 v[76:79], v[176:179], v[208:211], v[76:79]
	v_mfma_f32_16x16x32_bf16 v[72:75], v[184:187], v[208:211], v[72:75]
	v_mfma_f32_16x16x32_bf16 v[68:71], v[176:179], v[216:219], v[68:71]
	v_mfma_f32_16x16x32_bf16 v[64:67], v[184:187], v[216:219], v[64:67]
	v_mfma_f32_16x16x32_bf16 v[108:111], v[180:183], v[196:199], v[108:111]
	v_mfma_f32_16x16x32_bf16 v[104:107], v[188:191], v[196:199], v[104:107]
	v_mfma_f32_16x16x32_bf16 v[92:95], v[180:183], v[204:207], v[92:95]
	v_mfma_f32_16x16x32_bf16 v[88:91], v[188:191], v[204:207], v[88:91]
	v_mfma_f32_16x16x32_bf16 v[76:79], v[180:183], v[212:215], v[76:79]
	v_mfma_f32_16x16x32_bf16 v[72:75], v[188:191], v[212:215], v[72:75]
	v_mfma_f32_16x16x32_bf16 v[68:71], v[180:183], v[220:223], v[68:71]
	v_mfma_f32_16x16x32_bf16 v[64:67], v[188:191], v[220:223], v[64:67]
	v_mfma_f32_16x16x32_bf16 v[60:63], v[148:151], v[142:145], v[60:63]
	v_mfma_f32_16x16x32_bf16 v[56:59], v[156:159], v[142:145], v[56:59]
	v_mfma_f32_16x16x32_bf16 v[52:55], v[148:151], v[228:231], v[52:55]
	v_mfma_f32_16x16x32_bf16 v[48:51], v[156:159], v[228:231], v[48:51]
	v_mfma_f32_16x16x32_bf16 v[36:39], v[148:151], v[236:239], v[36:39]
	v_mfma_f32_16x16x32_bf16 v[32:35], v[156:159], v[236:239], v[32:35]
	v_mfma_f32_16x16x32_bf16 v[20:23], v[148:151], v[244:247], v[20:23]
	v_mfma_f32_16x16x32_bf16 v[16:19], v[156:159], v[244:247], v[16:19]
	v_mfma_f32_16x16x32_bf16 v[60:63], v[152:155], v[224:227], v[60:63]
	v_mfma_f32_16x16x32_bf16 v[56:59], v[172:175], v[224:227], v[56:59]
	v_mfma_f32_16x16x32_bf16 v[52:55], v[152:155], v[232:235], v[52:55]
	v_mfma_f32_16x16x32_bf16 v[48:51], v[172:175], v[232:235], v[48:51]
	v_mfma_f32_16x16x32_bf16 v[36:39], v[152:155], v[240:243], v[36:39]
	v_mfma_f32_16x16x32_bf16 v[32:35], v[172:175], v[240:243], v[32:35]
	v_mfma_f32_16x16x32_bf16 v[20:23], v[152:155], v[248:251], v[20:23]
	v_mfma_f32_16x16x32_bf16 v[16:19], v[172:175], v[248:251], v[16:19]
	v_mfma_f32_16x16x32_bf16 v[44:47], v[176:179], v[142:145], v[44:47]
	v_mfma_f32_16x16x32_bf16 v[40:43], v[184:187], v[142:145], v[40:43]
	v_mfma_f32_16x16x32_bf16 v[28:31], v[176:179], v[228:231], v[28:31]
	v_mfma_f32_16x16x32_bf16 v[24:27], v[184:187], v[228:231], v[24:27]
	v_mfma_f32_16x16x32_bf16 v[12:15], v[176:179], v[236:239], v[12:15]
	v_mfma_f32_16x16x32_bf16 v[8:11], v[184:187], v[236:239], v[8:11]
	v_mfma_f32_16x16x32_bf16 v[4:7], v[176:179], v[244:247], v[4:7]
	v_mfma_f32_16x16x32_bf16 v[0:3], v[184:187], v[244:247], v[0:3]
	v_mfma_f32_16x16x32_bf16 v[44:47], v[180:183], v[224:227], v[44:47]
	v_mfma_f32_16x16x32_bf16 v[40:43], v[188:191], v[224:227], v[40:43]
	v_mfma_f32_16x16x32_bf16 v[28:31], v[180:183], v[232:235], v[28:31]
	v_mfma_f32_16x16x32_bf16 v[24:27], v[188:191], v[232:235], v[24:27]
	v_mfma_f32_16x16x32_bf16 v[12:15], v[180:183], v[240:243], v[12:15]
	v_mfma_f32_16x16x32_bf16 v[8:11], v[188:191], v[240:243], v[8:11]
	v_mfma_f32_16x16x32_bf16 v[4:7], v[180:183], v[248:251], v[4:7]
	v_mfma_f32_16x16x32_bf16 v[0:3], v[188:191], v[248:251], v[0:3]
	s_waitcnt vmcnt(0)
	s_barrier
	s_add_i32 s64, s64, 2
	s_add_u32 s14, s14, 0x100
	s_addc_u32 s15, s15, 0
	s_add_u32 s20, s20, 0x100
	s_addc_u32 s21, s21, 0
	s_cmp_gt_u32 s64, 29
	s_cbranch_scc0 .LBB0_165
.Lk64_done_p1:
	s_setprio 0
	s_and_b64 vcc, exec, s[36:37]
	s_cbranch_vccz .LBB0_168
	s_barrier

.LBB0_613:
	s_add_u32 s24, s22, 0xfffc0080
	s_addc_u32 s25, s23, -1
	s_cmp_eq_u32 s49, 12
	s_cselect_b32 s27, s13, s25
	s_cselect_b32 s26, s41, s24
	s_cselect_b32 s25, s11, s48
	s_cselect_b32 s24, s46, s47
	s_and_b64 vcc, exec, s[6:7]
	s_cbranch_vccz .Lk64_trail_glu
	s_sub_u32 vcc_lo, s47, 0x80
	s_subb_u32 vcc_hi, s48, 0
	s_add_i32 m0, s28, 0x18000
	s_nop 0
	global_load_lds_dwordx4 v132, vcc
	s_add_i32 m0, s28, 0x1a000
	s_nop 0
	global_load_lds_dwordx4 v128, vcc
	s_add_u32 vcc_lo, vcc_lo, 0x10000
	s_addc_u32 vcc_hi, vcc_hi, 0
	s_add_i32 m0, s28, 0x19000
	s_nop 0
	global_load_lds_dwordx4 v132, vcc
	s_add_i32 m0, s28, 0x1b000
	s_nop 0
	global_load_lds_dwordx4 v128, vcc
	s_add_u32 vcc_lo, vcc_lo, 0x30000
	s_addc_u32 vcc_hi, vcc_hi, 0
	s_add_i32 m0, s28, 0x1c000
	s_nop 0
	global_load_lds_dwordx4 v132, vcc
	s_add_i32 m0, s28, 0x1e000
	s_nop 0
	global_load_lds_dwordx4 v128, vcc
	s_add_u32 vcc_lo, vcc_lo, 0x10000
	s_addc_u32 vcc_hi, vcc_hi, 0
	s_add_i32 m0, s28, 0x1d000
	s_nop 0
	global_load_lds_dwordx4 v132, vcc
	s_add_i32 m0, s28, 0x1f000
	s_nop 0
	global_load_lds_dwordx4 v128, vcc
	ds_read_b128 v[144:147], v151 offset:0
	ds_read_b128 v[154:157], v151 offset:1024
	ds_read_b128 v[158:161], v151 offset:2048
	ds_read_b128 v[162:165], v151 offset:3072
	ds_read_b128 v[166:169], v152 offset:0
	ds_read_b128 v[170:173], v152 offset:1024
	ds_read_b128 v[174:177], v152 offset:2048
	ds_read_b128 v[178:181], v152 offset:3072
	ds_read_b128 v[182:185], v153 offset:0
	ds_read_b128 v[186:189], v153 offset:1024
	ds_read_b128 v[190:193], v153 offset:2048
	ds_read_b128 v[194:197], v153 offset:3072
	ds_read_b128 v[198:201], v153 offset:4096
	ds_read_b128 v[202:205], v153 offset:5120
	ds_read_b128 v[206:209], v153 offset:6144
	ds_read_b128 v[210:213], v153 offset:7168
	ds_read_b128 v[220:223], v153 offset:16384
	ds_read_b128 v[224:227], v153 offset:17408
	ds_read_b128 v[228:231], v153 offset:18432
	ds_read_b128 v[232:235], v153 offset:19456
	ds_read_b128 v[236:239], v153 offset:20480
	ds_read_b128 v[240:243], v153 offset:21504
	ds_read_b128 v[244:247], v153 offset:22528
	ds_read_b128 v[248:251], v153 offset:23552
	s_nop 15
	s_nop 15
	s_waitcnt lgkmcnt(0)
	s_barrier
	v_mfma_f32_16x16x32_bf16 v[124:127], v[144:147], v[182:185], v[124:127]
	v_mfma_f32_16x16x32_bf16 v[120:123], v[158:161], v[182:185], v[120:123]
	v_mfma_f32_16x16x32_bf16 v[108:111], v[144:147], v[190:193], v[108:111]
	v_mfma_f32_16x16x32_bf16 v[104:107], v[158:161], v[190:193], v[104:107]
	v_mfma_f32_16x16x32_bf16 v[92:95], v[144:147], v[198:201], v[92:95]
	v_mfma_f32_16x16x32_bf16 v[88:91], v[158:161], v[198:201], v[88:91]
	v_mfma_f32_16x16x32_bf16 v[76:79], v[144:147], v[206:209], v[76:79]
	v_mfma_f32_16x16x32_bf16 v[72:75], v[158:161], v[206:209], v[72:75]
	v_mfma_f32_16x16x32_bf16 v[124:127], v[154:157], v[186:189], v[124:127]
	v_mfma_f32_16x16x32_bf16 v[120:123], v[162:165], v[186:189], v[120:123]
	v_mfma_f32_16x16x32_bf16 v[108:111], v[154:157], v[194:197], v[108:111]
	v_mfma_f32_16x16x32_bf16 v[104:107], v[162:165], v[194:197], v[104:107]
	v_mfma_f32_16x16x32_bf16 v[92:95], v[154:157], v[202:205], v[92:95]
	v_mfma_f32_16x16x32_bf16 v[88:91], v[162:165], v[202:205], v[88:91]
	v_mfma_f32_16x16x32_bf16 v[76:79], v[154:157], v[210:213], v[76:79]
	v_mfma_f32_16x16x32_bf16 v[72:75], v[162:165], v[210:213], v[72:75]
	v_mfma_f32_16x16x32_bf16 v[116:119], v[166:169], v[182:185], v[116:119]
	v_mfma_f32_16x16x32_bf16 v[112:115], v[174:177], v[182:185], v[112:115]
	v_mfma_f32_16x16x32_bf16 v[100:103], v[166:169], v[190:193], v[100:103]
	v_mfma_f32_16x16x32_bf16 v[96:99], v[174:177], v[190:193], v[96:99]
	v_mfma_f32_16x16x32_bf16 v[84:87], v[166:169], v[198:201], v[84:87]
	v_mfma_f32_16x16x32_bf16 v[80:83], v[174:177], v[198:201], v[80:83]
	v_mfma_f32_16x16x32_bf16 v[68:71], v[166:169], v[206:209], v[68:71]
	v_mfma_f32_16x16x32_bf16 v[64:67], v[174:177], v[206:209], v[64:67]
	v_mfma_f32_16x16x32_bf16 v[116:119], v[170:173], v[186:189], v[116:119]
	v_mfma_f32_16x16x32_bf16 v[112:115], v[178:181], v[186:189], v[112:115]
	v_mfma_f32_16x16x32_bf16 v[100:103], v[170:173], v[194:197], v[100:103]
	v_mfma_f32_16x16x32_bf16 v[96:99], v[178:181], v[194:197], v[96:99]
	v_mfma_f32_16x16x32_bf16 v[84:87], v[170:173], v[202:205], v[84:87]
	v_mfma_f32_16x16x32_bf16 v[80:83], v[178:181], v[202:205], v[80:83]
	v_mfma_f32_16x16x32_bf16 v[68:71], v[170:173], v[210:213], v[68:71]
	v_mfma_f32_16x16x32_bf16 v[64:67], v[178:181], v[210:213], v[64:67]
	v_mfma_f32_16x16x32_bf16 v[60:63], v[144:147], v[220:223], v[60:63]
	v_mfma_f32_16x16x32_bf16 v[56:59], v[158:161], v[220:223], v[56:59]
	v_mfma_f32_16x16x32_bf16 v[44:47], v[144:147], v[228:231], v[44:47]
	v_mfma_f32_16x16x32_bf16 v[40:43], v[158:161], v[228:231], v[40:43]
	v_mfma_f32_16x16x32_bf16 v[28:31], v[144:147], v[236:239], v[28:31]
	v_mfma_f32_16x16x32_bf16 v[24:27], v[158:161], v[236:239], v[24:27]
	v_mfma_f32_16x16x32_bf16 v[12:15], v[144:147], v[244:247], v[12:15]
	v_mfma_f32_16x16x32_bf16 v[8:11], v[158:161], v[244:247], v[8:11]
	v_mfma_f32_16x16x32_bf16 v[60:63], v[154:157], v[224:227], v[60:63]
	v_mfma_f32_16x16x32_bf16 v[56:59], v[162:165], v[224:227], v[56:59]
	v_mfma_f32_16x16x32_bf16 v[44:47], v[154:157], v[232:235], v[44:47]
	v_mfma_f32_16x16x32_bf16 v[40:43], v[162:165], v[232:235], v[40:43]
	v_mfma_f32_16x16x32_bf16 v[28:31], v[154:157], v[240:243], v[28:31]
	v_mfma_f32_16x16x32_bf16 v[24:27], v[162:165], v[240:243], v[24:27]
	v_mfma_f32_16x16x32_bf16 v[12:15], v[154:157], v[248:251], v[12:15]
	v_mfma_f32_16x16x32_bf16 v[8:11], v[162:165], v[248:251], v[8:11]
	v_mfma_f32_16x16x32_bf16 v[52:55], v[166:169], v[220:223], v[52:55]
	v_mfma_f32_16x16x32_bf16 v[48:51], v[174:177], v[220:223], v[48:51]
	v_mfma_f32_16x16x32_bf16 v[36:39], v[166:169], v[228:231], v[36:39]
	v_mfma_f32_16x16x32_bf16 v[32:35], v[174:177], v[228:231], v[32:35]
	v_mfma_f32_16x16x32_bf16 v[20:23], v[166:169], v[236:239], v[20:23]
	v_mfma_f32_16x16x32_bf16 v[16:19], v[174:177], v[236:239], v[16:19]
	v_mfma_f32_16x16x32_bf16 v[4:7], v[166:169], v[244:247], v[4:7]
	v_mfma_f32_16x16x32_bf16 v[0:3], v[174:177], v[244:247], v[0:3]
	v_mfma_f32_16x16x32_bf16 v[52:55], v[170:173], v[224:227], v[52:55]
	v_mfma_f32_16x16x32_bf16 v[48:51], v[178:181], v[224:227], v[48:51]
	v_mfma_f32_16x16x32_bf16 v[36:39], v[170:173], v[232:235], v[36:39]
	v_mfma_f32_16x16x32_bf16 v[32:35], v[178:181], v[232:235], v[32:35]
	v_mfma_f32_16x16x32_bf16 v[20:23], v[170:173], v[240:243], v[20:23]
	v_mfma_f32_16x16x32_bf16 v[16:19], v[178:181], v[240:243], v[16:19]
	v_mfma_f32_16x16x32_bf16 v[4:7], v[170:173], v[248:251], v[4:7]
	v_mfma_f32_16x16x32_bf16 v[0:3], v[178:181], v[248:251], v[0:3]
	s_waitcnt vmcnt(0)
	s_barrier
	s_add_u32 vcc_lo, s24, 0x0
	s_addc_u32 vcc_hi, s25, 0
	s_add_i32 m0, s28, 0x10000
	s_nop 0
	global_load_lds_dwordx4 v132, vcc
	s_add_i32 m0, s28, 0x12000
	s_nop 0
	global_load_lds_dwordx4 v128, vcc
	s_add_u32 vcc_lo, vcc_lo, 0x10000
	s_addc_u32 vcc_hi, vcc_hi, 0
	s_add_i32 m0, s28, 0x11000
	s_nop 0
	global_load_lds_dwordx4 v132, vcc
	s_add_i32 m0, s28, 0x13000
	s_nop 0
	global_load_lds_dwordx4 v128, vcc
	s_add_u32 vcc_lo, vcc_lo, 0x30000
	s_addc_u32 vcc_hi, vcc_hi, 0
	s_add_i32 m0, s28, 0x14000
	s_nop 0
	global_load_lds_dwordx4 v132, vcc
	s_add_i32 m0, s28, 0x16000
	s_nop 0
	global_load_lds_dwordx4 v128, vcc
	s_add_u32 vcc_lo, vcc_lo, 0x10000
	s_addc_u32 vcc_hi, vcc_hi, 0
	s_add_i32 m0, s28, 0x15000
	s_nop 0
	global_load_lds_dwordx4 v132, vcc
	s_add_i32 m0, s28, 0x17000
	s_nop 0
	global_load_lds_dwordx4 v128, vcc
	ds_read_b128 v[144:147], v151 offset:32768
	ds_read_b128 v[154:157], v151 offset:33792
	ds_read_b128 v[158:161], v151 offset:34816
	ds_read_b128 v[162:165], v151 offset:35840
	ds_read_b128 v[166:169], v152 offset:32768
	ds_read_b128 v[170:173], v152 offset:33792
	ds_read_b128 v[174:177], v152 offset:34816
	ds_read_b128 v[178:181], v152 offset:35840
	ds_read_b128 v[182:185], v153 offset:32768
	ds_read_b128 v[186:189], v153 offset:33792
	ds_read_b128 v[190:193], v153 offset:34816
	ds_read_b128 v[194:197], v153 offset:35840
	ds_read_b128 v[198:201], v153 offset:36864
	ds_read_b128 v[202:205], v153 offset:37888
	ds_read_b128 v[206:209], v153 offset:38912
	ds_read_b128 v[210:213], v153 offset:39936
	ds_read_b128 v[220:223], v153 offset:49152
	ds_read_b128 v[224:227], v153 offset:50176
	ds_read_b128 v[228:231], v153 offset:51200
	ds_read_b128 v[232:235], v153 offset:52224
	ds_read_b128 v[236:239], v153 offset:53248
	ds_read_b128 v[240:243], v153 offset:54272
	ds_read_b128 v[244:247], v153 offset:55296
	ds_read_b128 v[248:251], v153 offset:56320
	s_nop 15
	s_nop 15
	s_waitcnt lgkmcnt(0)
	s_barrier
	v_mfma_f32_16x16x32_bf16 v[124:127], v[144:147], v[182:185], v[124:127]
	v_mfma_f32_16x16x32_bf16 v[120:123], v[158:161], v[182:185], v[120:123]
	v_mfma_f32_16x16x32_bf16 v[108:111], v[144:147], v[190:193], v[108:111]
	v_mfma_f32_16x16x32_bf16 v[104:107], v[158:161], v[190:193], v[104:107]
	v_mfma_f32_16x16x32_bf16 v[92:95], v[144:147], v[198:201], v[92:95]
	v_mfma_f32_16x16x32_bf16 v[88:91], v[158:161], v[198:201], v[88:91]
	v_mfma_f32_16x16x32_bf16 v[76:79], v[144:147], v[206:209], v[76:79]
	v_mfma_f32_16x16x32_bf16 v[72:75], v[158:161], v[206:209], v[72:75]
	v_mfma_f32_16x16x32_bf16 v[124:127], v[154:157], v[186:189], v[124:127]
	v_mfma_f32_16x16x32_bf16 v[120:123], v[162:165], v[186:189], v[120:123]
	v_mfma_f32_16x16x32_bf16 v[108:111], v[154:157], v[194:197], v[108:111]
	v_mfma_f32_16x16x32_bf16 v[104:107], v[162:165], v[194:197], v[104:107]
	v_mfma_f32_16x16x32_bf16 v[92:95], v[154:157], v[202:205], v[92:95]
	v_mfma_f32_16x16x32_bf16 v[88:91], v[162:165], v[202:205], v[88:91]
	v_mfma_f32_16x16x32_bf16 v[76:79], v[154:157], v[210:213], v[76:79]
	v_mfma_f32_16x16x32_bf16 v[72:75], v[162:165], v[210:213], v[72:75]
	v_mfma_f32_16x16x32_bf16 v[116:119], v[166:169], v[182:185], v[116:119]
	v_mfma_f32_16x16x32_bf16 v[112:115], v[174:177], v[182:185], v[112:115]
	v_mfma_f32_16x16x32_bf16 v[100:103], v[166:169], v[190:193], v[100:103]
	v_mfma_f32_16x16x32_bf16 v[96:99], v[174:177], v[190:193], v[96:99]
	v_mfma_f32_16x16x32_bf16 v[84:87], v[166:169], v[198:201], v[84:87]
	v_mfma_f32_16x16x32_bf16 v[80:83], v[174:177], v[198:201], v[80:83]
	v_mfma_f32_16x16x32_bf16 v[68:71], v[166:169], v[206:209], v[68:71]
	v_mfma_f32_16x16x32_bf16 v[64:67], v[174:177], v[206:209], v[64:67]
	v_mfma_f32_16x16x32_bf16 v[116:119], v[170:173], v[186:189], v[116:119]
	v_mfma_f32_16x16x32_bf16 v[112:115], v[178:181], v[186:189], v[112:115]
	v_mfma_f32_16x16x32_bf16 v[100:103], v[170:173], v[194:197], v[100:103]
	v_mfma_f32_16x16x32_bf16 v[96:99], v[178:181], v[194:197], v[96:99]
	v_mfma_f32_16x16x32_bf16 v[84:87], v[170:173], v[202:205], v[84:87]
	v_mfma_f32_16x16x32_bf16 v[80:83], v[178:181], v[202:205], v[80:83]
	v_mfma_f32_16x16x32_bf16 v[68:71], v[170:173], v[210:213], v[68:71]
	v_mfma_f32_16x16x32_bf16 v[64:67], v[178:181], v[210:213], v[64:67]
	v_mfma_f32_16x16x32_bf16 v[60:63], v[144:147], v[220:223], v[60:63]
	v_mfma_f32_16x16x32_bf16 v[56:59], v[158:161], v[220:223], v[56:59]
	v_mfma_f32_16x16x32_bf16 v[44:47], v[144:147], v[228:231], v[44:47]
	v_mfma_f32_16x16x32_bf16 v[40:43], v[158:161], v[228:231], v[40:43]
	v_mfma_f32_16x16x32_bf16 v[28:31], v[144:147], v[236:239], v[28:31]
	v_mfma_f32_16x16x32_bf16 v[24:27], v[158:161], v[236:239], v[24:27]
	v_mfma_f32_16x16x32_bf16 v[12:15], v[144:147], v[244:247], v[12:15]
	v_mfma_f32_16x16x32_bf16 v[8:11], v[158:161], v[244:247], v[8:11]
	v_mfma_f32_16x16x32_bf16 v[60:63], v[154:157], v[224:227], v[60:63]
	v_mfma_f32_16x16x32_bf16 v[56:59], v[162:165], v[224:227], v[56:59]
	v_mfma_f32_16x16x32_bf16 v[44:47], v[154:157], v[232:235], v[44:47]
	v_mfma_f32_16x16x32_bf16 v[40:43], v[162:165], v[232:235], v[40:43]
	v_mfma_f32_16x16x32_bf16 v[28:31], v[154:157], v[240:243], v[28:31]
	v_mfma_f32_16x16x32_bf16 v[24:27], v[162:165], v[240:243], v[24:27]
	v_mfma_f32_16x16x32_bf16 v[12:15], v[154:157], v[248:251], v[12:15]
	v_mfma_f32_16x16x32_bf16 v[8:11], v[162:165], v[248:251], v[8:11]
	v_mfma_f32_16x16x32_bf16 v[52:55], v[166:169], v[220:223], v[52:55]
	v_mfma_f32_16x16x32_bf16 v[48:51], v[174:177], v[220:223], v[48:51]
	v_mfma_f32_16x16x32_bf16 v[36:39], v[166:169], v[228:231], v[36:39]
	v_mfma_f32_16x16x32_bf16 v[32:35], v[174:177], v[228:231], v[32:35]
	v_mfma_f32_16x16x32_bf16 v[20:23], v[166:169], v[236:239], v[20:23]
	v_mfma_f32_16x16x32_bf16 v[16:19], v[174:177], v[236:239], v[16:19]
	v_mfma_f32_16x16x32_bf16 v[4:7], v[166:169], v[244:247], v[4:7]
	v_mfma_f32_16x16x32_bf16 v[0:3], v[174:177], v[244:247], v[0:3]
	v_mfma_f32_16x16x32_bf16 v[52:55], v[170:173], v[224:227], v[52:55]
	v_mfma_f32_16x16x32_bf16 v[48:51], v[178:181], v[224:227], v[48:51]
	v_mfma_f32_16x16x32_bf16 v[36:39], v[170:173], v[232:235], v[36:39]
	v_mfma_f32_16x16x32_bf16 v[32:35], v[178:181], v[232:235], v[32:35]
	v_mfma_f32_16x16x32_bf16 v[20:23], v[170:173], v[240:243], v[20:23]
	v_mfma_f32_16x16x32_bf16 v[16:19], v[178:181], v[240:243], v[16:19]
	v_mfma_f32_16x16x32_bf16 v[4:7], v[170:173], v[248:251], v[4:7]
	v_mfma_f32_16x16x32_bf16 v[0:3], v[178:181], v[248:251], v[0:3]
	s_waitcnt vmcnt(0)
	s_barrier
	s_add_i32 s49, s49, 2
	s_add_u32 s22, s22, 0x100
	s_addc_u32 s23, s23, 0
	s_add_u32 s47, s47, 0x100
	s_addc_u32 s48, s48, 0
	s_cmp_gt_u32 s49, 13
	s_cbranch_scc0 .LBB0_613
	s_branch .Lk64_done_glu
.Lk64_trail_glu:
	s_setprio 1
	s_sub_u32 vcc_lo, s22, 0x40000
	s_subb_u32 vcc_hi, s23, 0
	s_add_i32 m0, s28, 0xa000
	s_nop 0
	global_load_lds_dwordx4 v130, vcc
	s_add_u32 vcc_lo, vcc_lo, 0x10000
	s_addc_u32 vcc_hi, vcc_hi, 0
	s_add_i32 m0, s28, 0x9000
	s_nop 0
	global_load_lds_dwordx4 v134, vcc
	s_add_u32 vcc_lo, vcc_lo, 0x30000
	s_addc_u32 vcc_hi, vcc_hi, 0
	s_add_i32 m0, s28, 0xe000
	s_nop 0
	global_load_lds_dwordx4 v130, vcc
	s_add_u32 vcc_lo, vcc_lo, 0x10000
	s_addc_u32 vcc_hi, vcc_hi, 0
	s_add_i32 m0, s28, 0xd000
	s_nop 0
	global_load_lds_dwordx4 v134, vcc
	s_add_u32 vcc_lo, s26, 0x0
	s_addc_u32 vcc_hi, s27, 0
	s_mov_b32 m0, s28
	s_nop 0
	global_load_lds_dwordx4 v134, vcc
	s_sub_u32 vcc_lo, vcc_lo, 0x10000
	s_subb_u32 vcc_hi, vcc_hi, 0
	s_sub_i32 m0, s28, 0x1000
	s_nop 0
	global_load_lds_dwordx4 v134, vcc
	s_add_u32 vcc_lo, vcc_lo, 0x50000
	s_addc_u32 vcc_hi, vcc_hi, 0
	s_add_i32 m0, s28, 0x4000
	s_nop 0
	global_load_lds_dwordx4 v134, vcc
	s_sub_u32 vcc_lo, vcc_lo, 0x10000
	s_subb_u32 vcc_hi, vcc_hi, 0
	s_add_i32 m0, s28, 0x3000
	s_nop 0
	global_load_lds_dwordx4 v134, vcc
	ds_read_b128 v[144:147], v151 offset:0
	ds_read_b128 v[154:157], v151 offset:1024
	ds_read_b128 v[158:161], v151 offset:2048
	ds_read_b128 v[162:165], v151 offset:3072
	ds_read_b128 v[166:169], v152 offset:0
	ds_read_b128 v[170:173], v152 offset:1024
	ds_read_b128 v[174:177], v152 offset:2048
	ds_read_b128 v[178:181], v152 offset:3072
	ds_read_b128 v[182:185], v153 offset:0
	ds_read_b128 v[186:189], v153 offset:1024
	ds_read_b128 v[190:193], v153 offset:2048
	ds_read_b128 v[194:197], v153 offset:3072
	ds_read_b128 v[198:201], v153 offset:4096
	ds_read_b128 v[202:205], v153 offset:5120
	ds_read_b128 v[206:209], v153 offset:6144
	ds_read_b128 v[210:213], v153 offset:7168
	ds_read_b128 v[220:223], v153 offset:16384
	ds_read_b128 v[224:227], v153 offset:17408
	ds_read_b128 v[228:231], v153 offset:18432
	ds_read_b128 v[232:235], v153 offset:19456
	ds_read_b128 v[236:239], v153 offset:20480
	ds_read_b128 v[240:243], v153 offset:21504
	ds_read_b128 v[244:247], v153 offset:22528
	ds_read_b128 v[248:251], v153 offset:23552
	s_nop 15
	s_nop 15
	s_waitcnt lgkmcnt(0)
	s_barrier
	v_mfma_f32_16x16x32_bf16 v[124:127], v[144:147], v[182:185], v[124:127]
	v_mfma_f32_16x16x32_bf16 v[120:123], v[158:161], v[182:185], v[120:123]
	v_mfma_f32_16x16x32_bf16 v[108:111], v[144:147], v[190:193], v[108:111]
	v_mfma_f32_16x16x32_bf16 v[104:107], v[158:161], v[190:193], v[104:107]
	v_mfma_f32_16x16x32_bf16 v[92:95], v[144:147], v[198:201], v[92:95]
	v_mfma_f32_16x16x32_bf16 v[88:91], v[158:161], v[198:201], v[88:91]
	v_mfma_f32_16x16x32_bf16 v[76:79], v[144:147], v[206:209], v[76:79]
	v_mfma_f32_16x16x32_bf16 v[72:75], v[158:161], v[206:209], v[72:75]
	v_mfma_f32_16x16x32_bf16 v[124:127], v[154:157], v[186:189], v[124:127]
	v_mfma_f32_16x16x32_bf16 v[120:123], v[162:165], v[186:189], v[120:123]
	v_mfma_f32_16x16x32_bf16 v[108:111], v[154:157], v[194:197], v[108:111]
	v_mfma_f32_16x16x32_bf16 v[104:107], v[162:165], v[194:197], v[104:107]
	v_mfma_f32_16x16x32_bf16 v[92:95], v[154:157], v[202:205], v[92:95]
	v_mfma_f32_16x16x32_bf16 v[88:91], v[162:165], v[202:205], v[88:91]
	v_mfma_f32_16x16x32_bf16 v[76:79], v[154:157], v[210:213], v[76:79]
	v_mfma_f32_16x16x32_bf16 v[72:75], v[162:165], v[210:213], v[72:75]
	v_mfma_f32_16x16x32_bf16 v[116:119], v[166:169], v[182:185], v[116:119]
	v_mfma_f32_16x16x32_bf16 v[112:115], v[174:177], v[182:185], v[112:115]
	v_mfma_f32_16x16x32_bf16 v[100:103], v[166:169], v[190:193], v[100:103]
	v_mfma_f32_16x16x32_bf16 v[96:99], v[174:177], v[190:193], v[96:99]
	v_mfma_f32_16x16x32_bf16 v[84:87], v[166:169], v[198:201], v[84:87]
	v_mfma_f32_16x16x32_bf16 v[80:83], v[174:177], v[198:201], v[80:83]
	v_mfma_f32_16x16x32_bf16 v[68:71], v[166:169], v[206:209], v[68:71]
	v_mfma_f32_16x16x32_bf16 v[64:67], v[174:177], v[206:209], v[64:67]
	v_mfma_f32_16x16x32_bf16 v[116:119], v[170:173], v[186:189], v[116:119]
	v_mfma_f32_16x16x32_bf16 v[112:115], v[178:181], v[186:189], v[112:115]
	v_mfma_f32_16x16x32_bf16 v[100:103], v[170:173], v[194:197], v[100:103]
	v_mfma_f32_16x16x32_bf16 v[96:99], v[178:181], v[194:197], v[96:99]
	v_mfma_f32_16x16x32_bf16 v[84:87], v[170:173], v[202:205], v[84:87]
	v_mfma_f32_16x16x32_bf16 v[80:83], v[178:181], v[202:205], v[80:83]
	v_mfma_f32_16x16x32_bf16 v[68:71], v[170:173], v[210:213], v[68:71]
	v_mfma_f32_16x16x32_bf16 v[64:67], v[178:181], v[210:213], v[64:67]
	v_mfma_f32_16x16x32_bf16 v[60:63], v[144:147], v[220:223], v[60:63]
	v_mfma_f32_16x16x32_bf16 v[56:59], v[158:161], v[220:223], v[56:59]
	v_mfma_f32_16x16x32_bf16 v[44:47], v[144:147], v[228:231], v[44:47]
	v_mfma_f32_16x16x32_bf16 v[40:43], v[158:161], v[228:231], v[40:43]
	v_mfma_f32_16x16x32_bf16 v[28:31], v[144:147], v[236:239], v[28:31]
	v_mfma_f32_16x16x32_bf16 v[24:27], v[158:161], v[236:239], v[24:27]
	v_mfma_f32_16x16x32_bf16 v[12:15], v[144:147], v[244:247], v[12:15]
	v_mfma_f32_16x16x32_bf16 v[8:11], v[158:161], v[244:247], v[8:11]
	v_mfma_f32_16x16x32_bf16 v[60:63], v[154:157], v[224:227], v[60:63]
	v_mfma_f32_16x16x32_bf16 v[56:59], v[162:165], v[224:227], v[56:59]
	v_mfma_f32_16x16x32_bf16 v[44:47], v[154:157], v[232:235], v[44:47]
	v_mfma_f32_16x16x32_bf16 v[40:43], v[162:165], v[232:235], v[40:43]
	v_mfma_f32_16x16x32_bf16 v[28:31], v[154:157], v[240:243], v[28:31]
	v_mfma_f32_16x16x32_bf16 v[24:27], v[162:165], v[240:243], v[24:27]
	v_mfma_f32_16x16x32_bf16 v[12:15], v[154:157], v[248:251], v[12:15]
	v_mfma_f32_16x16x32_bf16 v[8:11], v[162:165], v[248:251], v[8:11]
	v_mfma_f32_16x16x32_bf16 v[52:55], v[166:169], v[220:223], v[52:55]
	v_mfma_f32_16x16x32_bf16 v[48:51], v[174:177], v[220:223], v[48:51]
	v_mfma_f32_16x16x32_bf16 v[36:39], v[166:169], v[228:231], v[36:39]
	v_mfma_f32_16x16x32_bf16 v[32:35], v[174:177], v[228:231], v[32:35]
	v_mfma_f32_16x16x32_bf16 v[20:23], v[166:169], v[236:239], v[20:23]
	v_mfma_f32_16x16x32_bf16 v[16:19], v[174:177], v[236:239], v[16:19]
	v_mfma_f32_16x16x32_bf16 v[4:7], v[166:169], v[244:247], v[4:7]
	v_mfma_f32_16x16x32_bf16 v[0:3], v[174:177], v[244:247], v[0:3]
	v_mfma_f32_16x16x32_bf16 v[52:55], v[170:173], v[224:227], v[52:55]
	v_mfma_f32_16x16x32_bf16 v[48:51], v[178:181], v[224:227], v[48:51]
	v_mfma_f32_16x16x32_bf16 v[36:39], v[170:173], v[232:235], v[36:39]
	v_mfma_f32_16x16x32_bf16 v[32:35], v[178:181], v[232:235], v[32:35]
	v_mfma_f32_16x16x32_bf16 v[20:23], v[170:173], v[240:243], v[20:23]
	v_mfma_f32_16x16x32_bf16 v[16:19], v[178:181], v[240:243], v[16:19]
	v_mfma_f32_16x16x32_bf16 v[4:7], v[170:173], v[248:251], v[4:7]
	v_mfma_f32_16x16x32_bf16 v[0:3], v[178:181], v[248:251], v[0:3]
	s_waitcnt vmcnt(0)
	s_barrier
	s_add_u32 vcc_lo, s26, 0x0
	s_addc_u32 vcc_hi, s27, 0
	s_add_i32 m0, s28, 0x2000
	s_nop 0
	global_load_lds_dwordx4 v130, vcc
	s_add_u32 vcc_lo, vcc_lo, 0x10000
	s_addc_u32 vcc_hi, vcc_hi, 0
	s_add_i32 m0, s28, 0x1000
	s_nop 0
	global_load_lds_dwordx4 v134, vcc
	s_add_u32 vcc_lo, vcc_lo, 0x30000
	s_addc_u32 vcc_hi, vcc_hi, 0
	s_add_i32 m0, s28, 0x6000
	s_nop 0
	global_load_lds_dwordx4 v130, vcc
	s_add_u32 vcc_lo, vcc_lo, 0x10000
	s_addc_u32 vcc_hi, vcc_hi, 0
	s_add_i32 m0, s28, 0x5000
	s_nop 0
	global_load_lds_dwordx4 v134, vcc
	s_add_u32 vcc_lo, s26, 0x80
	s_addc_u32 vcc_hi, s27, 0
	s_add_i32 m0, s28, 0x8000
	s_nop 0
	global_load_lds_dwordx4 v134, vcc
	s_sub_u32 vcc_lo, vcc_lo, 0x10000
	s_subb_u32 vcc_hi, vcc_hi, 0
	s_add_i32 m0, s28, 0x7000
	s_nop 0
	global_load_lds_dwordx4 v134, vcc
	s_add_u32 vcc_lo, vcc_lo, 0x50000
	s_addc_u32 vcc_hi, vcc_hi, 0
	s_add_i32 m0, s28, 0xc000
	s_nop 0
	global_load_lds_dwordx4 v134, vcc
	s_sub_u32 vcc_lo, vcc_lo, 0x10000
	s_subb_u32 vcc_hi, vcc_hi, 0
	s_add_i32 m0, s28, 0xb000
	s_nop 0
	global_load_lds_dwordx4 v134, vcc
	ds_read_b128 v[144:147], v151 offset:32768
	ds_read_b128 v[154:157], v151 offset:33792
	ds_read_b128 v[158:161], v151 offset:34816
	ds_read_b128 v[162:165], v151 offset:35840
	ds_read_b128 v[166:169], v152 offset:32768
	ds_read_b128 v[170:173], v152 offset:33792
	ds_read_b128 v[174:177], v152 offset:34816
	ds_read_b128 v[178:181], v152 offset:35840
	ds_read_b128 v[182:185], v153 offset:32768
	ds_read_b128 v[186:189], v153 offset:33792
	ds_read_b128 v[190:193], v153 offset:34816
	ds_read_b128 v[194:197], v153 offset:35840
	ds_read_b128 v[198:201], v153 offset:36864
	ds_read_b128 v[202:205], v153 offset:37888
	ds_read_b128 v[206:209], v153 offset:38912
	ds_read_b128 v[210:213], v153 offset:39936
	ds_read_b128 v[220:223], v153 offset:49152
	ds_read_b128 v[224:227], v153 offset:50176
	ds_read_b128 v[228:231], v153 offset:51200
	ds_read_b128 v[232:235], v153 offset:52224
	ds_read_b128 v[236:239], v153 offset:53248
	ds_read_b128 v[240:243], v153 offset:54272
	ds_read_b128 v[244:247], v153 offset:55296
	ds_read_b128 v[248:251], v153 offset:56320
	s_nop 15
	s_nop 15
	s_waitcnt lgkmcnt(0)
	s_barrier
	v_mfma_f32_16x16x32_bf16 v[124:127], v[144:147], v[182:185], v[124:127]
	v_mfma_f32_16x16x32_bf16 v[120:123], v[158:161], v[182:185], v[120:123]
	v_mfma_f32_16x16x32_bf16 v[108:111], v[144:147], v[190:193], v[108:111]
	v_mfma_f32_16x16x32_bf16 v[104:107], v[158:161], v[190:193], v[104:107]
	v_mfma_f32_16x16x32_bf16 v[92:95], v[144:147], v[198:201], v[92:95]
	v_mfma_f32_16x16x32_bf16 v[88:91], v[158:161], v[198:201], v[88:91]
	v_mfma_f32_16x16x32_bf16 v[76:79], v[144:147], v[206:209], v[76:79]
	v_mfma_f32_16x16x32_bf16 v[72:75], v[158:161], v[206:209], v[72:75]
	v_mfma_f32_16x16x32_bf16 v[124:127], v[154:157], v[186:189], v[124:127]
	v_mfma_f32_16x16x32_bf16 v[120:123], v[162:165], v[186:189], v[120:123]
	v_mfma_f32_16x16x32_bf16 v[108:111], v[154:157], v[194:197], v[108:111]
	v_mfma_f32_16x16x32_bf16 v[104:107], v[162:165], v[194:197], v[104:107]
	v_mfma_f32_16x16x32_bf16 v[92:95], v[154:157], v[202:205], v[92:95]
	v_mfma_f32_16x16x32_bf16 v[88:91], v[162:165], v[202:205], v[88:91]
	v_mfma_f32_16x16x32_bf16 v[76:79], v[154:157], v[210:213], v[76:79]
	v_mfma_f32_16x16x32_bf16 v[72:75], v[162:165], v[210:213], v[72:75]
	v_mfma_f32_16x16x32_bf16 v[116:119], v[166:169], v[182:185], v[116:119]
	v_mfma_f32_16x16x32_bf16 v[112:115], v[174:177], v[182:185], v[112:115]
	v_mfma_f32_16x16x32_bf16 v[100:103], v[166:169], v[190:193], v[100:103]
	v_mfma_f32_16x16x32_bf16 v[96:99], v[174:177], v[190:193], v[96:99]
	v_mfma_f32_16x16x32_bf16 v[84:87], v[166:169], v[198:201], v[84:87]
	v_mfma_f32_16x16x32_bf16 v[80:83], v[174:177], v[198:201], v[80:83]
	v_mfma_f32_16x16x32_bf16 v[68:71], v[166:169], v[206:209], v[68:71]
	v_mfma_f32_16x16x32_bf16 v[64:67], v[174:177], v[206:209], v[64:67]
	v_mfma_f32_16x16x32_bf16 v[116:119], v[170:173], v[186:189], v[116:119]
	v_mfma_f32_16x16x32_bf16 v[112:115], v[178:181], v[186:189], v[112:115]
	v_mfma_f32_16x16x32_bf16 v[100:103], v[170:173], v[194:197], v[100:103]
	v_mfma_f32_16x16x32_bf16 v[96:99], v[178:181], v[194:197], v[96:99]
	v_mfma_f32_16x16x32_bf16 v[84:87], v[170:173], v[202:205], v[84:87]
	v_mfma_f32_16x16x32_bf16 v[80:83], v[178:181], v[202:205], v[80:83]
	v_mfma_f32_16x16x32_bf16 v[68:71], v[170:173], v[210:213], v[68:71]
	v_mfma_f32_16x16x32_bf16 v[64:67], v[178:181], v[210:213], v[64:67]
	v_mfma_f32_16x16x32_bf16 v[60:63], v[144:147], v[220:223], v[60:63]
	v_mfma_f32_16x16x32_bf16 v[56:59], v[158:161], v[220:223], v[56:59]
	v_mfma_f32_16x16x32_bf16 v[44:47], v[144:147], v[228:231], v[44:47]
	v_mfma_f32_16x16x32_bf16 v[40:43], v[158:161], v[228:231], v[40:43]
	v_mfma_f32_16x16x32_bf16 v[28:31], v[144:147], v[236:239], v[28:31]
	v_mfma_f32_16x16x32_bf16 v[24:27], v[158:161], v[236:239], v[24:27]
	v_mfma_f32_16x16x32_bf16 v[12:15], v[144:147], v[244:247], v[12:15]
	v_mfma_f32_16x16x32_bf16 v[8:11], v[158:161], v[244:247], v[8:11]
	v_mfma_f32_16x16x32_bf16 v[60:63], v[154:157], v[224:227], v[60:63]
	v_mfma_f32_16x16x32_bf16 v[56:59], v[162:165], v[224:227], v[56:59]
	v_mfma_f32_16x16x32_bf16 v[44:47], v[154:157], v[232:235], v[44:47]
	v_mfma_f32_16x16x32_bf16 v[40:43], v[162:165], v[232:235], v[40:43]
	v_mfma_f32_16x16x32_bf16 v[28:31], v[154:157], v[240:243], v[28:31]
	v_mfma_f32_16x16x32_bf16 v[24:27], v[162:165], v[240:243], v[24:27]
	v_mfma_f32_16x16x32_bf16 v[12:15], v[154:157], v[248:251], v[12:15]
	v_mfma_f32_16x16x32_bf16 v[8:11], v[162:165], v[248:251], v[8:11]
	v_mfma_f32_16x16x32_bf16 v[52:55], v[166:169], v[220:223], v[52:55]
	v_mfma_f32_16x16x32_bf16 v[48:51], v[174:177], v[220:223], v[48:51]
	v_mfma_f32_16x16x32_bf16 v[36:39], v[166:169], v[228:231], v[36:39]
	v_mfma_f32_16x16x32_bf16 v[32:35], v[174:177], v[228:231], v[32:35]
	v_mfma_f32_16x16x32_bf16 v[20:23], v[166:169], v[236:239], v[20:23]
	v_mfma_f32_16x16x32_bf16 v[16:19], v[174:177], v[236:239], v[16:19]
	v_mfma_f32_16x16x32_bf16 v[4:7], v[166:169], v[244:247], v[4:7]
	v_mfma_f32_16x16x32_bf16 v[0:3], v[174:177], v[244:247], v[0:3]
	v_mfma_f32_16x16x32_bf16 v[52:55], v[170:173], v[224:227], v[52:55]
	v_mfma_f32_16x16x32_bf16 v[48:51], v[178:181], v[224:227], v[48:51]
	v_mfma_f32_16x16x32_bf16 v[36:39], v[170:173], v[232:235], v[36:39]
	v_mfma_f32_16x16x32_bf16 v[32:35], v[178:181], v[232:235], v[32:35]
	v_mfma_f32_16x16x32_bf16 v[20:23], v[170:173], v[240:243], v[20:23]
	v_mfma_f32_16x16x32_bf16 v[16:19], v[178:181], v[240:243], v[16:19]
	v_mfma_f32_16x16x32_bf16 v[4:7], v[170:173], v[248:251], v[4:7]
	v_mfma_f32_16x16x32_bf16 v[0:3], v[178:181], v[248:251], v[0:3]
	s_waitcnt vmcnt(0)
	s_barrier
	s_add_i32 s49, s49, 2
	s_add_u32 s22, s22, 0x100
	s_addc_u32 s23, s23, 0
	s_add_u32 s47, s47, 0x100
	s_addc_u32 s48, s48, 0
	s_cmp_gt_u32 s49, 13
	s_cbranch_scc0 .LBB0_613
.Lk64_done_glu:
	s_setprio 0
	s_and_b64 vcc, exec, s[6:7]
	s_cbranch_vccz .LBB0_616
	s_barrier

.LBB0_686:
	s_add_u32 s30, s12, 0xfffc0080
	s_addc_u32 s31, s13, -1
	s_cmp_eq_u32 s56, 12
	s_cselect_b32 s35, s25, s31
	s_cselect_b32 s34, s49, s30
	s_cselect_b32 s31, s23, s55
	s_cselect_b32 s30, s51, s54
	s_and_b64 vcc, exec, s[4:5]
	s_cbranch_vccz .Lk64_trail_p4
	s_sub_u32 vcc_lo, s54, 0x80
	s_subb_u32 vcc_hi, s55, 0
	s_add_i32 m0, s36, 0x18000
	s_nop 0
	global_load_lds_dwordx4 v132, vcc
	s_add_i32 m0, s36, 0x1a000
	s_nop 0
	global_load_lds_dwordx4 v128, vcc
	s_add_u32 vcc_lo, vcc_lo, 0x10000
	s_addc_u32 vcc_hi, vcc_hi, 0
	s_add_i32 m0, s36, 0x19000
	s_nop 0
	global_load_lds_dwordx4 v132, vcc
	s_add_i32 m0, s36, 0x1b000
	s_nop 0
	global_load_lds_dwordx4 v128, vcc
	s_add_u32 vcc_lo, vcc_lo, 0x30000
	s_addc_u32 vcc_hi, vcc_hi, 0
	s_add_i32 m0, s36, 0x1c000
	s_nop 0
	global_load_lds_dwordx4 v132, vcc
	s_add_i32 m0, s36, 0x1e000
	s_nop 0
	global_load_lds_dwordx4 v128, vcc
	s_add_u32 vcc_lo, vcc_lo, 0x10000
	s_addc_u32 vcc_hi, vcc_hi, 0
	s_add_i32 m0, s36, 0x1d000
	s_nop 0
	global_load_lds_dwordx4 v132, vcc
	s_add_i32 m0, s36, 0x1f000
	s_nop 0
	global_load_lds_dwordx4 v128, vcc
	ds_read_b128 v[144:147], v151 offset:0
	ds_read_b128 v[154:157], v151 offset:1024
	ds_read_b128 v[158:161], v151 offset:2048
	ds_read_b128 v[162:165], v151 offset:3072
	ds_read_b128 v[166:169], v152 offset:0
	ds_read_b128 v[170:173], v152 offset:1024
	ds_read_b128 v[174:177], v152 offset:2048
	ds_read_b128 v[178:181], v152 offset:3072
	ds_read_b128 v[182:185], v153 offset:0
	ds_read_b128 v[186:189], v153 offset:1024
	ds_read_b128 v[190:193], v153 offset:2048
	ds_read_b128 v[194:197], v153 offset:3072
	ds_read_b128 v[198:201], v153 offset:4096
	ds_read_b128 v[202:205], v153 offset:5120
	ds_read_b128 v[206:209], v153 offset:6144
	ds_read_b128 v[210:213], v153 offset:7168
	ds_read_b128 v[220:223], v153 offset:16384
	ds_read_b128 v[224:227], v153 offset:17408
	ds_read_b128 v[228:231], v153 offset:18432
	ds_read_b128 v[232:235], v153 offset:19456
	ds_read_b128 v[236:239], v153 offset:20480
	ds_read_b128 v[240:243], v153 offset:21504
	ds_read_b128 v[244:247], v153 offset:22528
	ds_read_b128 v[248:251], v153 offset:23552
	s_nop 15
	s_nop 15
	s_waitcnt lgkmcnt(0)
	s_barrier
	v_mfma_f32_16x16x32_bf16 v[124:127], v[144:147], v[182:185], v[124:127]
	v_mfma_f32_16x16x32_bf16 v[120:123], v[158:161], v[182:185], v[120:123]
	v_mfma_f32_16x16x32_bf16 v[108:111], v[144:147], v[190:193], v[108:111]
	v_mfma_f32_16x16x32_bf16 v[104:107], v[158:161], v[190:193], v[104:107]
	v_mfma_f32_16x16x32_bf16 v[92:95], v[144:147], v[198:201], v[92:95]
	v_mfma_f32_16x16x32_bf16 v[88:91], v[158:161], v[198:201], v[88:91]
	v_mfma_f32_16x16x32_bf16 v[76:79], v[144:147], v[206:209], v[76:79]
	v_mfma_f32_16x16x32_bf16 v[72:75], v[158:161], v[206:209], v[72:75]
	v_mfma_f32_16x16x32_bf16 v[124:127], v[154:157], v[186:189], v[124:127]
	v_mfma_f32_16x16x32_bf16 v[120:123], v[162:165], v[186:189], v[120:123]
	v_mfma_f32_16x16x32_bf16 v[108:111], v[154:157], v[194:197], v[108:111]
	v_mfma_f32_16x16x32_bf16 v[104:107], v[162:165], v[194:197], v[104:107]
	v_mfma_f32_16x16x32_bf16 v[92:95], v[154:157], v[202:205], v[92:95]
	v_mfma_f32_16x16x32_bf16 v[88:91], v[162:165], v[202:205], v[88:91]
	v_mfma_f32_16x16x32_bf16 v[76:79], v[154:157], v[210:213], v[76:79]
	v_mfma_f32_16x16x32_bf16 v[72:75], v[162:165], v[210:213], v[72:75]
	v_mfma_f32_16x16x32_bf16 v[116:119], v[166:169], v[182:185], v[116:119]
	v_mfma_f32_16x16x32_bf16 v[112:115], v[174:177], v[182:185], v[112:115]
	v_mfma_f32_16x16x32_bf16 v[100:103], v[166:169], v[190:193], v[100:103]
	v_mfma_f32_16x16x32_bf16 v[96:99], v[174:177], v[190:193], v[96:99]
	v_mfma_f32_16x16x32_bf16 v[84:87], v[166:169], v[198:201], v[84:87]
	v_mfma_f32_16x16x32_bf16 v[80:83], v[174:177], v[198:201], v[80:83]
	v_mfma_f32_16x16x32_bf16 v[68:71], v[166:169], v[206:209], v[68:71]
	v_mfma_f32_16x16x32_bf16 v[64:67], v[174:177], v[206:209], v[64:67]
	v_mfma_f32_16x16x32_bf16 v[116:119], v[170:173], v[186:189], v[116:119]
	v_mfma_f32_16x16x32_bf16 v[112:115], v[178:181], v[186:189], v[112:115]
	v_mfma_f32_16x16x32_bf16 v[100:103], v[170:173], v[194:197], v[100:103]
	v_mfma_f32_16x16x32_bf16 v[96:99], v[178:181], v[194:197], v[96:99]
	v_mfma_f32_16x16x32_bf16 v[84:87], v[170:173], v[202:205], v[84:87]
	v_mfma_f32_16x16x32_bf16 v[80:83], v[178:181], v[202:205], v[80:83]
	v_mfma_f32_16x16x32_bf16 v[68:71], v[170:173], v[210:213], v[68:71]
	v_mfma_f32_16x16x32_bf16 v[64:67], v[178:181], v[210:213], v[64:67]
	v_mfma_f32_16x16x32_bf16 v[60:63], v[144:147], v[220:223], v[60:63]
	v_mfma_f32_16x16x32_bf16 v[56:59], v[158:161], v[220:223], v[56:59]
	v_mfma_f32_16x16x32_bf16 v[44:47], v[144:147], v[228:231], v[44:47]
	v_mfma_f32_16x16x32_bf16 v[40:43], v[158:161], v[228:231], v[40:43]
	v_mfma_f32_16x16x32_bf16 v[28:31], v[144:147], v[236:239], v[28:31]
	v_mfma_f32_16x16x32_bf16 v[24:27], v[158:161], v[236:239], v[24:27]
	v_mfma_f32_16x16x32_bf16 v[12:15], v[144:147], v[244:247], v[12:15]
	v_mfma_f32_16x16x32_bf16 v[8:11], v[158:161], v[244:247], v[8:11]
	v_mfma_f32_16x16x32_bf16 v[60:63], v[154:157], v[224:227], v[60:63]
	v_mfma_f32_16x16x32_bf16 v[56:59], v[162:165], v[224:227], v[56:59]
	v_mfma_f32_16x16x32_bf16 v[44:47], v[154:157], v[232:235], v[44:47]
	v_mfma_f32_16x16x32_bf16 v[40:43], v[162:165], v[232:235], v[40:43]
	v_mfma_f32_16x16x32_bf16 v[28:31], v[154:157], v[240:243], v[28:31]
	v_mfma_f32_16x16x32_bf16 v[24:27], v[162:165], v[240:243], v[24:27]
	v_mfma_f32_16x16x32_bf16 v[12:15], v[154:157], v[248:251], v[12:15]
	v_mfma_f32_16x16x32_bf16 v[8:11], v[162:165], v[248:251], v[8:11]
	v_mfma_f32_16x16x32_bf16 v[52:55], v[166:169], v[220:223], v[52:55]
	v_mfma_f32_16x16x32_bf16 v[48:51], v[174:177], v[220:223], v[48:51]
	v_mfma_f32_16x16x32_bf16 v[36:39], v[166:169], v[228:231], v[36:39]
	v_mfma_f32_16x16x32_bf16 v[32:35], v[174:177], v[228:231], v[32:35]
	v_mfma_f32_16x16x32_bf16 v[20:23], v[166:169], v[236:239], v[20:23]
	v_mfma_f32_16x16x32_bf16 v[16:19], v[174:177], v[236:239], v[16:19]
	v_mfma_f32_16x16x32_bf16 v[4:7], v[166:169], v[244:247], v[4:7]
	v_mfma_f32_16x16x32_bf16 v[0:3], v[174:177], v[244:247], v[0:3]
	v_mfma_f32_16x16x32_bf16 v[52:55], v[170:173], v[224:227], v[52:55]
	v_mfma_f32_16x16x32_bf16 v[48:51], v[178:181], v[224:227], v[48:51]
	v_mfma_f32_16x16x32_bf16 v[36:39], v[170:173], v[232:235], v[36:39]
	v_mfma_f32_16x16x32_bf16 v[32:35], v[178:181], v[232:235], v[32:35]
	v_mfma_f32_16x16x32_bf16 v[20:23], v[170:173], v[240:243], v[20:23]
	v_mfma_f32_16x16x32_bf16 v[16:19], v[178:181], v[240:243], v[16:19]
	v_mfma_f32_16x16x32_bf16 v[4:7], v[170:173], v[248:251], v[4:7]
	v_mfma_f32_16x16x32_bf16 v[0:3], v[178:181], v[248:251], v[0:3]
	s_waitcnt vmcnt(0)
	s_barrier
	s_add_u32 vcc_lo, s30, 0x0
	s_addc_u32 vcc_hi, s31, 0
	s_add_i32 m0, s36, 0x10000
	s_nop 0
	global_load_lds_dwordx4 v132, vcc
	s_add_i32 m0, s36, 0x12000
	s_nop 0
	global_load_lds_dwordx4 v128, vcc
	s_add_u32 vcc_lo, vcc_lo, 0x10000
	s_addc_u32 vcc_hi, vcc_hi, 0
	s_add_i32 m0, s36, 0x11000
	s_nop 0
	global_load_lds_dwordx4 v132, vcc
	s_add_i32 m0, s36, 0x13000
	s_nop 0
	global_load_lds_dwordx4 v128, vcc
	s_add_u32 vcc_lo, vcc_lo, 0x30000
	s_addc_u32 vcc_hi, vcc_hi, 0
	s_add_i32 m0, s36, 0x14000
	s_nop 0
	global_load_lds_dwordx4 v132, vcc
	s_add_i32 m0, s36, 0x16000
	s_nop 0
	global_load_lds_dwordx4 v128, vcc
	s_add_u32 vcc_lo, vcc_lo, 0x10000
	s_addc_u32 vcc_hi, vcc_hi, 0
	s_add_i32 m0, s36, 0x15000
	s_nop 0
	global_load_lds_dwordx4 v132, vcc
	s_add_i32 m0, s36, 0x17000
	s_nop 0
	global_load_lds_dwordx4 v128, vcc
	ds_read_b128 v[144:147], v151 offset:32768
	ds_read_b128 v[154:157], v151 offset:33792
	ds_read_b128 v[158:161], v151 offset:34816
	ds_read_b128 v[162:165], v151 offset:35840
	ds_read_b128 v[166:169], v152 offset:32768
	ds_read_b128 v[170:173], v152 offset:33792
	ds_read_b128 v[174:177], v152 offset:34816
	ds_read_b128 v[178:181], v152 offset:35840
	ds_read_b128 v[182:185], v153 offset:32768
	ds_read_b128 v[186:189], v153 offset:33792
	ds_read_b128 v[190:193], v153 offset:34816
	ds_read_b128 v[194:197], v153 offset:35840
	ds_read_b128 v[198:201], v153 offset:36864
	ds_read_b128 v[202:205], v153 offset:37888
	ds_read_b128 v[206:209], v153 offset:38912
	ds_read_b128 v[210:213], v153 offset:39936
	ds_read_b128 v[220:223], v153 offset:49152
	ds_read_b128 v[224:227], v153 offset:50176
	ds_read_b128 v[228:231], v153 offset:51200
	ds_read_b128 v[232:235], v153 offset:52224
	ds_read_b128 v[236:239], v153 offset:53248
	ds_read_b128 v[240:243], v153 offset:54272
	ds_read_b128 v[244:247], v153 offset:55296
	ds_read_b128 v[248:251], v153 offset:56320
	s_nop 15
	s_nop 15
	s_waitcnt lgkmcnt(0)
	s_barrier
	v_mfma_f32_16x16x32_bf16 v[124:127], v[144:147], v[182:185], v[124:127]
	v_mfma_f32_16x16x32_bf16 v[120:123], v[158:161], v[182:185], v[120:123]
	v_mfma_f32_16x16x32_bf16 v[108:111], v[144:147], v[190:193], v[108:111]
	v_mfma_f32_16x16x32_bf16 v[104:107], v[158:161], v[190:193], v[104:107]
	v_mfma_f32_16x16x32_bf16 v[92:95], v[144:147], v[198:201], v[92:95]
	v_mfma_f32_16x16x32_bf16 v[88:91], v[158:161], v[198:201], v[88:91]
	v_mfma_f32_16x16x32_bf16 v[76:79], v[144:147], v[206:209], v[76:79]
	v_mfma_f32_16x16x32_bf16 v[72:75], v[158:161], v[206:209], v[72:75]
	v_mfma_f32_16x16x32_bf16 v[124:127], v[154:157], v[186:189], v[124:127]
	v_mfma_f32_16x16x32_bf16 v[120:123], v[162:165], v[186:189], v[120:123]
	v_mfma_f32_16x16x32_bf16 v[108:111], v[154:157], v[194:197], v[108:111]
	v_mfma_f32_16x16x32_bf16 v[104:107], v[162:165], v[194:197], v[104:107]
	v_mfma_f32_16x16x32_bf16 v[92:95], v[154:157], v[202:205], v[92:95]
	v_mfma_f32_16x16x32_bf16 v[88:91], v[162:165], v[202:205], v[88:91]
	v_mfma_f32_16x16x32_bf16 v[76:79], v[154:157], v[210:213], v[76:79]
	v_mfma_f32_16x16x32_bf16 v[72:75], v[162:165], v[210:213], v[72:75]
	v_mfma_f32_16x16x32_bf16 v[116:119], v[166:169], v[182:185], v[116:119]
	v_mfma_f32_16x16x32_bf16 v[112:115], v[174:177], v[182:185], v[112:115]
	v_mfma_f32_16x16x32_bf16 v[100:103], v[166:169], v[190:193], v[100:103]
	v_mfma_f32_16x16x32_bf16 v[96:99], v[174:177], v[190:193], v[96:99]
	v_mfma_f32_16x16x32_bf16 v[84:87], v[166:169], v[198:201], v[84:87]
	v_mfma_f32_16x16x32_bf16 v[80:83], v[174:177], v[198:201], v[80:83]
	v_mfma_f32_16x16x32_bf16 v[68:71], v[166:169], v[206:209], v[68:71]
	v_mfma_f32_16x16x32_bf16 v[64:67], v[174:177], v[206:209], v[64:67]
	v_mfma_f32_16x16x32_bf16 v[116:119], v[170:173], v[186:189], v[116:119]
	v_mfma_f32_16x16x32_bf16 v[112:115], v[178:181], v[186:189], v[112:115]
	v_mfma_f32_16x16x32_bf16 v[100:103], v[170:173], v[194:197], v[100:103]
	v_mfma_f32_16x16x32_bf16 v[96:99], v[178:181], v[194:197], v[96:99]
	v_mfma_f32_16x16x32_bf16 v[84:87], v[170:173], v[202:205], v[84:87]
	v_mfma_f32_16x16x32_bf16 v[80:83], v[178:181], v[202:205], v[80:83]
	v_mfma_f32_16x16x32_bf16 v[68:71], v[170:173], v[210:213], v[68:71]
	v_mfma_f32_16x16x32_bf16 v[64:67], v[178:181], v[210:213], v[64:67]
	v_mfma_f32_16x16x32_bf16 v[60:63], v[144:147], v[220:223], v[60:63]
	v_mfma_f32_16x16x32_bf16 v[56:59], v[158:161], v[220:223], v[56:59]
	v_mfma_f32_16x16x32_bf16 v[44:47], v[144:147], v[228:231], v[44:47]
	v_mfma_f32_16x16x32_bf16 v[40:43], v[158:161], v[228:231], v[40:43]
	v_mfma_f32_16x16x32_bf16 v[28:31], v[144:147], v[236:239], v[28:31]
	v_mfma_f32_16x16x32_bf16 v[24:27], v[158:161], v[236:239], v[24:27]
	v_mfma_f32_16x16x32_bf16 v[12:15], v[144:147], v[244:247], v[12:15]
	v_mfma_f32_16x16x32_bf16 v[8:11], v[158:161], v[244:247], v[8:11]
	v_mfma_f32_16x16x32_bf16 v[60:63], v[154:157], v[224:227], v[60:63]
	v_mfma_f32_16x16x32_bf16 v[56:59], v[162:165], v[224:227], v[56:59]
	v_mfma_f32_16x16x32_bf16 v[44:47], v[154:157], v[232:235], v[44:47]
	v_mfma_f32_16x16x32_bf16 v[40:43], v[162:165], v[232:235], v[40:43]
	v_mfma_f32_16x16x32_bf16 v[28:31], v[154:157], v[240:243], v[28:31]
	v_mfma_f32_16x16x32_bf16 v[24:27], v[162:165], v[240:243], v[24:27]
	v_mfma_f32_16x16x32_bf16 v[12:15], v[154:157], v[248:251], v[12:15]
	v_mfma_f32_16x16x32_bf16 v[8:11], v[162:165], v[248:251], v[8:11]
	v_mfma_f32_16x16x32_bf16 v[52:55], v[166:169], v[220:223], v[52:55]
	v_mfma_f32_16x16x32_bf16 v[48:51], v[174:177], v[220:223], v[48:51]
	v_mfma_f32_16x16x32_bf16 v[36:39], v[166:169], v[228:231], v[36:39]
	v_mfma_f32_16x16x32_bf16 v[32:35], v[174:177], v[228:231], v[32:35]
	v_mfma_f32_16x16x32_bf16 v[20:23], v[166:169], v[236:239], v[20:23]
	v_mfma_f32_16x16x32_bf16 v[16:19], v[174:177], v[236:239], v[16:19]
	v_mfma_f32_16x16x32_bf16 v[4:7], v[166:169], v[244:247], v[4:7]
	v_mfma_f32_16x16x32_bf16 v[0:3], v[174:177], v[244:247], v[0:3]
	v_mfma_f32_16x16x32_bf16 v[52:55], v[170:173], v[224:227], v[52:55]
	v_mfma_f32_16x16x32_bf16 v[48:51], v[178:181], v[224:227], v[48:51]
	v_mfma_f32_16x16x32_bf16 v[36:39], v[170:173], v[232:235], v[36:39]
	v_mfma_f32_16x16x32_bf16 v[32:35], v[178:181], v[232:235], v[32:35]
	v_mfma_f32_16x16x32_bf16 v[20:23], v[170:173], v[240:243], v[20:23]
	v_mfma_f32_16x16x32_bf16 v[16:19], v[178:181], v[240:243], v[16:19]
	v_mfma_f32_16x16x32_bf16 v[4:7], v[170:173], v[248:251], v[4:7]
	v_mfma_f32_16x16x32_bf16 v[0:3], v[178:181], v[248:251], v[0:3]
	s_waitcnt vmcnt(0)
	s_barrier
	s_add_i32 s56, s56, 2
	s_add_u32 s12, s12, 0x100
	s_addc_u32 s13, s13, 0
	s_add_u32 s54, s54, 0x100
	s_addc_u32 s55, s55, 0
	s_cmp_gt_u32 s56, 13
	s_cbranch_scc0 .LBB0_686
	s_branch .Lk64_done_p4
.Lk64_trail_p4:
	s_setprio 1
	s_sub_u32 vcc_lo, s12, 0x40000
	s_subb_u32 vcc_hi, s13, 0
	s_add_i32 m0, s36, 0xa000
	s_nop 0
	global_load_lds_dwordx4 v130, vcc
	s_add_u32 vcc_lo, vcc_lo, 0x10000
	s_addc_u32 vcc_hi, vcc_hi, 0
	s_add_i32 m0, s36, 0x9000
	s_nop 0
	global_load_lds_dwordx4 v134, vcc
	s_add_u32 vcc_lo, vcc_lo, 0x30000
	s_addc_u32 vcc_hi, vcc_hi, 0
	s_add_i32 m0, s36, 0xe000
	s_nop 0
	global_load_lds_dwordx4 v130, vcc
	s_add_u32 vcc_lo, vcc_lo, 0x10000
	s_addc_u32 vcc_hi, vcc_hi, 0
	s_add_i32 m0, s36, 0xd000
	s_nop 0
	global_load_lds_dwordx4 v134, vcc
	s_add_u32 vcc_lo, s34, 0x0
	s_addc_u32 vcc_hi, s35, 0
	s_mov_b32 m0, s36
	s_nop 0
	global_load_lds_dwordx4 v134, vcc
	s_sub_u32 vcc_lo, vcc_lo, 0x10000
	s_subb_u32 vcc_hi, vcc_hi, 0
	s_sub_i32 m0, s36, 0x1000
	s_nop 0
	global_load_lds_dwordx4 v134, vcc
	s_add_u32 vcc_lo, vcc_lo, 0x50000
	s_addc_u32 vcc_hi, vcc_hi, 0
	s_add_i32 m0, s36, 0x4000
	s_nop 0
	global_load_lds_dwordx4 v134, vcc
	s_sub_u32 vcc_lo, vcc_lo, 0x10000
	s_subb_u32 vcc_hi, vcc_hi, 0
	s_add_i32 m0, s36, 0x3000
	s_nop 0
	global_load_lds_dwordx4 v134, vcc
	ds_read_b128 v[144:147], v151 offset:0
	ds_read_b128 v[154:157], v151 offset:1024
	ds_read_b128 v[158:161], v151 offset:2048
	ds_read_b128 v[162:165], v151 offset:3072
	ds_read_b128 v[166:169], v152 offset:0
	ds_read_b128 v[170:173], v152 offset:1024
	ds_read_b128 v[174:177], v152 offset:2048
	ds_read_b128 v[178:181], v152 offset:3072
	ds_read_b128 v[182:185], v153 offset:0
	ds_read_b128 v[186:189], v153 offset:1024
	ds_read_b128 v[190:193], v153 offset:2048
	ds_read_b128 v[194:197], v153 offset:3072
	ds_read_b128 v[198:201], v153 offset:4096
	ds_read_b128 v[202:205], v153 offset:5120
	ds_read_b128 v[206:209], v153 offset:6144
	ds_read_b128 v[210:213], v153 offset:7168
	ds_read_b128 v[220:223], v153 offset:16384
	ds_read_b128 v[224:227], v153 offset:17408
	ds_read_b128 v[228:231], v153 offset:18432
	ds_read_b128 v[232:235], v153 offset:19456
	ds_read_b128 v[236:239], v153 offset:20480
	ds_read_b128 v[240:243], v153 offset:21504
	ds_read_b128 v[244:247], v153 offset:22528
	ds_read_b128 v[248:251], v153 offset:23552
	s_nop 15
	s_nop 15
	s_waitcnt lgkmcnt(0)
	s_barrier
	v_mfma_f32_16x16x32_bf16 v[124:127], v[144:147], v[182:185], v[124:127]
	v_mfma_f32_16x16x32_bf16 v[120:123], v[158:161], v[182:185], v[120:123]
	v_mfma_f32_16x16x32_bf16 v[108:111], v[144:147], v[190:193], v[108:111]
	v_mfma_f32_16x16x32_bf16 v[104:107], v[158:161], v[190:193], v[104:107]
	v_mfma_f32_16x16x32_bf16 v[92:95], v[144:147], v[198:201], v[92:95]
	v_mfma_f32_16x16x32_bf16 v[88:91], v[158:161], v[198:201], v[88:91]
	v_mfma_f32_16x16x32_bf16 v[76:79], v[144:147], v[206:209], v[76:79]
	v_mfma_f32_16x16x32_bf16 v[72:75], v[158:161], v[206:209], v[72:75]
	v_mfma_f32_16x16x32_bf16 v[124:127], v[154:157], v[186:189], v[124:127]
	v_mfma_f32_16x16x32_bf16 v[120:123], v[162:165], v[186:189], v[120:123]
	v_mfma_f32_16x16x32_bf16 v[108:111], v[154:157], v[194:197], v[108:111]
	v_mfma_f32_16x16x32_bf16 v[104:107], v[162:165], v[194:197], v[104:107]
	v_mfma_f32_16x16x32_bf16 v[92:95], v[154:157], v[202:205], v[92:95]
	v_mfma_f32_16x16x32_bf16 v[88:91], v[162:165], v[202:205], v[88:91]
	v_mfma_f32_16x16x32_bf16 v[76:79], v[154:157], v[210:213], v[76:79]
	v_mfma_f32_16x16x32_bf16 v[72:75], v[162:165], v[210:213], v[72:75]
	v_mfma_f32_16x16x32_bf16 v[116:119], v[166:169], v[182:185], v[116:119]
	v_mfma_f32_16x16x32_bf16 v[112:115], v[174:177], v[182:185], v[112:115]
	v_mfma_f32_16x16x32_bf16 v[100:103], v[166:169], v[190:193], v[100:103]
	v_mfma_f32_16x16x32_bf16 v[96:99], v[174:177], v[190:193], v[96:99]
	v_mfma_f32_16x16x32_bf16 v[84:87], v[166:169], v[198:201], v[84:87]
	v_mfma_f32_16x16x32_bf16 v[80:83], v[174:177], v[198:201], v[80:83]
	v_mfma_f32_16x16x32_bf16 v[68:71], v[166:169], v[206:209], v[68:71]
	v_mfma_f32_16x16x32_bf16 v[64:67], v[174:177], v[206:209], v[64:67]
	v_mfma_f32_16x16x32_bf16 v[116:119], v[170:173], v[186:189], v[116:119]
	v_mfma_f32_16x16x32_bf16 v[112:115], v[178:181], v[186:189], v[112:115]
	v_mfma_f32_16x16x32_bf16 v[100:103], v[170:173], v[194:197], v[100:103]
	v_mfma_f32_16x16x32_bf16 v[96:99], v[178:181], v[194:197], v[96:99]
	v_mfma_f32_16x16x32_bf16 v[84:87], v[170:173], v[202:205], v[84:87]
	v_mfma_f32_16x16x32_bf16 v[80:83], v[178:181], v[202:205], v[80:83]
	v_mfma_f32_16x16x32_bf16 v[68:71], v[170:173], v[210:213], v[68:71]
	v_mfma_f32_16x16x32_bf16 v[64:67], v[178:181], v[210:213], v[64:67]
	v_mfma_f32_16x16x32_bf16 v[60:63], v[144:147], v[220:223], v[60:63]
	v_mfma_f32_16x16x32_bf16 v[56:59], v[158:161], v[220:223], v[56:59]
	v_mfma_f32_16x16x32_bf16 v[44:47], v[144:147], v[228:231], v[44:47]
	v_mfma_f32_16x16x32_bf16 v[40:43], v[158:161], v[228:231], v[40:43]
	v_mfma_f32_16x16x32_bf16 v[28:31], v[144:147], v[236:239], v[28:31]
	v_mfma_f32_16x16x32_bf16 v[24:27], v[158:161], v[236:239], v[24:27]
	v_mfma_f32_16x16x32_bf16 v[12:15], v[144:147], v[244:247], v[12:15]
	v_mfma_f32_16x16x32_bf16 v[8:11], v[158:161], v[244:247], v[8:11]
	v_mfma_f32_16x16x32_bf16 v[60:63], v[154:157], v[224:227], v[60:63]
	v_mfma_f32_16x16x32_bf16 v[56:59], v[162:165], v[224:227], v[56:59]
	v_mfma_f32_16x16x32_bf16 v[44:47], v[154:157], v[232:235], v[44:47]
	v_mfma_f32_16x16x32_bf16 v[40:43], v[162:165], v[232:235], v[40:43]
	v_mfma_f32_16x16x32_bf16 v[28:31], v[154:157], v[240:243], v[28:31]
	v_mfma_f32_16x16x32_bf16 v[24:27], v[162:165], v[240:243], v[24:27]
	v_mfma_f32_16x16x32_bf16 v[12:15], v[154:157], v[248:251], v[12:15]
	v_mfma_f32_16x16x32_bf16 v[8:11], v[162:165], v[248:251], v[8:11]
	v_mfma_f32_16x16x32_bf16 v[52:55], v[166:169], v[220:223], v[52:55]
	v_mfma_f32_16x16x32_bf16 v[48:51], v[174:177], v[220:223], v[48:51]
	v_mfma_f32_16x16x32_bf16 v[36:39], v[166:169], v[228:231], v[36:39]
	v_mfma_f32_16x16x32_bf16 v[32:35], v[174:177], v[228:231], v[32:35]
	v_mfma_f32_16x16x32_bf16 v[20:23], v[166:169], v[236:239], v[20:23]
	v_mfma_f32_16x16x32_bf16 v[16:19], v[174:177], v[236:239], v[16:19]
	v_mfma_f32_16x16x32_bf16 v[4:7], v[166:169], v[244:247], v[4:7]
	v_mfma_f32_16x16x32_bf16 v[0:3], v[174:177], v[244:247], v[0:3]
	v_mfma_f32_16x16x32_bf16 v[52:55], v[170:173], v[224:227], v[52:55]
	v_mfma_f32_16x16x32_bf16 v[48:51], v[178:181], v[224:227], v[48:51]
	v_mfma_f32_16x16x32_bf16 v[36:39], v[170:173], v[232:235], v[36:39]
	v_mfma_f32_16x16x32_bf16 v[32:35], v[178:181], v[232:235], v[32:35]
	v_mfma_f32_16x16x32_bf16 v[20:23], v[170:173], v[240:243], v[20:23]
	v_mfma_f32_16x16x32_bf16 v[16:19], v[178:181], v[240:243], v[16:19]
	v_mfma_f32_16x16x32_bf16 v[4:7], v[170:173], v[248:251], v[4:7]
	v_mfma_f32_16x16x32_bf16 v[0:3], v[178:181], v[248:251], v[0:3]
	s_waitcnt vmcnt(0)
	s_barrier
	s_add_u32 vcc_lo, s34, 0x0
	s_addc_u32 vcc_hi, s35, 0
	s_add_i32 m0, s36, 0x2000
	s_nop 0
	global_load_lds_dwordx4 v130, vcc
	s_add_u32 vcc_lo, vcc_lo, 0x10000
	s_addc_u32 vcc_hi, vcc_hi, 0
	s_add_i32 m0, s36, 0x1000
	s_nop 0
	global_load_lds_dwordx4 v134, vcc
	s_add_u32 vcc_lo, vcc_lo, 0x30000
	s_addc_u32 vcc_hi, vcc_hi, 0
	s_add_i32 m0, s36, 0x6000
	s_nop 0
	global_load_lds_dwordx4 v130, vcc
	s_add_u32 vcc_lo, vcc_lo, 0x10000
	s_addc_u32 vcc_hi, vcc_hi, 0
	s_add_i32 m0, s36, 0x5000
	s_nop 0
	global_load_lds_dwordx4 v134, vcc
	s_add_u32 vcc_lo, s34, 0x80
	s_addc_u32 vcc_hi, s35, 0
	s_add_i32 m0, s36, 0x8000
	s_nop 0
	global_load_lds_dwordx4 v134, vcc
	s_sub_u32 vcc_lo, vcc_lo, 0x10000
	s_subb_u32 vcc_hi, vcc_hi, 0
	s_add_i32 m0, s36, 0x7000
	s_nop 0
	global_load_lds_dwordx4 v134, vcc
	s_add_u32 vcc_lo, vcc_lo, 0x50000
	s_addc_u32 vcc_hi, vcc_hi, 0
	s_add_i32 m0, s36, 0xc000
	s_nop 0
	global_load_lds_dwordx4 v134, vcc
	s_sub_u32 vcc_lo, vcc_lo, 0x10000
	s_subb_u32 vcc_hi, vcc_hi, 0
	s_add_i32 m0, s36, 0xb000
	s_nop 0
	global_load_lds_dwordx4 v134, vcc
	ds_read_b128 v[144:147], v151 offset:32768
	ds_read_b128 v[154:157], v151 offset:33792
	ds_read_b128 v[158:161], v151 offset:34816
	ds_read_b128 v[162:165], v151 offset:35840
	ds_read_b128 v[166:169], v152 offset:32768
	ds_read_b128 v[170:173], v152 offset:33792
	ds_read_b128 v[174:177], v152 offset:34816
	ds_read_b128 v[178:181], v152 offset:35840
	ds_read_b128 v[182:185], v153 offset:32768
	ds_read_b128 v[186:189], v153 offset:33792
	ds_read_b128 v[190:193], v153 offset:34816
	ds_read_b128 v[194:197], v153 offset:35840
	ds_read_b128 v[198:201], v153 offset:36864
	ds_read_b128 v[202:205], v153 offset:37888
	ds_read_b128 v[206:209], v153 offset:38912
	ds_read_b128 v[210:213], v153 offset:39936
	ds_read_b128 v[220:223], v153 offset:49152
	ds_read_b128 v[224:227], v153 offset:50176
	ds_read_b128 v[228:231], v153 offset:51200
	ds_read_b128 v[232:235], v153 offset:52224
	ds_read_b128 v[236:239], v153 offset:53248
	ds_read_b128 v[240:243], v153 offset:54272
	ds_read_b128 v[244:247], v153 offset:55296
	ds_read_b128 v[248:251], v153 offset:56320
	s_nop 15
	s_nop 15
	s_waitcnt lgkmcnt(0)
	s_barrier
	v_mfma_f32_16x16x32_bf16 v[124:127], v[144:147], v[182:185], v[124:127]
	v_mfma_f32_16x16x32_bf16 v[120:123], v[158:161], v[182:185], v[120:123]
	v_mfma_f32_16x16x32_bf16 v[108:111], v[144:147], v[190:193], v[108:111]
	v_mfma_f32_16x16x32_bf16 v[104:107], v[158:161], v[190:193], v[104:107]
	v_mfma_f32_16x16x32_bf16 v[92:95], v[144:147], v[198:201], v[92:95]
	v_mfma_f32_16x16x32_bf16 v[88:91], v[158:161], v[198:201], v[88:91]
	v_mfma_f32_16x16x32_bf16 v[76:79], v[144:147], v[206:209], v[76:79]
	v_mfma_f32_16x16x32_bf16 v[72:75], v[158:161], v[206:209], v[72:75]
	v_mfma_f32_16x16x32_bf16 v[124:127], v[154:157], v[186:189], v[124:127]
	v_mfma_f32_16x16x32_bf16 v[120:123], v[162:165], v[186:189], v[120:123]
	v_mfma_f32_16x16x32_bf16 v[108:111], v[154:157], v[194:197], v[108:111]
	v_mfma_f32_16x16x32_bf16 v[104:107], v[162:165], v[194:197], v[104:107]
	v_mfma_f32_16x16x32_bf16 v[92:95], v[154:157], v[202:205], v[92:95]
	v_mfma_f32_16x16x32_bf16 v[88:91], v[162:165], v[202:205], v[88:91]
	v_mfma_f32_16x16x32_bf16 v[76:79], v[154:157], v[210:213], v[76:79]
	v_mfma_f32_16x16x32_bf16 v[72:75], v[162:165], v[210:213], v[72:75]
	v_mfma_f32_16x16x32_bf16 v[116:119], v[166:169], v[182:185], v[116:119]
	v_mfma_f32_16x16x32_bf16 v[112:115], v[174:177], v[182:185], v[112:115]
	v_mfma_f32_16x16x32_bf16 v[100:103], v[166:169], v[190:193], v[100:103]
	v_mfma_f32_16x16x32_bf16 v[96:99], v[174:177], v[190:193], v[96:99]
	v_mfma_f32_16x16x32_bf16 v[84:87], v[166:169], v[198:201], v[84:87]
	v_mfma_f32_16x16x32_bf16 v[80:83], v[174:177], v[198:201], v[80:83]
	v_mfma_f32_16x16x32_bf16 v[68:71], v[166:169], v[206:209], v[68:71]
	v_mfma_f32_16x16x32_bf16 v[64:67], v[174:177], v[206:209], v[64:67]
	v_mfma_f32_16x16x32_bf16 v[116:119], v[170:173], v[186:189], v[116:119]
	v_mfma_f32_16x16x32_bf16 v[112:115], v[178:181], v[186:189], v[112:115]
	v_mfma_f32_16x16x32_bf16 v[100:103], v[170:173], v[194:197], v[100:103]
	v_mfma_f32_16x16x32_bf16 v[96:99], v[178:181], v[194:197], v[96:99]
	v_mfma_f32_16x16x32_bf16 v[84:87], v[170:173], v[202:205], v[84:87]
	v_mfma_f32_16x16x32_bf16 v[80:83], v[178:181], v[202:205], v[80:83]
	v_mfma_f32_16x16x32_bf16 v[68:71], v[170:173], v[210:213], v[68:71]
	v_mfma_f32_16x16x32_bf16 v[64:67], v[178:181], v[210:213], v[64:67]
	v_mfma_f32_16x16x32_bf16 v[60:63], v[144:147], v[220:223], v[60:63]
	v_mfma_f32_16x16x32_bf16 v[56:59], v[158:161], v[220:223], v[56:59]
	v_mfma_f32_16x16x32_bf16 v[44:47], v[144:147], v[228:231], v[44:47]
	v_mfma_f32_16x16x32_bf16 v[40:43], v[158:161], v[228:231], v[40:43]
	v_mfma_f32_16x16x32_bf16 v[28:31], v[144:147], v[236:239], v[28:31]
	v_mfma_f32_16x16x32_bf16 v[24:27], v[158:161], v[236:239], v[24:27]
	v_mfma_f32_16x16x32_bf16 v[12:15], v[144:147], v[244:247], v[12:15]
	v_mfma_f32_16x16x32_bf16 v[8:11], v[158:161], v[244:247], v[8:11]
	v_mfma_f32_16x16x32_bf16 v[60:63], v[154:157], v[224:227], v[60:63]
	v_mfma_f32_16x16x32_bf16 v[56:59], v[162:165], v[224:227], v[56:59]
	v_mfma_f32_16x16x32_bf16 v[44:47], v[154:157], v[232:235], v[44:47]
	v_mfma_f32_16x16x32_bf16 v[40:43], v[162:165], v[232:235], v[40:43]
	v_mfma_f32_16x16x32_bf16 v[28:31], v[154:157], v[240:243], v[28:31]
	v_mfma_f32_16x16x32_bf16 v[24:27], v[162:165], v[240:243], v[24:27]
	v_mfma_f32_16x16x32_bf16 v[12:15], v[154:157], v[248:251], v[12:15]
	v_mfma_f32_16x16x32_bf16 v[8:11], v[162:165], v[248:251], v[8:11]
	v_mfma_f32_16x16x32_bf16 v[52:55], v[166:169], v[220:223], v[52:55]
	v_mfma_f32_16x16x32_bf16 v[48:51], v[174:177], v[220:223], v[48:51]
	v_mfma_f32_16x16x32_bf16 v[36:39], v[166:169], v[228:231], v[36:39]
	v_mfma_f32_16x16x32_bf16 v[32:35], v[174:177], v[228:231], v[32:35]
	v_mfma_f32_16x16x32_bf16 v[20:23], v[166:169], v[236:239], v[20:23]
	v_mfma_f32_16x16x32_bf16 v[16:19], v[174:177], v[236:239], v[16:19]
	v_mfma_f32_16x16x32_bf16 v[4:7], v[166:169], v[244:247], v[4:7]
	v_mfma_f32_16x16x32_bf16 v[0:3], v[174:177], v[244:247], v[0:3]
	v_mfma_f32_16x16x32_bf16 v[52:55], v[170:173], v[224:227], v[52:55]
	v_mfma_f32_16x16x32_bf16 v[48:51], v[178:181], v[224:227], v[48:51]
	v_mfma_f32_16x16x32_bf16 v[36:39], v[170:173], v[232:235], v[36:39]
	v_mfma_f32_16x16x32_bf16 v[32:35], v[178:181], v[232:235], v[32:35]
	v_mfma_f32_16x16x32_bf16 v[20:23], v[170:173], v[240:243], v[20:23]
	v_mfma_f32_16x16x32_bf16 v[16:19], v[178:181], v[240:243], v[16:19]
	v_mfma_f32_16x16x32_bf16 v[4:7], v[170:173], v[248:251], v[4:7]
	v_mfma_f32_16x16x32_bf16 v[0:3], v[178:181], v[248:251], v[0:3]
	s_waitcnt vmcnt(0)
	s_barrier
	s_add_i32 s56, s56, 2
	s_add_u32 s12, s12, 0x100
	s_addc_u32 s13, s13, 0
	s_add_u32 s54, s54, 0x100
	s_addc_u32 s55, s55, 0
	s_cmp_gt_u32 s56, 13
	s_cbranch_scc0 .LBB0_686
.Lk64_done_p4:
	s_setprio 0
	s_and_b64 vcc, exec, s[4:5]
	s_cbranch_vccz .LBB0_689
	s_barrier

.LBB0_761:
	s_add_u32 s36, s34, 0xfff80080
	s_addc_u32 s37, s35, -1
	s_cmp_eq_u32 s58, 28
	s_cselect_b32 s43, s23, s37
	s_cselect_b32 s42, s29, s36
	s_cselect_b32 s37, s13, s57
	s_cselect_b32 s36, s31, s56
	s_and_b64 vcc, exec, s[10:11]
	s_cbranch_vccz .Lk64_trail_p5
	s_sub_u32 vcc_lo, s56, 0x80
	s_subb_u32 vcc_hi, s57, 0
	s_add_i32 m0, s44, 0x18000
	s_nop 0
	global_load_lds_dwordx4 v130, vcc
	s_add_i32 m0, s44, 0x1a000
	s_nop 0
	global_load_lds_dwordx4 v134, vcc
	s_add_u32 vcc_lo, vcc_lo, 0x20000
	s_addc_u32 vcc_hi, vcc_hi, 0
	s_add_i32 m0, s44, 0x19000
	s_nop 0
	global_load_lds_dwordx4 v130, vcc
	s_add_i32 m0, s44, 0x1b000
	s_nop 0
	global_load_lds_dwordx4 v134, vcc
	s_add_u32 vcc_lo, vcc_lo, 0x60000
	s_addc_u32 vcc_hi, vcc_hi, 0
	s_add_i32 m0, s44, 0x1c000
	s_nop 0
	global_load_lds_dwordx4 v130, vcc
	s_add_i32 m0, s44, 0x1e000
	s_nop 0
	global_load_lds_dwordx4 v134, vcc
	s_add_u32 vcc_lo, vcc_lo, 0x20000
	s_addc_u32 vcc_hi, vcc_hi, 0
	s_add_i32 m0, s44, 0x1d000
	s_nop 0
	global_load_lds_dwordx4 v130, vcc
	s_add_i32 m0, s44, 0x1f000
	s_nop 0
	global_load_lds_dwordx4 v134, vcc
	ds_read_b128 v[144:147], v153 offset:0
	ds_read_b128 v[158:161], v153 offset:1024
	ds_read_b128 v[162:165], v153 offset:2048
	ds_read_b128 v[166:169], v153 offset:3072
	ds_read_b128 v[170:173], v154 offset:0
	ds_read_b128 v[174:177], v154 offset:1024
	ds_read_b128 v[178:181], v154 offset:2048
	ds_read_b128 v[182:185], v154 offset:3072
	ds_read_b128 v[186:189], v155 offset:0
	ds_read_b128 v[190:193], v155 offset:1024
	ds_read_b128 v[194:197], v155 offset:2048
	ds_read_b128 v[198:201], v155 offset:3072
	ds_read_b128 v[202:205], v155 offset:4096
	ds_read_b128 v[206:209], v155 offset:5120
	ds_read_b128 v[210:213], v155 offset:6144
	ds_read_b128 v[214:217], v155 offset:7168
	ds_read_b128 v[220:223], v155 offset:16384
	ds_read_b128 v[224:227], v155 offset:17408
	ds_read_b128 v[228:231], v155 offset:18432
	ds_read_b128 v[232:235], v155 offset:19456
	ds_read_b128 v[236:239], v155 offset:20480
	ds_read_b128 v[240:243], v155 offset:21504
	ds_read_b128 v[244:247], v155 offset:22528
	ds_read_b128 v[248:251], v155 offset:23552
	s_nop 15
	s_nop 15
	s_waitcnt lgkmcnt(0)
	s_barrier
	v_mfma_f32_16x16x32_bf16 v[124:127], v[144:147], v[186:189], v[124:127]
	v_mfma_f32_16x16x32_bf16 v[120:123], v[162:165], v[186:189], v[120:123]
	v_mfma_f32_16x16x32_bf16 v[108:111], v[144:147], v[194:197], v[108:111]
	v_mfma_f32_16x16x32_bf16 v[104:107], v[162:165], v[194:197], v[104:107]
	v_mfma_f32_16x16x32_bf16 v[92:95], v[144:147], v[202:205], v[92:95]
	v_mfma_f32_16x16x32_bf16 v[88:91], v[162:165], v[202:205], v[88:91]
	v_mfma_f32_16x16x32_bf16 v[76:79], v[144:147], v[210:213], v[76:79]
	v_mfma_f32_16x16x32_bf16 v[72:75], v[162:165], v[210:213], v[72:75]
	v_mfma_f32_16x16x32_bf16 v[124:127], v[158:161], v[190:193], v[124:127]
	v_mfma_f32_16x16x32_bf16 v[120:123], v[166:169], v[190:193], v[120:123]
	v_mfma_f32_16x16x32_bf16 v[108:111], v[158:161], v[198:201], v[108:111]
	v_mfma_f32_16x16x32_bf16 v[104:107], v[166:169], v[198:201], v[104:107]
	v_mfma_f32_16x16x32_bf16 v[92:95], v[158:161], v[206:209], v[92:95]
	v_mfma_f32_16x16x32_bf16 v[88:91], v[166:169], v[206:209], v[88:91]
	v_mfma_f32_16x16x32_bf16 v[76:79], v[158:161], v[214:217], v[76:79]
	v_mfma_f32_16x16x32_bf16 v[72:75], v[166:169], v[214:217], v[72:75]
	v_mfma_f32_16x16x32_bf16 v[116:119], v[170:173], v[186:189], v[116:119]
	v_mfma_f32_16x16x32_bf16 v[112:115], v[178:181], v[186:189], v[112:115]
	v_mfma_f32_16x16x32_bf16 v[100:103], v[170:173], v[194:197], v[100:103]
	v_mfma_f32_16x16x32_bf16 v[96:99], v[178:181], v[194:197], v[96:99]
	v_mfma_f32_16x16x32_bf16 v[84:87], v[170:173], v[202:205], v[84:87]
	v_mfma_f32_16x16x32_bf16 v[80:83], v[178:181], v[202:205], v[80:83]
	v_mfma_f32_16x16x32_bf16 v[68:71], v[170:173], v[210:213], v[68:71]
	v_mfma_f32_16x16x32_bf16 v[64:67], v[178:181], v[210:213], v[64:67]
	v_mfma_f32_16x16x32_bf16 v[116:119], v[174:177], v[190:193], v[116:119]
	v_mfma_f32_16x16x32_bf16 v[112:115], v[182:185], v[190:193], v[112:115]
	v_mfma_f32_16x16x32_bf16 v[100:103], v[174:177], v[198:201], v[100:103]
	v_mfma_f32_16x16x32_bf16 v[96:99], v[182:185], v[198:201], v[96:99]
	v_mfma_f32_16x16x32_bf16 v[84:87], v[174:177], v[206:209], v[84:87]
	v_mfma_f32_16x16x32_bf16 v[80:83], v[182:185], v[206:209], v[80:83]
	v_mfma_f32_16x16x32_bf16 v[68:71], v[174:177], v[214:217], v[68:71]
	v_mfma_f32_16x16x32_bf16 v[64:67], v[182:185], v[214:217], v[64:67]
	v_mfma_f32_16x16x32_bf16 v[60:63], v[144:147], v[220:223], v[60:63]
	v_mfma_f32_16x16x32_bf16 v[56:59], v[162:165], v[220:223], v[56:59]
	v_mfma_f32_16x16x32_bf16 v[44:47], v[144:147], v[228:231], v[44:47]
	v_mfma_f32_16x16x32_bf16 v[40:43], v[162:165], v[228:231], v[40:43]
	v_mfma_f32_16x16x32_bf16 v[28:31], v[144:147], v[236:239], v[28:31]
	v_mfma_f32_16x16x32_bf16 v[24:27], v[162:165], v[236:239], v[24:27]
	v_mfma_f32_16x16x32_bf16 v[12:15], v[144:147], v[244:247], v[12:15]
	v_mfma_f32_16x16x32_bf16 v[8:11], v[162:165], v[244:247], v[8:11]
	v_mfma_f32_16x16x32_bf16 v[60:63], v[158:161], v[224:227], v[60:63]
	v_mfma_f32_16x16x32_bf16 v[56:59], v[166:169], v[224:227], v[56:59]
	v_mfma_f32_16x16x32_bf16 v[44:47], v[158:161], v[232:235], v[44:47]
	v_mfma_f32_16x16x32_bf16 v[40:43], v[166:169], v[232:235], v[40:43]
	v_mfma_f32_16x16x32_bf16 v[28:31], v[158:161], v[240:243], v[28:31]
	v_mfma_f32_16x16x32_bf16 v[24:27], v[166:169], v[240:243], v[24:27]
	v_mfma_f32_16x16x32_bf16 v[12:15], v[158:161], v[248:251], v[12:15]
	v_mfma_f32_16x16x32_bf16 v[8:11], v[166:169], v[248:251], v[8:11]
	v_mfma_f32_16x16x32_bf16 v[52:55], v[170:173], v[220:223], v[52:55]
	v_mfma_f32_16x16x32_bf16 v[48:51], v[178:181], v[220:223], v[48:51]
	v_mfma_f32_16x16x32_bf16 v[36:39], v[170:173], v[228:231], v[36:39]
	v_mfma_f32_16x16x32_bf16 v[32:35], v[178:181], v[228:231], v[32:35]
	v_mfma_f32_16x16x32_bf16 v[20:23], v[170:173], v[236:239], v[20:23]
	v_mfma_f32_16x16x32_bf16 v[16:19], v[178:181], v[236:239], v[16:19]
	v_mfma_f32_16x16x32_bf16 v[4:7], v[170:173], v[244:247], v[4:7]
	v_mfma_f32_16x16x32_bf16 v[0:3], v[178:181], v[244:247], v[0:3]
	v_mfma_f32_16x16x32_bf16 v[52:55], v[174:177], v[224:227], v[52:55]
	v_mfma_f32_16x16x32_bf16 v[48:51], v[182:185], v[224:227], v[48:51]
	v_mfma_f32_16x16x32_bf16 v[36:39], v[174:177], v[232:235], v[36:39]
	v_mfma_f32_16x16x32_bf16 v[32:35], v[182:185], v[232:235], v[32:35]
	v_mfma_f32_16x16x32_bf16 v[20:23], v[174:177], v[240:243], v[20:23]
	v_mfma_f32_16x16x32_bf16 v[16:19], v[182:185], v[240:243], v[16:19]
	v_mfma_f32_16x16x32_bf16 v[4:7], v[174:177], v[248:251], v[4:7]
	v_mfma_f32_16x16x32_bf16 v[0:3], v[182:185], v[248:251], v[0:3]
	s_waitcnt vmcnt(0)
	s_barrier
	s_add_u32 vcc_lo, s36, 0x0
	s_addc_u32 vcc_hi, s37, 0
	s_add_i32 m0, s44, 0x10000
	s_nop 0
	global_load_lds_dwordx4 v130, vcc
	s_add_i32 m0, s44, 0x12000
	s_nop 0
	global_load_lds_dwordx4 v134, vcc
	s_add_u32 vcc_lo, vcc_lo, 0x20000
	s_addc_u32 vcc_hi, vcc_hi, 0
	s_add_i32 m0, s44, 0x11000
	s_nop 0
	global_load_lds_dwordx4 v130, vcc
	s_add_i32 m0, s44, 0x13000
	s_nop 0
	global_load_lds_dwordx4 v134, vcc
	s_add_u32 vcc_lo, vcc_lo, 0x60000
	s_addc_u32 vcc_hi, vcc_hi, 0
	s_add_i32 m0, s44, 0x14000
	s_nop 0
	global_load_lds_dwordx4 v130, vcc
	s_add_i32 m0, s44, 0x16000
	s_nop 0
	global_load_lds_dwordx4 v134, vcc
	s_add_u32 vcc_lo, vcc_lo, 0x20000
	s_addc_u32 vcc_hi, vcc_hi, 0
	s_add_i32 m0, s44, 0x15000
	s_nop 0
	global_load_lds_dwordx4 v130, vcc
	s_add_i32 m0, s44, 0x17000
	s_nop 0
	global_load_lds_dwordx4 v134, vcc
	ds_read_b128 v[144:147], v153 offset:32768
	ds_read_b128 v[158:161], v153 offset:33792
	ds_read_b128 v[162:165], v153 offset:34816
	ds_read_b128 v[166:169], v153 offset:35840
	ds_read_b128 v[170:173], v154 offset:32768
	ds_read_b128 v[174:177], v154 offset:33792
	ds_read_b128 v[178:181], v154 offset:34816
	ds_read_b128 v[182:185], v154 offset:35840
	ds_read_b128 v[186:189], v155 offset:32768
	ds_read_b128 v[190:193], v155 offset:33792
	ds_read_b128 v[194:197], v155 offset:34816
	ds_read_b128 v[198:201], v155 offset:35840
	ds_read_b128 v[202:205], v155 offset:36864
	ds_read_b128 v[206:209], v155 offset:37888
	ds_read_b128 v[210:213], v155 offset:38912
	ds_read_b128 v[214:217], v155 offset:39936
	ds_read_b128 v[220:223], v155 offset:49152
	ds_read_b128 v[224:227], v155 offset:50176
	ds_read_b128 v[228:231], v155 offset:51200
	ds_read_b128 v[232:235], v155 offset:52224
	ds_read_b128 v[236:239], v155 offset:53248
	ds_read_b128 v[240:243], v155 offset:54272
	ds_read_b128 v[244:247], v155 offset:55296
	ds_read_b128 v[248:251], v155 offset:56320
	s_nop 15
	s_nop 15
	s_waitcnt lgkmcnt(0)
	s_barrier
	v_mfma_f32_16x16x32_bf16 v[124:127], v[144:147], v[186:189], v[124:127]
	v_mfma_f32_16x16x32_bf16 v[120:123], v[162:165], v[186:189], v[120:123]
	v_mfma_f32_16x16x32_bf16 v[108:111], v[144:147], v[194:197], v[108:111]
	v_mfma_f32_16x16x32_bf16 v[104:107], v[162:165], v[194:197], v[104:107]
	v_mfma_f32_16x16x32_bf16 v[92:95], v[144:147], v[202:205], v[92:95]
	v_mfma_f32_16x16x32_bf16 v[88:91], v[162:165], v[202:205], v[88:91]
	v_mfma_f32_16x16x32_bf16 v[76:79], v[144:147], v[210:213], v[76:79]
	v_mfma_f32_16x16x32_bf16 v[72:75], v[162:165], v[210:213], v[72:75]
	v_mfma_f32_16x16x32_bf16 v[124:127], v[158:161], v[190:193], v[124:127]
	v_mfma_f32_16x16x32_bf16 v[120:123], v[166:169], v[190:193], v[120:123]
	v_mfma_f32_16x16x32_bf16 v[108:111], v[158:161], v[198:201], v[108:111]
	v_mfma_f32_16x16x32_bf16 v[104:107], v[166:169], v[198:201], v[104:107]
	v_mfma_f32_16x16x32_bf16 v[92:95], v[158:161], v[206:209], v[92:95]
	v_mfma_f32_16x16x32_bf16 v[88:91], v[166:169], v[206:209], v[88:91]
	v_mfma_f32_16x16x32_bf16 v[76:79], v[158:161], v[214:217], v[76:79]
	v_mfma_f32_16x16x32_bf16 v[72:75], v[166:169], v[214:217], v[72:75]
	v_mfma_f32_16x16x32_bf16 v[116:119], v[170:173], v[186:189], v[116:119]
	v_mfma_f32_16x16x32_bf16 v[112:115], v[178:181], v[186:189], v[112:115]
	v_mfma_f32_16x16x32_bf16 v[100:103], v[170:173], v[194:197], v[100:103]
	v_mfma_f32_16x16x32_bf16 v[96:99], v[178:181], v[194:197], v[96:99]
	v_mfma_f32_16x16x32_bf16 v[84:87], v[170:173], v[202:205], v[84:87]
	v_mfma_f32_16x16x32_bf16 v[80:83], v[178:181], v[202:205], v[80:83]
	v_mfma_f32_16x16x32_bf16 v[68:71], v[170:173], v[210:213], v[68:71]
	v_mfma_f32_16x16x32_bf16 v[64:67], v[178:181], v[210:213], v[64:67]
	v_mfma_f32_16x16x32_bf16 v[116:119], v[174:177], v[190:193], v[116:119]
	v_mfma_f32_16x16x32_bf16 v[112:115], v[182:185], v[190:193], v[112:115]
	v_mfma_f32_16x16x32_bf16 v[100:103], v[174:177], v[198:201], v[100:103]
	v_mfma_f32_16x16x32_bf16 v[96:99], v[182:185], v[198:201], v[96:99]
	v_mfma_f32_16x16x32_bf16 v[84:87], v[174:177], v[206:209], v[84:87]
	v_mfma_f32_16x16x32_bf16 v[80:83], v[182:185], v[206:209], v[80:83]
	v_mfma_f32_16x16x32_bf16 v[68:71], v[174:177], v[214:217], v[68:71]
	v_mfma_f32_16x16x32_bf16 v[64:67], v[182:185], v[214:217], v[64:67]
	v_mfma_f32_16x16x32_bf16 v[60:63], v[144:147], v[220:223], v[60:63]
	v_mfma_f32_16x16x32_bf16 v[56:59], v[162:165], v[220:223], v[56:59]
	v_mfma_f32_16x16x32_bf16 v[44:47], v[144:147], v[228:231], v[44:47]
	v_mfma_f32_16x16x32_bf16 v[40:43], v[162:165], v[228:231], v[40:43]
	v_mfma_f32_16x16x32_bf16 v[28:31], v[144:147], v[236:239], v[28:31]
	v_mfma_f32_16x16x32_bf16 v[24:27], v[162:165], v[236:239], v[24:27]
	v_mfma_f32_16x16x32_bf16 v[12:15], v[144:147], v[244:247], v[12:15]
	v_mfma_f32_16x16x32_bf16 v[8:11], v[162:165], v[244:247], v[8:11]
	v_mfma_f32_16x16x32_bf16 v[60:63], v[158:161], v[224:227], v[60:63]
	v_mfma_f32_16x16x32_bf16 v[56:59], v[166:169], v[224:227], v[56:59]
	v_mfma_f32_16x16x32_bf16 v[44:47], v[158:161], v[232:235], v[44:47]
	v_mfma_f32_16x16x32_bf16 v[40:43], v[166:169], v[232:235], v[40:43]
	v_mfma_f32_16x16x32_bf16 v[28:31], v[158:161], v[240:243], v[28:31]
	v_mfma_f32_16x16x32_bf16 v[24:27], v[166:169], v[240:243], v[24:27]
	v_mfma_f32_16x16x32_bf16 v[12:15], v[158:161], v[248:251], v[12:15]
	v_mfma_f32_16x16x32_bf16 v[8:11], v[166:169], v[248:251], v[8:11]
	v_mfma_f32_16x16x32_bf16 v[52:55], v[170:173], v[220:223], v[52:55]
	v_mfma_f32_16x16x32_bf16 v[48:51], v[178:181], v[220:223], v[48:51]
	v_mfma_f32_16x16x32_bf16 v[36:39], v[170:173], v[228:231], v[36:39]
	v_mfma_f32_16x16x32_bf16 v[32:35], v[178:181], v[228:231], v[32:35]
	v_mfma_f32_16x16x32_bf16 v[20:23], v[170:173], v[236:239], v[20:23]
	v_mfma_f32_16x16x32_bf16 v[16:19], v[178:181], v[236:239], v[16:19]
	v_mfma_f32_16x16x32_bf16 v[4:7], v[170:173], v[244:247], v[4:7]
	v_mfma_f32_16x16x32_bf16 v[0:3], v[178:181], v[244:247], v[0:3]
	v_mfma_f32_16x16x32_bf16 v[52:55], v[174:177], v[224:227], v[52:55]
	v_mfma_f32_16x16x32_bf16 v[48:51], v[182:185], v[224:227], v[48:51]
	v_mfma_f32_16x16x32_bf16 v[36:39], v[174:177], v[232:235], v[36:39]
	v_mfma_f32_16x16x32_bf16 v[32:35], v[182:185], v[232:235], v[32:35]
	v_mfma_f32_16x16x32_bf16 v[20:23], v[174:177], v[240:243], v[20:23]
	v_mfma_f32_16x16x32_bf16 v[16:19], v[182:185], v[240:243], v[16:19]
	v_mfma_f32_16x16x32_bf16 v[4:7], v[174:177], v[248:251], v[4:7]
	v_mfma_f32_16x16x32_bf16 v[0:3], v[182:185], v[248:251], v[0:3]
	s_waitcnt vmcnt(0)
	s_barrier
	s_add_i32 s58, s58, 2
	s_add_u32 s34, s34, 0x100
	s_addc_u32 s35, s35, 0
	s_add_u32 s56, s56, 0x100
	s_addc_u32 s57, s57, 0
	s_cmp_gt_u32 s58, 29
	s_cbranch_scc0 .LBB0_761
	s_branch .Lk64_done_p5
.Lk64_trail_p5:
	s_setprio 1
	s_sub_u32 vcc_lo, s34, 0x80000
	s_subb_u32 vcc_hi, s35, 0
	s_add_i32 m0, s44, 0xa000
	s_nop 0
	global_load_lds_dwordx4 v132, vcc
	s_add_u32 vcc_lo, vcc_lo, 0x20000
	s_addc_u32 vcc_hi, vcc_hi, 0
	s_add_i32 m0, s44, 0x9000
	s_nop 0
	global_load_lds_dwordx4 v128, vcc
	s_add_u32 vcc_lo, vcc_lo, 0x60000
	s_addc_u32 vcc_hi, vcc_hi, 0
	s_add_i32 m0, s44, 0xe000
	s_nop 0
	global_load_lds_dwordx4 v132, vcc
	s_add_u32 vcc_lo, vcc_lo, 0x20000
	s_addc_u32 vcc_hi, vcc_hi, 0
	s_add_i32 m0, s44, 0xd000
	s_nop 0
	global_load_lds_dwordx4 v128, vcc
	s_add_u32 vcc_lo, s42, 0x0
	s_addc_u32 vcc_hi, s43, 0
	s_mov_b32 m0, s44
	s_nop 0
	global_load_lds_dwordx4 v128, vcc
	s_sub_u32 vcc_lo, vcc_lo, 0x20000
	s_subb_u32 vcc_hi, vcc_hi, 0
	s_sub_i32 m0, s44, 0x1000
	s_nop 0
	global_load_lds_dwordx4 v128, vcc
	s_add_u32 vcc_lo, vcc_lo, 0xa0000
	s_addc_u32 vcc_hi, vcc_hi, 0
	s_add_i32 m0, s44, 0x4000
	s_nop 0
	global_load_lds_dwordx4 v128, vcc
	s_sub_u32 vcc_lo, vcc_lo, 0x20000
	s_subb_u32 vcc_hi, vcc_hi, 0
	s_add_i32 m0, s44, 0x3000
	s_nop 0
	global_load_lds_dwordx4 v128, vcc
	ds_read_b128 v[144:147], v153 offset:0
	ds_read_b128 v[158:161], v153 offset:1024
	ds_read_b128 v[162:165], v153 offset:2048
	ds_read_b128 v[166:169], v153 offset:3072
	ds_read_b128 v[170:173], v154 offset:0
	ds_read_b128 v[174:177], v154 offset:1024
	ds_read_b128 v[178:181], v154 offset:2048
	ds_read_b128 v[182:185], v154 offset:3072
	ds_read_b128 v[186:189], v155 offset:0
	ds_read_b128 v[190:193], v155 offset:1024
	ds_read_b128 v[194:197], v155 offset:2048
	ds_read_b128 v[198:201], v155 offset:3072
	ds_read_b128 v[202:205], v155 offset:4096
	ds_read_b128 v[206:209], v155 offset:5120
	ds_read_b128 v[210:213], v155 offset:6144
	ds_read_b128 v[214:217], v155 offset:7168
	ds_read_b128 v[220:223], v155 offset:16384
	ds_read_b128 v[224:227], v155 offset:17408
	ds_read_b128 v[228:231], v155 offset:18432
	ds_read_b128 v[232:235], v155 offset:19456
	ds_read_b128 v[236:239], v155 offset:20480
	ds_read_b128 v[240:243], v155 offset:21504
	ds_read_b128 v[244:247], v155 offset:22528
	ds_read_b128 v[248:251], v155 offset:23552
	s_nop 15
	s_nop 15
	s_waitcnt lgkmcnt(0)
	s_barrier
	v_mfma_f32_16x16x32_bf16 v[124:127], v[144:147], v[186:189], v[124:127]
	v_mfma_f32_16x16x32_bf16 v[120:123], v[162:165], v[186:189], v[120:123]
	v_mfma_f32_16x16x32_bf16 v[108:111], v[144:147], v[194:197], v[108:111]
	v_mfma_f32_16x16x32_bf16 v[104:107], v[162:165], v[194:197], v[104:107]
	v_mfma_f32_16x16x32_bf16 v[92:95], v[144:147], v[202:205], v[92:95]
	v_mfma_f32_16x16x32_bf16 v[88:91], v[162:165], v[202:205], v[88:91]
	v_mfma_f32_16x16x32_bf16 v[76:79], v[144:147], v[210:213], v[76:79]
	v_mfma_f32_16x16x32_bf16 v[72:75], v[162:165], v[210:213], v[72:75]
	v_mfma_f32_16x16x32_bf16 v[124:127], v[158:161], v[190:193], v[124:127]
	v_mfma_f32_16x16x32_bf16 v[120:123], v[166:169], v[190:193], v[120:123]
	v_mfma_f32_16x16x32_bf16 v[108:111], v[158:161], v[198:201], v[108:111]
	v_mfma_f32_16x16x32_bf16 v[104:107], v[166:169], v[198:201], v[104:107]
	v_mfma_f32_16x16x32_bf16 v[92:95], v[158:161], v[206:209], v[92:95]
	v_mfma_f32_16x16x32_bf16 v[88:91], v[166:169], v[206:209], v[88:91]
	v_mfma_f32_16x16x32_bf16 v[76:79], v[158:161], v[214:217], v[76:79]
	v_mfma_f32_16x16x32_bf16 v[72:75], v[166:169], v[214:217], v[72:75]
	v_mfma_f32_16x16x32_bf16 v[116:119], v[170:173], v[186:189], v[116:119]
	v_mfma_f32_16x16x32_bf16 v[112:115], v[178:181], v[186:189], v[112:115]
	v_mfma_f32_16x16x32_bf16 v[100:103], v[170:173], v[194:197], v[100:103]
	v_mfma_f32_16x16x32_bf16 v[96:99], v[178:181], v[194:197], v[96:99]
	v_mfma_f32_16x16x32_bf16 v[84:87], v[170:173], v[202:205], v[84:87]
	v_mfma_f32_16x16x32_bf16 v[80:83], v[178:181], v[202:205], v[80:83]
	v_mfma_f32_16x16x32_bf16 v[68:71], v[170:173], v[210:213], v[68:71]
	v_mfma_f32_16x16x32_bf16 v[64:67], v[178:181], v[210:213], v[64:67]
	v_mfma_f32_16x16x32_bf16 v[116:119], v[174:177], v[190:193], v[116:119]
	v_mfma_f32_16x16x32_bf16 v[112:115], v[182:185], v[190:193], v[112:115]
	v_mfma_f32_16x16x32_bf16 v[100:103], v[174:177], v[198:201], v[100:103]
	v_mfma_f32_16x16x32_bf16 v[96:99], v[182:185], v[198:201], v[96:99]
	v_mfma_f32_16x16x32_bf16 v[84:87], v[174:177], v[206:209], v[84:87]
	v_mfma_f32_16x16x32_bf16 v[80:83], v[182:185], v[206:209], v[80:83]
	v_mfma_f32_16x16x32_bf16 v[68:71], v[174:177], v[214:217], v[68:71]
	v_mfma_f32_16x16x32_bf16 v[64:67], v[182:185], v[214:217], v[64:67]
	v_mfma_f32_16x16x32_bf16 v[60:63], v[144:147], v[220:223], v[60:63]
	v_mfma_f32_16x16x32_bf16 v[56:59], v[162:165], v[220:223], v[56:59]
	v_mfma_f32_16x16x32_bf16 v[44:47], v[144:147], v[228:231], v[44:47]
	v_mfma_f32_16x16x32_bf16 v[40:43], v[162:165], v[228:231], v[40:43]
	v_mfma_f32_16x16x32_bf16 v[28:31], v[144:147], v[236:239], v[28:31]
	v_mfma_f32_16x16x32_bf16 v[24:27], v[162:165], v[236:239], v[24:27]
	v_mfma_f32_16x16x32_bf16 v[12:15], v[144:147], v[244:247], v[12:15]
	v_mfma_f32_16x16x32_bf16 v[8:11], v[162:165], v[244:247], v[8:11]
	v_mfma_f32_16x16x32_bf16 v[60:63], v[158:161], v[224:227], v[60:63]
	v_mfma_f32_16x16x32_bf16 v[56:59], v[166:169], v[224:227], v[56:59]
	v_mfma_f32_16x16x32_bf16 v[44:47], v[158:161], v[232:235], v[44:47]
	v_mfma_f32_16x16x32_bf16 v[40:43], v[166:169], v[232:235], v[40:43]
	v_mfma_f32_16x16x32_bf16 v[28:31], v[158:161], v[240:243], v[28:31]
	v_mfma_f32_16x16x32_bf16 v[24:27], v[166:169], v[240:243], v[24:27]
	v_mfma_f32_16x16x32_bf16 v[12:15], v[158:161], v[248:251], v[12:15]
	v_mfma_f32_16x16x32_bf16 v[8:11], v[166:169], v[248:251], v[8:11]
	v_mfma_f32_16x16x32_bf16 v[52:55], v[170:173], v[220:223], v[52:55]
	v_mfma_f32_16x16x32_bf16 v[48:51], v[178:181], v[220:223], v[48:51]
	v_mfma_f32_16x16x32_bf16 v[36:39], v[170:173], v[228:231], v[36:39]
	v_mfma_f32_16x16x32_bf16 v[32:35], v[178:181], v[228:231], v[32:35]
	v_mfma_f32_16x16x32_bf16 v[20:23], v[170:173], v[236:239], v[20:23]
	v_mfma_f32_16x16x32_bf16 v[16:19], v[178:181], v[236:239], v[16:19]
	v_mfma_f32_16x16x32_bf16 v[4:7], v[170:173], v[244:247], v[4:7]
	v_mfma_f32_16x16x32_bf16 v[0:3], v[178:181], v[244:247], v[0:3]
	v_mfma_f32_16x16x32_bf16 v[52:55], v[174:177], v[224:227], v[52:55]
	v_mfma_f32_16x16x32_bf16 v[48:51], v[182:185], v[224:227], v[48:51]
	v_mfma_f32_16x16x32_bf16 v[36:39], v[174:177], v[232:235], v[36:39]
	v_mfma_f32_16x16x32_bf16 v[32:35], v[182:185], v[232:235], v[32:35]
	v_mfma_f32_16x16x32_bf16 v[20:23], v[174:177], v[240:243], v[20:23]
	v_mfma_f32_16x16x32_bf16 v[16:19], v[182:185], v[240:243], v[16:19]
	v_mfma_f32_16x16x32_bf16 v[4:7], v[174:177], v[248:251], v[4:7]
	v_mfma_f32_16x16x32_bf16 v[0:3], v[182:185], v[248:251], v[0:3]
	s_waitcnt vmcnt(0)
	s_barrier
	s_add_u32 vcc_lo, s42, 0x0
	s_addc_u32 vcc_hi, s43, 0
	s_add_i32 m0, s44, 0x2000
	s_nop 0
	global_load_lds_dwordx4 v132, vcc
	s_add_u32 vcc_lo, vcc_lo, 0x20000
	s_addc_u32 vcc_hi, vcc_hi, 0
	s_add_i32 m0, s44, 0x1000
	s_nop 0
	global_load_lds_dwordx4 v128, vcc
	s_add_u32 vcc_lo, vcc_lo, 0x60000
	s_addc_u32 vcc_hi, vcc_hi, 0
	s_add_i32 m0, s44, 0x6000
	s_nop 0
	global_load_lds_dwordx4 v132, vcc
	s_add_u32 vcc_lo, vcc_lo, 0x20000
	s_addc_u32 vcc_hi, vcc_hi, 0
	s_add_i32 m0, s44, 0x5000
	s_nop 0
	global_load_lds_dwordx4 v128, vcc
	s_add_u32 vcc_lo, s42, 0x80
	s_addc_u32 vcc_hi, s43, 0
	s_add_i32 m0, s44, 0x8000
	s_nop 0
	global_load_lds_dwordx4 v128, vcc
	s_sub_u32 vcc_lo, vcc_lo, 0x20000
	s_subb_u32 vcc_hi, vcc_hi, 0
	s_add_i32 m0, s44, 0x7000
	s_nop 0
	global_load_lds_dwordx4 v128, vcc
	s_add_u32 vcc_lo, vcc_lo, 0xa0000
	s_addc_u32 vcc_hi, vcc_hi, 0
	s_add_i32 m0, s44, 0xc000
	s_nop 0
	global_load_lds_dwordx4 v128, vcc
	s_sub_u32 vcc_lo, vcc_lo, 0x20000
	s_subb_u32 vcc_hi, vcc_hi, 0
	s_add_i32 m0, s44, 0xb000
	s_nop 0
	global_load_lds_dwordx4 v128, vcc
	ds_read_b128 v[144:147], v153 offset:32768
	ds_read_b128 v[158:161], v153 offset:33792
	ds_read_b128 v[162:165], v153 offset:34816
	ds_read_b128 v[166:169], v153 offset:35840
	ds_read_b128 v[170:173], v154 offset:32768
	ds_read_b128 v[174:177], v154 offset:33792
	ds_read_b128 v[178:181], v154 offset:34816
	ds_read_b128 v[182:185], v154 offset:35840
	ds_read_b128 v[186:189], v155 offset:32768
	ds_read_b128 v[190:193], v155 offset:33792
	ds_read_b128 v[194:197], v155 offset:34816
	ds_read_b128 v[198:201], v155 offset:35840
	ds_read_b128 v[202:205], v155 offset:36864
	ds_read_b128 v[206:209], v155 offset:37888
	ds_read_b128 v[210:213], v155 offset:38912
	ds_read_b128 v[214:217], v155 offset:39936
	ds_read_b128 v[220:223], v155 offset:49152
	ds_read_b128 v[224:227], v155 offset:50176
	ds_read_b128 v[228:231], v155 offset:51200
	ds_read_b128 v[232:235], v155 offset:52224
	ds_read_b128 v[236:239], v155 offset:53248
	ds_read_b128 v[240:243], v155 offset:54272
	ds_read_b128 v[244:247], v155 offset:55296
	ds_read_b128 v[248:251], v155 offset:56320
	s_nop 15
	s_nop 15
	s_waitcnt lgkmcnt(0)
	s_barrier
	v_mfma_f32_16x16x32_bf16 v[124:127], v[144:147], v[186:189], v[124:127]
	v_mfma_f32_16x16x32_bf16 v[120:123], v[162:165], v[186:189], v[120:123]
	v_mfma_f32_16x16x32_bf16 v[108:111], v[144:147], v[194:197], v[108:111]
	v_mfma_f32_16x16x32_bf16 v[104:107], v[162:165], v[194:197], v[104:107]
	v_mfma_f32_16x16x32_bf16 v[92:95], v[144:147], v[202:205], v[92:95]
	v_mfma_f32_16x16x32_bf16 v[88:91], v[162:165], v[202:205], v[88:91]
	v_mfma_f32_16x16x32_bf16 v[76:79], v[144:147], v[210:213], v[76:79]
	v_mfma_f32_16x16x32_bf16 v[72:75], v[162:165], v[210:213], v[72:75]
	v_mfma_f32_16x16x32_bf16 v[124:127], v[158:161], v[190:193], v[124:127]
	v_mfma_f32_16x16x32_bf16 v[120:123], v[166:169], v[190:193], v[120:123]
	v_mfma_f32_16x16x32_bf16 v[108:111], v[158:161], v[198:201], v[108:111]
	v_mfma_f32_16x16x32_bf16 v[104:107], v[166:169], v[198:201], v[104:107]
	v_mfma_f32_16x16x32_bf16 v[92:95], v[158:161], v[206:209], v[92:95]
	v_mfma_f32_16x16x32_bf16 v[88:91], v[166:169], v[206:209], v[88:91]
	v_mfma_f32_16x16x32_bf16 v[76:79], v[158:161], v[214:217], v[76:79]
	v_mfma_f32_16x16x32_bf16 v[72:75], v[166:169], v[214:217], v[72:75]
	v_mfma_f32_16x16x32_bf16 v[116:119], v[170:173], v[186:189], v[116:119]
	v_mfma_f32_16x16x32_bf16 v[112:115], v[178:181], v[186:189], v[112:115]
	v_mfma_f32_16x16x32_bf16 v[100:103], v[170:173], v[194:197], v[100:103]
	v_mfma_f32_16x16x32_bf16 v[96:99], v[178:181], v[194:197], v[96:99]
	v_mfma_f32_16x16x32_bf16 v[84:87], v[170:173], v[202:205], v[84:87]
	v_mfma_f32_16x16x32_bf16 v[80:83], v[178:181], v[202:205], v[80:83]
	v_mfma_f32_16x16x32_bf16 v[68:71], v[170:173], v[210:213], v[68:71]
	v_mfma_f32_16x16x32_bf16 v[64:67], v[178:181], v[210:213], v[64:67]
	v_mfma_f32_16x16x32_bf16 v[116:119], v[174:177], v[190:193], v[116:119]
	v_mfma_f32_16x16x32_bf16 v[112:115], v[182:185], v[190:193], v[112:115]
	v_mfma_f32_16x16x32_bf16 v[100:103], v[174:177], v[198:201], v[100:103]
	v_mfma_f32_16x16x32_bf16 v[96:99], v[182:185], v[198:201], v[96:99]
	v_mfma_f32_16x16x32_bf16 v[84:87], v[174:177], v[206:209], v[84:87]
	v_mfma_f32_16x16x32_bf16 v[80:83], v[182:185], v[206:209], v[80:83]
	v_mfma_f32_16x16x32_bf16 v[68:71], v[174:177], v[214:217], v[68:71]
	v_mfma_f32_16x16x32_bf16 v[64:67], v[182:185], v[214:217], v[64:67]
	v_mfma_f32_16x16x32_bf16 v[60:63], v[144:147], v[220:223], v[60:63]
	v_mfma_f32_16x16x32_bf16 v[56:59], v[162:165], v[220:223], v[56:59]
	v_mfma_f32_16x16x32_bf16 v[44:47], v[144:147], v[228:231], v[44:47]
	v_mfma_f32_16x16x32_bf16 v[40:43], v[162:165], v[228:231], v[40:43]
	v_mfma_f32_16x16x32_bf16 v[28:31], v[144:147], v[236:239], v[28:31]
	v_mfma_f32_16x16x32_bf16 v[24:27], v[162:165], v[236:239], v[24:27]
	v_mfma_f32_16x16x32_bf16 v[12:15], v[144:147], v[244:247], v[12:15]
	v_mfma_f32_16x16x32_bf16 v[8:11], v[162:165], v[244:247], v[8:11]
	v_mfma_f32_16x16x32_bf16 v[60:63], v[158:161], v[224:227], v[60:63]
	v_mfma_f32_16x16x32_bf16 v[56:59], v[166:169], v[224:227], v[56:59]
	v_mfma_f32_16x16x32_bf16 v[44:47], v[158:161], v[232:235], v[44:47]
	v_mfma_f32_16x16x32_bf16 v[40:43], v[166:169], v[232:235], v[40:43]
	v_mfma_f32_16x16x32_bf16 v[28:31], v[158:161], v[240:243], v[28:31]
	v_mfma_f32_16x16x32_bf16 v[24:27], v[166:169], v[240:243], v[24:27]
	v_mfma_f32_16x16x32_bf16 v[12:15], v[158:161], v[248:251], v[12:15]
	v_mfma_f32_16x16x32_bf16 v[8:11], v[166:169], v[248:251], v[8:11]
	v_mfma_f32_16x16x32_bf16 v[52:55], v[170:173], v[220:223], v[52:55]
	v_mfma_f32_16x16x32_bf16 v[48:51], v[178:181], v[220:223], v[48:51]
	v_mfma_f32_16x16x32_bf16 v[36:39], v[170:173], v[228:231], v[36:39]
	v_mfma_f32_16x16x32_bf16 v[32:35], v[178:181], v[228:231], v[32:35]
	v_mfma_f32_16x16x32_bf16 v[20:23], v[170:173], v[236:239], v[20:23]
	v_mfma_f32_16x16x32_bf16 v[16:19], v[178:181], v[236:239], v[16:19]
	v_mfma_f32_16x16x32_bf16 v[4:7], v[170:173], v[244:247], v[4:7]
	v_mfma_f32_16x16x32_bf16 v[0:3], v[178:181], v[244:247], v[0:3]
	v_mfma_f32_16x16x32_bf16 v[52:55], v[174:177], v[224:227], v[52:55]
	v_mfma_f32_16x16x32_bf16 v[48:51], v[182:185], v[224:227], v[48:51]
	v_mfma_f32_16x16x32_bf16 v[36:39], v[174:177], v[232:235], v[36:39]
	v_mfma_f32_16x16x32_bf16 v[32:35], v[182:185], v[232:235], v[32:35]
	v_mfma_f32_16x16x32_bf16 v[20:23], v[174:177], v[240:243], v[20:23]
	v_mfma_f32_16x16x32_bf16 v[16:19], v[182:185], v[240:243], v[16:19]
	v_mfma_f32_16x16x32_bf16 v[4:7], v[174:177], v[248:251], v[4:7]
	v_mfma_f32_16x16x32_bf16 v[0:3], v[182:185], v[248:251], v[0:3]
	s_waitcnt vmcnt(0)
	s_barrier
	s_add_i32 s58, s58, 2
	s_add_u32 s34, s34, 0x100
	s_addc_u32 s35, s35, 0
	s_add_u32 s56, s56, 0x100
	s_addc_u32 s57, s57, 0
	s_cmp_gt_u32 s58, 29
	s_cbranch_scc0 .LBB0_761
.Lk64_done_p5:
	s_setprio 0
	s_and_b64 vcc, exec, s[10:11]
	s_cbranch_vccz .LBB0_764
	s_barrier

.Lk64_epd_p6_l:
	ds_read_b128 v[32:35], v169 offset:0
	ds_read_b128 v[36:39], v169 offset:1024
	ds_read_b128 v[40:43], v169 offset:2048
	ds_read_b128 v[44:47], v169 offset:3072
	ds_read_b128 v[162:165], v170 offset:0
	ds_read_b128 v[174:177], v170 offset:1024
	ds_read_b128 v[178:181], v170 offset:2048
	ds_read_b128 v[182:185], v170 offset:3072
	ds_read_b128 v[186:189], v171 offset:0
	ds_read_b128 v[190:193], v171 offset:1024
	ds_read_b128 v[194:197], v171 offset:2048
	ds_read_b128 v[198:201], v171 offset:3072
	ds_read_b128 v[202:205], v171 offset:4096
	ds_read_b128 v[206:209], v171 offset:5120
	ds_read_b128 v[210:213], v171 offset:6144
	ds_read_b128 v[214:217], v171 offset:7168
	ds_read_b128 v[220:223], v171 offset:16384
	ds_read_b128 v[224:227], v171 offset:17408
	ds_read_b128 v[228:231], v171 offset:18432
	ds_read_b128 v[232:235], v171 offset:19456
	ds_read_b128 v[236:239], v171 offset:20480
	ds_read_b128 v[240:243], v171 offset:21504
	ds_read_b128 v[244:247], v171 offset:22528
	ds_read_b128 v[248:251], v171 offset:23552
	s_nop 15
	s_nop 15
	s_waitcnt lgkmcnt(0)
	s_barrier
	v_mfma_f32_16x16x32_bf16 v[140:143], v[32:35], v[186:189], v[140:143]
	v_mfma_f32_16x16x32_bf16 v[136:139], v[40:43], v[186:189], v[136:139]
	v_mfma_f32_16x16x32_bf16 v[124:127], v[32:35], v[194:197], v[124:127]
	v_mfma_f32_16x16x32_bf16 v[120:123], v[40:43], v[194:197], v[120:123]
	v_mfma_f32_16x16x32_bf16 v[108:111], v[32:35], v[202:205], v[108:111]
	v_mfma_f32_16x16x32_bf16 v[104:107], v[40:43], v[202:205], v[104:107]
	v_mfma_f32_16x16x32_bf16 v[92:95], v[32:35], v[210:213], v[92:95]
	v_mfma_f32_16x16x32_bf16 v[88:91], v[40:43], v[210:213], v[88:91]
	v_mfma_f32_16x16x32_bf16 v[140:143], v[36:39], v[190:193], v[140:143]
	v_mfma_f32_16x16x32_bf16 v[136:139], v[44:47], v[190:193], v[136:139]
	v_mfma_f32_16x16x32_bf16 v[124:127], v[36:39], v[198:201], v[124:127]
	v_mfma_f32_16x16x32_bf16 v[120:123], v[44:47], v[198:201], v[120:123]
	v_mfma_f32_16x16x32_bf16 v[108:111], v[36:39], v[206:209], v[108:111]
	v_mfma_f32_16x16x32_bf16 v[104:107], v[44:47], v[206:209], v[104:107]
	v_mfma_f32_16x16x32_bf16 v[92:95], v[36:39], v[214:217], v[92:95]
	v_mfma_f32_16x16x32_bf16 v[88:91], v[44:47], v[214:217], v[88:91]
	v_mfma_f32_16x16x32_bf16 v[132:135], v[162:165], v[186:189], v[132:135]
	v_mfma_f32_16x16x32_bf16 v[128:131], v[178:181], v[186:189], v[128:131]
	v_mfma_f32_16x16x32_bf16 v[116:119], v[162:165], v[194:197], v[116:119]
	v_mfma_f32_16x16x32_bf16 v[112:115], v[178:181], v[194:197], v[112:115]
	v_mfma_f32_16x16x32_bf16 v[100:103], v[162:165], v[202:205], v[100:103]
	v_mfma_f32_16x16x32_bf16 v[96:99], v[178:181], v[202:205], v[96:99]
	v_mfma_f32_16x16x32_bf16 v[84:87], v[162:165], v[210:213], v[84:87]
	v_mfma_f32_16x16x32_bf16 v[80:83], v[178:181], v[210:213], v[80:83]
	v_mfma_f32_16x16x32_bf16 v[132:135], v[174:177], v[190:193], v[132:135]
	v_mfma_f32_16x16x32_bf16 v[128:131], v[182:185], v[190:193], v[128:131]
	v_mfma_f32_16x16x32_bf16 v[116:119], v[174:177], v[198:201], v[116:119]
	v_mfma_f32_16x16x32_bf16 v[112:115], v[182:185], v[198:201], v[112:115]
	v_mfma_f32_16x16x32_bf16 v[100:103], v[174:177], v[206:209], v[100:103]
	v_mfma_f32_16x16x32_bf16 v[96:99], v[182:185], v[206:209], v[96:99]
	v_mfma_f32_16x16x32_bf16 v[84:87], v[174:177], v[214:217], v[84:87]
	v_mfma_f32_16x16x32_bf16 v[80:83], v[182:185], v[214:217], v[80:83]
	v_mfma_f32_16x16x32_bf16 v[76:79], v[32:35], v[220:223], v[76:79]
	v_mfma_f32_16x16x32_bf16 v[72:75], v[40:43], v[220:223], v[72:75]
	v_mfma_f32_16x16x32_bf16 v[60:63], v[32:35], v[228:231], v[60:63]
	v_mfma_f32_16x16x32_bf16 v[56:59], v[40:43], v[228:231], v[56:59]
	v_mfma_f32_16x16x32_bf16 v[28:31], v[32:35], v[236:239], v[28:31]
	v_mfma_f32_16x16x32_bf16 v[24:27], v[40:43], v[236:239], v[24:27]
	v_mfma_f32_16x16x32_bf16 v[12:15], v[32:35], v[244:247], v[12:15]
	v_mfma_f32_16x16x32_bf16 v[8:11], v[40:43], v[244:247], v[8:11]
	v_mfma_f32_16x16x32_bf16 v[76:79], v[36:39], v[224:227], v[76:79]
	v_mfma_f32_16x16x32_bf16 v[72:75], v[44:47], v[224:227], v[72:75]
	v_mfma_f32_16x16x32_bf16 v[60:63], v[36:39], v[232:235], v[60:63]
	v_mfma_f32_16x16x32_bf16 v[56:59], v[44:47], v[232:235], v[56:59]
	v_mfma_f32_16x16x32_bf16 v[28:31], v[36:39], v[240:243], v[28:31]
	v_mfma_f32_16x16x32_bf16 v[24:27], v[44:47], v[240:243], v[24:27]
	v_mfma_f32_16x16x32_bf16 v[12:15], v[36:39], v[248:251], v[12:15]
	v_mfma_f32_16x16x32_bf16 v[8:11], v[44:47], v[248:251], v[8:11]
	v_mfma_f32_16x16x32_bf16 v[68:71], v[162:165], v[220:223], v[68:71]
	v_mfma_f32_16x16x32_bf16 v[64:67], v[178:181], v[220:223], v[64:67]
	v_mfma_f32_16x16x32_bf16 v[52:55], v[162:165], v[228:231], v[52:55]
	v_mfma_f32_16x16x32_bf16 v[48:51], v[178:181], v[228:231], v[48:51]
	v_mfma_f32_16x16x32_bf16 v[20:23], v[162:165], v[236:239], v[20:23]
	v_mfma_f32_16x16x32_bf16 v[16:19], v[178:181], v[236:239], v[16:19]
	v_mfma_f32_16x16x32_bf16 v[4:7], v[162:165], v[244:247], v[4:7]
	v_mfma_f32_16x16x32_bf16 v[0:3], v[178:181], v[244:247], v[0:3]
	v_mfma_f32_16x16x32_bf16 v[68:71], v[174:177], v[224:227], v[68:71]
	v_mfma_f32_16x16x32_bf16 v[64:67], v[182:185], v[224:227], v[64:67]
	v_mfma_f32_16x16x32_bf16 v[52:55], v[174:177], v[232:235], v[52:55]
	v_mfma_f32_16x16x32_bf16 v[48:51], v[182:185], v[232:235], v[48:51]
	v_mfma_f32_16x16x32_bf16 v[20:23], v[174:177], v[240:243], v[20:23]
	v_mfma_f32_16x16x32_bf16 v[16:19], v[182:185], v[240:243], v[16:19]
	v_mfma_f32_16x16x32_bf16 v[4:7], v[174:177], v[248:251], v[4:7]
	v_mfma_f32_16x16x32_bf16 v[0:3], v[182:185], v[248:251], v[0:3]
	s_waitcnt vmcnt(0)
	s_barrier
	s_add_u32 vcc_lo, s30, 0x0
	s_addc_u32 vcc_hi, s31, 0
	s_add_i32 m0, s37, 0x10000
	s_nop 0
	global_load_lds_dwordx4 v148, vcc
	s_add_i32 m0, s37, 0x12000
	s_nop 0
	global_load_lds_dwordx4 v144, vcc
	s_add_u32 vcc_lo, vcc_lo, 0x20000
	s_addc_u32 vcc_hi, vcc_hi, 0
	s_add_i32 m0, s37, 0x11000
	s_nop 0
	global_load_lds_dwordx4 v148, vcc
	s_add_i32 m0, s37, 0x13000
	s_nop 0
	global_load_lds_dwordx4 v144, vcc
	s_add_u32 vcc_lo, vcc_lo, 0x60000
	s_addc_u32 vcc_hi, vcc_hi, 0
	s_add_i32 m0, s37, 0x14000
	s_nop 0
	global_load_lds_dwordx4 v148, vcc
	s_add_i32 m0, s37, 0x16000
	s_nop 0
	global_load_lds_dwordx4 v144, vcc
	s_add_u32 vcc_lo, vcc_lo, 0x20000
	s_addc_u32 vcc_hi, vcc_hi, 0
	s_add_i32 m0, s37, 0x15000
	s_nop 0
	global_load_lds_dwordx4 v148, vcc
	s_add_i32 m0, s37, 0x17000
	s_nop 0
	global_load_lds_dwordx4 v144, vcc
	ds_read_b128 v[32:35], v169 offset:32768
	ds_read_b128 v[36:39], v169 offset:33792
	ds_read_b128 v[40:43], v169 offset:34816
	ds_read_b128 v[44:47], v169 offset:35840
	ds_read_b128 v[162:165], v170 offset:32768
	ds_read_b128 v[174:177], v170 offset:33792
	ds_read_b128 v[178:181], v170 offset:34816
	ds_read_b128 v[182:185], v170 offset:35840
	ds_read_b128 v[186:189], v171 offset:32768
	ds_read_b128 v[190:193], v171 offset:33792
	ds_read_b128 v[194:197], v171 offset:34816
	ds_read_b128 v[198:201], v171 offset:35840
	ds_read_b128 v[202:205], v171 offset:36864
	ds_read_b128 v[206:209], v171 offset:37888
	ds_read_b128 v[210:213], v171 offset:38912
	ds_read_b128 v[214:217], v171 offset:39936
	ds_read_b128 v[220:223], v171 offset:49152
	ds_read_b128 v[224:227], v171 offset:50176
	ds_read_b128 v[228:231], v171 offset:51200
	ds_read_b128 v[232:235], v171 offset:52224
	ds_read_b128 v[236:239], v171 offset:53248
	ds_read_b128 v[240:243], v171 offset:54272
	ds_read_b128 v[244:247], v171 offset:55296
	ds_read_b128 v[248:251], v171 offset:56320
	s_nop 15
	s_nop 15
	s_waitcnt lgkmcnt(0)
	s_barrier
	v_mfma_f32_16x16x32_bf16 v[140:143], v[32:35], v[186:189], v[140:143]
	v_mfma_f32_16x16x32_bf16 v[136:139], v[40:43], v[186:189], v[136:139]
	v_mfma_f32_16x16x32_bf16 v[124:127], v[32:35], v[194:197], v[124:127]
	v_mfma_f32_16x16x32_bf16 v[120:123], v[40:43], v[194:197], v[120:123]
	v_mfma_f32_16x16x32_bf16 v[108:111], v[32:35], v[202:205], v[108:111]
	v_mfma_f32_16x16x32_bf16 v[104:107], v[40:43], v[202:205], v[104:107]
	v_mfma_f32_16x16x32_bf16 v[92:95], v[32:35], v[210:213], v[92:95]
	v_mfma_f32_16x16x32_bf16 v[88:91], v[40:43], v[210:213], v[88:91]
	v_mfma_f32_16x16x32_bf16 v[140:143], v[36:39], v[190:193], v[140:143]
	v_mfma_f32_16x16x32_bf16 v[136:139], v[44:47], v[190:193], v[136:139]
	v_mfma_f32_16x16x32_bf16 v[124:127], v[36:39], v[198:201], v[124:127]
	v_mfma_f32_16x16x32_bf16 v[120:123], v[44:47], v[198:201], v[120:123]
	v_mfma_f32_16x16x32_bf16 v[108:111], v[36:39], v[206:209], v[108:111]
	v_mfma_f32_16x16x32_bf16 v[104:107], v[44:47], v[206:209], v[104:107]
	v_mfma_f32_16x16x32_bf16 v[92:95], v[36:39], v[214:217], v[92:95]
	v_mfma_f32_16x16x32_bf16 v[88:91], v[44:47], v[214:217], v[88:91]
	v_mfma_f32_16x16x32_bf16 v[132:135], v[162:165], v[186:189], v[132:135]
	v_mfma_f32_16x16x32_bf16 v[128:131], v[178:181], v[186:189], v[128:131]
	v_mfma_f32_16x16x32_bf16 v[116:119], v[162:165], v[194:197], v[116:119]
	v_mfma_f32_16x16x32_bf16 v[112:115], v[178:181], v[194:197], v[112:115]
	v_mfma_f32_16x16x32_bf16 v[100:103], v[162:165], v[202:205], v[100:103]
	v_mfma_f32_16x16x32_bf16 v[96:99], v[178:181], v[202:205], v[96:99]
	v_mfma_f32_16x16x32_bf16 v[84:87], v[162:165], v[210:213], v[84:87]
	v_mfma_f32_16x16x32_bf16 v[80:83], v[178:181], v[210:213], v[80:83]
	v_mfma_f32_16x16x32_bf16 v[132:135], v[174:177], v[190:193], v[132:135]
	v_mfma_f32_16x16x32_bf16 v[128:131], v[182:185], v[190:193], v[128:131]
	v_mfma_f32_16x16x32_bf16 v[116:119], v[174:177], v[198:201], v[116:119]
	v_mfma_f32_16x16x32_bf16 v[112:115], v[182:185], v[198:201], v[112:115]
	v_mfma_f32_16x16x32_bf16 v[100:103], v[174:177], v[206:209], v[100:103]
	v_mfma_f32_16x16x32_bf16 v[96:99], v[182:185], v[206:209], v[96:99]
	v_mfma_f32_16x16x32_bf16 v[84:87], v[174:177], v[214:217], v[84:87]
	v_mfma_f32_16x16x32_bf16 v[80:83], v[182:185], v[214:217], v[80:83]
	v_mfma_f32_16x16x32_bf16 v[76:79], v[32:35], v[220:223], v[76:79]
	v_mfma_f32_16x16x32_bf16 v[72:75], v[40:43], v[220:223], v[72:75]
	v_mfma_f32_16x16x32_bf16 v[60:63], v[32:35], v[228:231], v[60:63]
	v_mfma_f32_16x16x32_bf16 v[56:59], v[40:43], v[228:231], v[56:59]
	v_mfma_f32_16x16x32_bf16 v[28:31], v[32:35], v[236:239], v[28:31]
	v_mfma_f32_16x16x32_bf16 v[24:27], v[40:43], v[236:239], v[24:27]
	v_mfma_f32_16x16x32_bf16 v[12:15], v[32:35], v[244:247], v[12:15]
	v_mfma_f32_16x16x32_bf16 v[8:11], v[40:43], v[244:247], v[8:11]
	v_mfma_f32_16x16x32_bf16 v[76:79], v[36:39], v[224:227], v[76:79]
	v_mfma_f32_16x16x32_bf16 v[72:75], v[44:47], v[224:227], v[72:75]
	v_mfma_f32_16x16x32_bf16 v[60:63], v[36:39], v[232:235], v[60:63]
	v_mfma_f32_16x16x32_bf16 v[56:59], v[44:47], v[232:235], v[56:59]
	v_mfma_f32_16x16x32_bf16 v[28:31], v[36:39], v[240:243], v[28:31]
	v_mfma_f32_16x16x32_bf16 v[24:27], v[44:47], v[240:243], v[24:27]
	v_mfma_f32_16x16x32_bf16 v[12:15], v[36:39], v[248:251], v[12:15]
	v_mfma_f32_16x16x32_bf16 v[8:11], v[44:47], v[248:251], v[8:11]
	v_mfma_f32_16x16x32_bf16 v[68:71], v[162:165], v[220:223], v[68:71]
	v_mfma_f32_16x16x32_bf16 v[64:67], v[178:181], v[220:223], v[64:67]
	v_mfma_f32_16x16x32_bf16 v[52:55], v[162:165], v[228:231], v[52:55]
	v_mfma_f32_16x16x32_bf16 v[48:51], v[178:181], v[228:231], v[48:51]
	v_mfma_f32_16x16x32_bf16 v[20:23], v[162:165], v[236:239], v[20:23]
	v_mfma_f32_16x16x32_bf16 v[16:19], v[178:181], v[236:239], v[16:19]
	v_mfma_f32_16x16x32_bf16 v[4:7], v[162:165], v[244:247], v[4:7]
	v_mfma_f32_16x16x32_bf16 v[0:3], v[178:181], v[244:247], v[0:3]
	v_mfma_f32_16x16x32_bf16 v[68:71], v[174:177], v[224:227], v[68:71]
	v_mfma_f32_16x16x32_bf16 v[64:67], v[182:185], v[224:227], v[64:67]
	v_mfma_f32_16x16x32_bf16 v[52:55], v[174:177], v[232:235], v[52:55]
	v_mfma_f32_16x16x32_bf16 v[48:51], v[182:185], v[232:235], v[48:51]
	v_mfma_f32_16x16x32_bf16 v[20:23], v[174:177], v[240:243], v[20:23]
	v_mfma_f32_16x16x32_bf16 v[16:19], v[182:185], v[240:243], v[16:19]
	v_mfma_f32_16x16x32_bf16 v[4:7], v[174:177], v[248:251], v[4:7]
	v_mfma_f32_16x16x32_bf16 v[0:3], v[182:185], v[248:251], v[0:3]
	s_waitcnt vmcnt(0)
	s_barrier
	s_add_i32 s56, s56, 2
	s_add_u32 s12, s12, 0x100
	s_addc_u32 s13, s13, 0
	s_add_u32 s54, s54, 0x100
	s_addc_u32 s55, s55, 0
	s_cmp_gt_u32 s56, 29
	s_cbranch_scc0 .LBB0_846
	s_branch .Lk64_done_p6
.Lk64_trail_p6:
	s_setprio 1
	s_sub_u32 vcc_lo, s12, 0x80000
	s_subb_u32 vcc_hi, s13, 0
	s_add_i32 m0, s37, 0xa000
	s_nop 0
	global_load_lds_dwordx4 v146, vcc
	s_add_u32 vcc_lo, vcc_lo, 0x20000
	s_addc_u32 vcc_hi, vcc_hi, 0
	s_add_i32 m0, s37, 0x9000
	s_nop 0
	global_load_lds_dwordx4 v150, vcc
	s_add_u32 vcc_lo, vcc_lo, 0x60000
	s_addc_u32 vcc_hi, vcc_hi, 0
	s_add_i32 m0, s37, 0xe000
	s_nop 0
	global_load_lds_dwordx4 v146, vcc
	s_add_u32 vcc_lo, vcc_lo, 0x20000
	s_addc_u32 vcc_hi, vcc_hi, 0
	s_add_i32 m0, s37, 0xd000
	s_nop 0
	global_load_lds_dwordx4 v150, vcc
	s_add_u32 vcc_lo, s34, 0x0
	s_addc_u32 vcc_hi, s35, 0
	s_mov_b32 m0, s37
	s_nop 0
	global_load_lds_dwordx4 v150, vcc
	s_sub_u32 vcc_lo, vcc_lo, 0x20000
	s_subb_u32 vcc_hi, vcc_hi, 0
	s_sub_i32 m0, s37, 0x1000
	s_nop 0
	global_load_lds_dwordx4 v150, vcc
	s_add_u32 vcc_lo, vcc_lo, 0xa0000
	s_addc_u32 vcc_hi, vcc_hi, 0
	s_add_i32 m0, s37, 0x4000
	s_nop 0
	global_load_lds_dwordx4 v150, vcc
	s_sub_u32 vcc_lo, vcc_lo, 0x20000
	s_subb_u32 vcc_hi, vcc_hi, 0
	s_add_i32 m0, s37, 0x3000
	s_nop 0
	global_load_lds_dwordx4 v150, vcc
	s_cmp_eq_u32 s56, 28
	s_cbranch_scc0 .Lk64_epd_p6_t
	s_lshl_b32 vcc_lo, s10, 10
	s_lshr_b32 vcc_hi, s37, 2
	s_add_i32 vcc_lo, vcc_lo, vcc_hi
	s_sub_i32 vcc_lo, vcc_lo, 0x400
	s_add_u32 vcc_lo, s18, vcc_lo
	s_addc_u32 vcc_hi, s19, 0
	v_and_b32_e32 v248, 63, v252
	v_lshlrev_b32_e32 v248, 2, v248
	s_lshr_b32 m0, s37, 2
	s_add_i32 m0, m0, 0x20000
	s_nop 0
	global_load_lds_dword v248, vcc
.Lk64_epd_p6_t:
	ds_read_b128 v[32:35], v169 offset:0
	ds_read_b128 v[36:39], v169 offset:1024
	ds_read_b128 v[40:43], v169 offset:2048
	ds_read_b128 v[44:47], v169 offset:3072
	ds_read_b128 v[162:165], v170 offset:0
	ds_read_b128 v[174:177], v170 offset:1024
	ds_read_b128 v[178:181], v170 offset:2048
	ds_read_b128 v[182:185], v170 offset:3072
	ds_read_b128 v[186:189], v171 offset:0
	ds_read_b128 v[190:193], v171 offset:1024
	ds_read_b128 v[194:197], v171 offset:2048
	ds_read_b128 v[198:201], v171 offset:3072
	ds_read_b128 v[202:205], v171 offset:4096
	ds_read_b128 v[206:209], v171 offset:5120
	ds_read_b128 v[210:213], v171 offset:6144
	ds_read_b128 v[214:217], v171 offset:7168
	ds_read_b128 v[220:223], v171 offset:16384
	ds_read_b128 v[224:227], v171 offset:17408
	ds_read_b128 v[228:231], v171 offset:18432
	ds_read_b128 v[232:235], v171 offset:19456
	ds_read_b128 v[236:239], v171 offset:20480
	ds_read_b128 v[240:243], v171 offset:21504
	ds_read_b128 v[244:247], v171 offset:22528
	ds_read_b128 v[248:251], v171 offset:23552
	s_nop 15
	s_nop 15
	s_waitcnt lgkmcnt(0)
	s_barrier
	v_mfma_f32_16x16x32_bf16 v[140:143], v[32:35], v[186:189], v[140:143]
	v_mfma_f32_16x16x32_bf16 v[136:139], v[40:43], v[186:189], v[136:139]
	v_mfma_f32_16x16x32_bf16 v[124:127], v[32:35], v[194:197], v[124:127]
	v_mfma_f32_16x16x32_bf16 v[120:123], v[40:43], v[194:197], v[120:123]
	v_mfma_f32_16x16x32_bf16 v[108:111], v[32:35], v[202:205], v[108:111]
	v_mfma_f32_16x16x32_bf16 v[104:107], v[40:43], v[202:205], v[104:107]
	v_mfma_f32_16x16x32_bf16 v[92:95], v[32:35], v[210:213], v[92:95]
	v_mfma_f32_16x16x32_bf16 v[88:91], v[40:43], v[210:213], v[88:91]
	v_mfma_f32_16x16x32_bf16 v[140:143], v[36:39], v[190:193], v[140:143]
	v_mfma_f32_16x16x32_bf16 v[136:139], v[44:47], v[190:193], v[136:139]
	v_mfma_f32_16x16x32_bf16 v[124:127], v[36:39], v[198:201], v[124:127]
	v_mfma_f32_16x16x32_bf16 v[120:123], v[44:47], v[198:201], v[120:123]
	v_mfma_f32_16x16x32_bf16 v[108:111], v[36:39], v[206:209], v[108:111]
	v_mfma_f32_16x16x32_bf16 v[104:107], v[44:47], v[206:209], v[104:107]
	v_mfma_f32_16x16x32_bf16 v[92:95], v[36:39], v[214:217], v[92:95]
	v_mfma_f32_16x16x32_bf16 v[88:91], v[44:47], v[214:217], v[88:91]
	v_mfma_f32_16x16x32_bf16 v[132:135], v[162:165], v[186:189], v[132:135]
	v_mfma_f32_16x16x32_bf16 v[128:131], v[178:181], v[186:189], v[128:131]
	v_mfma_f32_16x16x32_bf16 v[116:119], v[162:165], v[194:197], v[116:119]
	v_mfma_f32_16x16x32_bf16 v[112:115], v[178:181], v[194:197], v[112:115]
	v_mfma_f32_16x16x32_bf16 v[100:103], v[162:165], v[202:205], v[100:103]
	v_mfma_f32_16x16x32_bf16 v[96:99], v[178:181], v[202:205], v[96:99]
	v_mfma_f32_16x16x32_bf16 v[84:87], v[162:165], v[210:213], v[84:87]
	v_mfma_f32_16x16x32_bf16 v[80:83], v[178:181], v[210:213], v[80:83]
	v_mfma_f32_16x16x32_bf16 v[132:135], v[174:177], v[190:193], v[132:135]
	v_mfma_f32_16x16x32_bf16 v[128:131], v[182:185], v[190:193], v[128:131]
	v_mfma_f32_16x16x32_bf16 v[116:119], v[174:177], v[198:201], v[116:119]
	v_mfma_f32_16x16x32_bf16 v[112:115], v[182:185], v[198:201], v[112:115]
	v_mfma_f32_16x16x32_bf16 v[100:103], v[174:177], v[206:209], v[100:103]
	v_mfma_f32_16x16x32_bf16 v[96:99], v[182:185], v[206:209], v[96:99]
	v_mfma_f32_16x16x32_bf16 v[84:87], v[174:177], v[214:217], v[84:87]
	v_mfma_f32_16x16x32_bf16 v[80:83], v[182:185], v[214:217], v[80:83]
	v_mfma_f32_16x16x32_bf16 v[76:79], v[32:35], v[220:223], v[76:79]
	v_mfma_f32_16x16x32_bf16 v[72:75], v[40:43], v[220:223], v[72:75]
	v_mfma_f32_16x16x32_bf16 v[60:63], v[32:35], v[228:231], v[60:63]
	v_mfma_f32_16x16x32_bf16 v[56:59], v[40:43], v[228:231], v[56:59]
	v_mfma_f32_16x16x32_bf16 v[28:31], v[32:35], v[236:239], v[28:31]
	v_mfma_f32_16x16x32_bf16 v[24:27], v[40:43], v[236:239], v[24:27]
	v_mfma_f32_16x16x32_bf16 v[12:15], v[32:35], v[244:247], v[12:15]
	v_mfma_f32_16x16x32_bf16 v[8:11], v[40:43], v[244:247], v[8:11]
	v_mfma_f32_16x16x32_bf16 v[76:79], v[36:39], v[224:227], v[76:79]
	v_mfma_f32_16x16x32_bf16 v[72:75], v[44:47], v[224:227], v[72:75]
	v_mfma_f32_16x16x32_bf16 v[60:63], v[36:39], v[232:235], v[60:63]
	v_mfma_f32_16x16x32_bf16 v[56:59], v[44:47], v[232:235], v[56:59]
	v_mfma_f32_16x16x32_bf16 v[28:31], v[36:39], v[240:243], v[28:31]
	v_mfma_f32_16x16x32_bf16 v[24:27], v[44:47], v[240:243], v[24:27]
	v_mfma_f32_16x16x32_bf16 v[12:15], v[36:39], v[248:251], v[12:15]
	v_mfma_f32_16x16x32_bf16 v[8:11], v[44:47], v[248:251], v[8:11]
	v_mfma_f32_16x16x32_bf16 v[68:71], v[162:165], v[220:223], v[68:71]
	v_mfma_f32_16x16x32_bf16 v[64:67], v[178:181], v[220:223], v[64:67]
	v_mfma_f32_16x16x32_bf16 v[52:55], v[162:165], v[228:231], v[52:55]
	v_mfma_f32_16x16x32_bf16 v[48:51], v[178:181], v[228:231], v[48:51]
	v_mfma_f32_16x16x32_bf16 v[20:23], v[162:165], v[236:239], v[20:23]
	v_mfma_f32_16x16x32_bf16 v[16:19], v[178:181], v[236:239], v[16:19]
	v_mfma_f32_16x16x32_bf16 v[4:7], v[162:165], v[244:247], v[4:7]
	v_mfma_f32_16x16x32_bf16 v[0:3], v[178:181], v[244:247], v[0:3]
	v_mfma_f32_16x16x32_bf16 v[68:71], v[174:177], v[224:227], v[68:71]
	v_mfma_f32_16x16x32_bf16 v[64:67], v[182:185], v[224:227], v[64:67]
	v_mfma_f32_16x16x32_bf16 v[52:55], v[174:177], v[232:235], v[52:55]
	v_mfma_f32_16x16x32_bf16 v[48:51], v[182:185], v[232:235], v[48:51]
	v_mfma_f32_16x16x32_bf16 v[20:23], v[174:177], v[240:243], v[20:23]
	v_mfma_f32_16x16x32_bf16 v[16:19], v[182:185], v[240:243], v[16:19]
	v_mfma_f32_16x16x32_bf16 v[4:7], v[174:177], v[248:251], v[4:7]
	v_mfma_f32_16x16x32_bf16 v[0:3], v[182:185], v[248:251], v[0:3]
	s_waitcnt vmcnt(0)
	s_barrier
	s_add_u32 vcc_lo, s34, 0x0
	s_addc_u32 vcc_hi, s35, 0
	s_add_i32 m0, s37, 0x2000
	s_nop 0
	global_load_lds_dwordx4 v146, vcc
	s_add_u32 vcc_lo, vcc_lo, 0x20000
	s_addc_u32 vcc_hi, vcc_hi, 0
	s_add_i32 m0, s37, 0x1000
	s_nop 0
	global_load_lds_dwordx4 v150, vcc
	s_add_u32 vcc_lo, vcc_lo, 0x60000
	s_addc_u32 vcc_hi, vcc_hi, 0
	s_add_i32 m0, s37, 0x6000
	s_nop 0
	global_load_lds_dwordx4 v146, vcc
	s_add_u32 vcc_lo, vcc_lo, 0x20000
	s_addc_u32 vcc_hi, vcc_hi, 0
	s_add_i32 m0, s37, 0x5000
	s_nop 0
	global_load_lds_dwordx4 v150, vcc
	s_add_u32 vcc_lo, s34, 0x80
	s_addc_u32 vcc_hi, s35, 0
	s_add_i32 m0, s37, 0x8000
	s_nop 0
	global_load_lds_dwordx4 v150, vcc
	s_sub_u32 vcc_lo, vcc_lo, 0x20000
	s_subb_u32 vcc_hi, vcc_hi, 0
	s_add_i32 m0, s37, 0x7000
	s_nop 0
	global_load_lds_dwordx4 v150, vcc
	s_add_u32 vcc_lo, vcc_lo, 0xa0000
	s_addc_u32 vcc_hi, vcc_hi, 0
	s_add_i32 m0, s37, 0xc000
	s_nop 0
	global_load_lds_dwordx4 v150, vcc
	s_sub_u32 vcc_lo, vcc_lo, 0x20000
	s_subb_u32 vcc_hi, vcc_hi, 0
	s_add_i32 m0, s37, 0xb000
	s_nop 0
	global_load_lds_dwordx4 v150, vcc
	ds_read_b128 v[32:35], v169 offset:32768
	ds_read_b128 v[36:39], v169 offset:33792
	ds_read_b128 v[40:43], v169 offset:34816
	ds_read_b128 v[44:47], v169 offset:35840
	ds_read_b128 v[162:165], v170 offset:32768
	ds_read_b128 v[174:177], v170 offset:33792
	ds_read_b128 v[178:181], v170 offset:34816
	ds_read_b128 v[182:185], v170 offset:35840
	ds_read_b128 v[186:189], v171 offset:32768
	ds_read_b128 v[190:193], v171 offset:33792
	ds_read_b128 v[194:197], v171 offset:34816
	ds_read_b128 v[198:201], v171 offset:35840
	ds_read_b128 v[202:205], v171 offset:36864
	ds_read_b128 v[206:209], v171 offset:37888
	ds_read_b128 v[210:213], v171 offset:38912
	ds_read_b128 v[214:217], v171 offset:39936
	ds_read_b128 v[220:223], v171 offset:49152
	ds_read_b128 v[224:227], v171 offset:50176
	ds_read_b128 v[228:231], v171 offset:51200
	ds_read_b128 v[232:235], v171 offset:52224
	ds_read_b128 v[236:239], v171 offset:53248
	ds_read_b128 v[240:243], v171 offset:54272
	ds_read_b128 v[244:247], v171 offset:55296
	ds_read_b128 v[248:251], v171 offset:56320
	s_nop 15
	s_nop 15
	s_waitcnt lgkmcnt(0)
	s_barrier
	v_mfma_f32_16x16x32_bf16 v[140:143], v[32:35], v[186:189], v[140:143]
	v_mfma_f32_16x16x32_bf16 v[136:139], v[40:43], v[186:189], v[136:139]
	v_mfma_f32_16x16x32_bf16 v[124:127], v[32:35], v[194:197], v[124:127]
	v_mfma_f32_16x16x32_bf16 v[120:123], v[40:43], v[194:197], v[120:123]
	v_mfma_f32_16x16x32_bf16 v[108:111], v[32:35], v[202:205], v[108:111]
	v_mfma_f32_16x16x32_bf16 v[104:107], v[40:43], v[202:205], v[104:107]
	v_mfma_f32_16x16x32_bf16 v[92:95], v[32:35], v[210:213], v[92:95]
	v_mfma_f32_16x16x32_bf16 v[88:91], v[40:43], v[210:213], v[88:91]
	v_mfma_f32_16x16x32_bf16 v[140:143], v[36:39], v[190:193], v[140:143]
	v_mfma_f32_16x16x32_bf16 v[136:139], v[44:47], v[190:193], v[136:139]
	v_mfma_f32_16x16x32_bf16 v[124:127], v[36:39], v[198:201], v[124:127]
	v_mfma_f32_16x16x32_bf16 v[120:123], v[44:47], v[198:201], v[120:123]
	v_mfma_f32_16x16x32_bf16 v[108:111], v[36:39], v[206:209], v[108:111]
	v_mfma_f32_16x16x32_bf16 v[104:107], v[44:47], v[206:209], v[104:107]
	v_mfma_f32_16x16x32_bf16 v[92:95], v[36:39], v[214:217], v[92:95]
	v_mfma_f32_16x16x32_bf16 v[88:91], v[44:47], v[214:217], v[88:91]
	v_mfma_f32_16x16x32_bf16 v[132:135], v[162:165], v[186:189], v[132:135]
	v_mfma_f32_16x16x32_bf16 v[128:131], v[178:181], v[186:189], v[128:131]
	v_mfma_f32_16x16x32_bf16 v[116:119], v[162:165], v[194:197], v[116:119]
	v_mfma_f32_16x16x32_bf16 v[112:115], v[178:181], v[194:197], v[112:115]
	v_mfma_f32_16x16x32_bf16 v[100:103], v[162:165], v[202:205], v[100:103]
	v_mfma_f32_16x16x32_bf16 v[96:99], v[178:181], v[202:205], v[96:99]
	v_mfma_f32_16x16x32_bf16 v[84:87], v[162:165], v[210:213], v[84:87]
	v_mfma_f32_16x16x32_bf16 v[80:83], v[178:181], v[210:213], v[80:83]
	v_mfma_f32_16x16x32_bf16 v[132:135], v[174:177], v[190:193], v[132:135]
	v_mfma_f32_16x16x32_bf16 v[128:131], v[182:185], v[190:193], v[128:131]
	v_mfma_f32_16x16x32_bf16 v[116:119], v[174:177], v[198:201], v[116:119]
	v_mfma_f32_16x16x32_bf16 v[112:115], v[182:185], v[198:201], v[112:115]
	v_mfma_f32_16x16x32_bf16 v[100:103], v[174:177], v[206:209], v[100:103]
	v_mfma_f32_16x16x32_bf16 v[96:99], v[182:185], v[206:209], v[96:99]
	v_mfma_f32_16x16x32_bf16 v[84:87], v[174:177], v[214:217], v[84:87]
	v_mfma_f32_16x16x32_bf16 v[80:83], v[182:185], v[214:217], v[80:83]
	v_mfma_f32_16x16x32_bf16 v[76:79], v[32:35], v[220:223], v[76:79]
	v_mfma_f32_16x16x32_bf16 v[72:75], v[40:43], v[220:223], v[72:75]
	v_mfma_f32_16x16x32_bf16 v[60:63], v[32:35], v[228:231], v[60:63]
	v_mfma_f32_16x16x32_bf16 v[56:59], v[40:43], v[228:231], v[56:59]
	v_mfma_f32_16x16x32_bf16 v[28:31], v[32:35], v[236:239], v[28:31]
	v_mfma_f32_16x16x32_bf16 v[24:27], v[40:43], v[236:239], v[24:27]
	v_mfma_f32_16x16x32_bf16 v[12:15], v[32:35], v[244:247], v[12:15]
	v_mfma_f32_16x16x32_bf16 v[8:11], v[40:43], v[244:247], v[8:11]
	v_mfma_f32_16x16x32_bf16 v[76:79], v[36:39], v[224:227], v[76:79]
	v_mfma_f32_16x16x32_bf16 v[72:75], v[44:47], v[224:227], v[72:75]
	v_mfma_f32_16x16x32_bf16 v[60:63], v[36:39], v[232:235], v[60:63]
	v_mfma_f32_16x16x32_bf16 v[56:59], v[44:47], v[232:235], v[56:59]
	v_mfma_f32_16x16x32_bf16 v[28:31], v[36:39], v[240:243], v[28:31]
	v_mfma_f32_16x16x32_bf16 v[24:27], v[44:47], v[240:243], v[24:27]
	v_mfma_f32_16x16x32_bf16 v[12:15], v[36:39], v[248:251], v[12:15]
	v_mfma_f32_16x16x32_bf16 v[8:11], v[44:47], v[248:251], v[8:11]
	v_mfma_f32_16x16x32_bf16 v[68:71], v[162:165], v[220:223], v[68:71]
	v_mfma_f32_16x16x32_bf16 v[64:67], v[178:181], v[220:223], v[64:67]
	v_mfma_f32_16x16x32_bf16 v[52:55], v[162:165], v[228:231], v[52:55]
	v_mfma_f32_16x16x32_bf16 v[48:51], v[178:181], v[228:231], v[48:51]
	v_mfma_f32_16x16x32_bf16 v[20:23], v[162:165], v[236:239], v[20:23]
	v_mfma_f32_16x16x32_bf16 v[16:19], v[178:181], v[236:239], v[16:19]
	v_mfma_f32_16x16x32_bf16 v[4:7], v[162:165], v[244:247], v[4:7]
	v_mfma_f32_16x16x32_bf16 v[0:3], v[178:181], v[244:247], v[0:3]
	v_mfma_f32_16x16x32_bf16 v[68:71], v[174:177], v[224:227], v[68:71]
	v_mfma_f32_16x16x32_bf16 v[64:67], v[182:185], v[224:227], v[64:67]
	v_mfma_f32_16x16x32_bf16 v[52:55], v[174:177], v[232:235], v[52:55]
	v_mfma_f32_16x16x32_bf16 v[48:51], v[182:185], v[232:235], v[48:51]
	v_mfma_f32_16x16x32_bf16 v[20:23], v[174:177], v[240:243], v[20:23]
	v_mfma_f32_16x16x32_bf16 v[16:19], v[182:185], v[240:243], v[16:19]
	v_mfma_f32_16x16x32_bf16 v[4:7], v[174:177], v[248:251], v[4:7]
	v_mfma_f32_16x16x32_bf16 v[0:3], v[182:185], v[248:251], v[0:3]
	s_waitcnt vmcnt(0)
	s_barrier
	s_add_i32 s56, s56, 2
	s_add_u32 s12, s12, 0x100
	s_addc_u32 s13, s13, 0
	s_add_u32 s54, s54, 0x100
	s_addc_u32 s55, s55, 0
	s_cmp_gt_u32 s56, 29
	s_cbranch_scc0 .LBB0_846
.Lk64_done_p6:
	s_setprio 0
	s_and_b64 vcc, exec, s[16:17]
	s_cbranch_vccz .LBB0_849
	s_barrier

.LBB0_940:
	s_add_u32 s24, s22, 0x100
	s_addc_u32 s25, s23, 0
	s_cmpk_eq_i32 s56, 0x54
	s_cselect_b32 s29, s19, s25
	s_cselect_b32 s28, s18, s24
	s_cselect_b32 s27, s21, s47
	s_cselect_b32 s26, s20, s46
	s_and_b64 vcc, exec, s[12:13]
	s_cbranch_vccz .Lk64_trail_p7
	s_sub_u32 vcc_lo, s46, 0x80
	s_subb_u32 vcc_hi, s47, 0
	s_add_i32 m0, s30, 0x18000
	s_nop 0
	global_load_lds_dwordx4 v130, vcc
	s_add_i32 m0, s30, 0x1a000
	s_nop 0
	global_load_lds_dwordx4 v134, vcc
	s_add_u32 vcc_lo, vcc_lo, 0x58000
	s_addc_u32 vcc_hi, vcc_hi, 0
	s_add_i32 m0, s30, 0x19000
	s_nop 0
	global_load_lds_dwordx4 v130, vcc
	s_add_i32 m0, s30, 0x1b000
	s_nop 0
	global_load_lds_dwordx4 v134, vcc
	s_add_u32 vcc_lo, vcc_lo, 0x108000
	s_addc_u32 vcc_hi, vcc_hi, 0
	s_add_i32 m0, s30, 0x1c000
	s_nop 0
	global_load_lds_dwordx4 v130, vcc
	s_add_i32 m0, s30, 0x1e000
	s_nop 0
	global_load_lds_dwordx4 v134, vcc
	s_add_u32 vcc_lo, vcc_lo, 0x58000
	s_addc_u32 vcc_hi, vcc_hi, 0
	s_add_i32 m0, s30, 0x1d000
	s_nop 0
	global_load_lds_dwordx4 v130, vcc
	s_add_i32 m0, s30, 0x1f000
	s_nop 0
	global_load_lds_dwordx4 v134, vcc
	ds_read_b128 v[144:147], v185 offset:0
	ds_read_b128 v[148:151], v185 offset:1024
	ds_read_b128 v[152:155], v185 offset:2048
	ds_read_b128 v[156:159], v185 offset:3072
	ds_read_b128 v[160:163], v186 offset:0
	ds_read_b128 v[164:167], v186 offset:1024
	ds_read_b128 v[168:171], v186 offset:2048
	ds_read_b128 v[172:175], v186 offset:3072
	ds_read_b128 v[176:179], v187 offset:0
	ds_read_b128 v[190:193], v187 offset:1024
	ds_read_b128 v[194:197], v187 offset:2048
	ds_read_b128 v[198:201], v187 offset:3072
	ds_read_b128 v[202:205], v187 offset:4096
	ds_read_b128 v[206:209], v187 offset:5120
	ds_read_b128 v[210:213], v187 offset:6144
	ds_read_b128 v[214:217], v187 offset:7168
	ds_read_b128 v[220:223], v187 offset:16384
	ds_read_b128 v[224:227], v187 offset:17408
	ds_read_b128 v[228:231], v187 offset:18432
	ds_read_b128 v[232:235], v187 offset:19456
	ds_read_b128 v[236:239], v187 offset:20480
	ds_read_b128 v[240:243], v187 offset:21504
	ds_read_b128 v[244:247], v187 offset:22528
	ds_read_b128 v[248:251], v187 offset:23552
	s_nop 15
	s_nop 15
	s_waitcnt lgkmcnt(0)
	s_barrier
	v_mfma_f32_16x16x32_bf16 v[72:75], v[144:147], v[176:179], v[72:75]
	v_mfma_f32_16x16x32_bf16 v[76:79], v[152:155], v[176:179], v[76:79]
	v_mfma_f32_16x16x32_bf16 v[96:99], v[144:147], v[194:197], v[96:99]
	v_mfma_f32_16x16x32_bf16 v[100:103], v[152:155], v[194:197], v[100:103]
	v_mfma_f32_16x16x32_bf16 v[120:123], v[144:147], v[202:205], v[120:123]
	v_mfma_f32_16x16x32_bf16 v[124:127], v[152:155], v[202:205], v[124:127]
	v_mfma_f32_16x16x32_bf16 v[92:95], v[144:147], v[210:213], v[92:95]
	v_mfma_f32_16x16x32_bf16 v[84:87], v[152:155], v[210:213], v[84:87]
	v_mfma_f32_16x16x32_bf16 v[72:75], v[148:151], v[190:193], v[72:75]
	v_mfma_f32_16x16x32_bf16 v[76:79], v[156:159], v[190:193], v[76:79]
	v_mfma_f32_16x16x32_bf16 v[96:99], v[148:151], v[198:201], v[96:99]
	v_mfma_f32_16x16x32_bf16 v[100:103], v[156:159], v[198:201], v[100:103]
	v_mfma_f32_16x16x32_bf16 v[120:123], v[148:151], v[206:209], v[120:123]
	v_mfma_f32_16x16x32_bf16 v[124:127], v[156:159], v[206:209], v[124:127]
	v_mfma_f32_16x16x32_bf16 v[92:95], v[148:151], v[214:217], v[92:95]
	v_mfma_f32_16x16x32_bf16 v[84:87], v[156:159], v[214:217], v[84:87]
	v_mfma_f32_16x16x32_bf16 v[80:83], v[160:163], v[176:179], v[80:83]
	v_mfma_f32_16x16x32_bf16 v[88:91], v[168:171], v[176:179], v[88:91]
	v_mfma_f32_16x16x32_bf16 v[108:111], v[160:163], v[194:197], v[108:111]
	v_mfma_f32_16x16x32_bf16 v[112:115], v[168:171], v[194:197], v[112:115]
	v_mfma_f32_16x16x32_bf16 v[116:119], v[160:163], v[202:205], v[116:119]
	v_mfma_f32_16x16x32_bf16 v[104:107], v[168:171], v[202:205], v[104:107]
	v_mfma_f32_16x16x32_bf16 v[68:71], v[160:163], v[210:213], v[68:71]
	v_mfma_f32_16x16x32_bf16 v[64:67], v[168:171], v[210:213], v[64:67]
	v_mfma_f32_16x16x32_bf16 v[80:83], v[164:167], v[190:193], v[80:83]
	v_mfma_f32_16x16x32_bf16 v[88:91], v[172:175], v[190:193], v[88:91]
	v_mfma_f32_16x16x32_bf16 v[108:111], v[164:167], v[198:201], v[108:111]
	v_mfma_f32_16x16x32_bf16 v[112:115], v[172:175], v[198:201], v[112:115]
	v_mfma_f32_16x16x32_bf16 v[116:119], v[164:167], v[206:209], v[116:119]
	v_mfma_f32_16x16x32_bf16 v[104:107], v[172:175], v[206:209], v[104:107]
	v_mfma_f32_16x16x32_bf16 v[68:71], v[164:167], v[214:217], v[68:71]
	v_mfma_f32_16x16x32_bf16 v[64:67], v[172:175], v[214:217], v[64:67]
	v_mfma_f32_16x16x32_bf16 v[60:63], v[144:147], v[220:223], v[60:63]
	v_mfma_f32_16x16x32_bf16 v[56:59], v[152:155], v[220:223], v[56:59]
	v_mfma_f32_16x16x32_bf16 v[44:47], v[144:147], v[228:231], v[44:47]
	v_mfma_f32_16x16x32_bf16 v[40:43], v[152:155], v[228:231], v[40:43]
	v_mfma_f32_16x16x32_bf16 v[28:31], v[144:147], v[236:239], v[28:31]
	v_mfma_f32_16x16x32_bf16 v[24:27], v[152:155], v[236:239], v[24:27]
	v_mfma_f32_16x16x32_bf16 v[12:15], v[144:147], v[244:247], v[12:15]
	v_mfma_f32_16x16x32_bf16 v[8:11], v[152:155], v[244:247], v[8:11]
	v_mfma_f32_16x16x32_bf16 v[60:63], v[148:151], v[224:227], v[60:63]
	v_mfma_f32_16x16x32_bf16 v[56:59], v[156:159], v[224:227], v[56:59]
	v_mfma_f32_16x16x32_bf16 v[44:47], v[148:151], v[232:235], v[44:47]
	v_mfma_f32_16x16x32_bf16 v[40:43], v[156:159], v[232:235], v[40:43]
	v_mfma_f32_16x16x32_bf16 v[28:31], v[148:151], v[240:243], v[28:31]
	v_mfma_f32_16x16x32_bf16 v[24:27], v[156:159], v[240:243], v[24:27]
	v_mfma_f32_16x16x32_bf16 v[12:15], v[148:151], v[248:251], v[12:15]
	v_mfma_f32_16x16x32_bf16 v[8:11], v[156:159], v[248:251], v[8:11]
	v_mfma_f32_16x16x32_bf16 v[52:55], v[160:163], v[220:223], v[52:55]
	v_mfma_f32_16x16x32_bf16 v[48:51], v[168:171], v[220:223], v[48:51]
	v_mfma_f32_16x16x32_bf16 v[36:39], v[160:163], v[228:231], v[36:39]
	v_mfma_f32_16x16x32_bf16 v[32:35], v[168:171], v[228:231], v[32:35]
	v_mfma_f32_16x16x32_bf16 v[20:23], v[160:163], v[236:239], v[20:23]
	v_mfma_f32_16x16x32_bf16 v[16:19], v[168:171], v[236:239], v[16:19]
	v_mfma_f32_16x16x32_bf16 v[4:7], v[160:163], v[244:247], v[4:7]
	v_mfma_f32_16x16x32_bf16 v[0:3], v[168:171], v[244:247], v[0:3]
	v_mfma_f32_16x16x32_bf16 v[52:55], v[164:167], v[224:227], v[52:55]
	v_mfma_f32_16x16x32_bf16 v[48:51], v[172:175], v[224:227], v[48:51]
	v_mfma_f32_16x16x32_bf16 v[36:39], v[164:167], v[232:235], v[36:39]
	v_mfma_f32_16x16x32_bf16 v[32:35], v[172:175], v[232:235], v[32:35]
	v_mfma_f32_16x16x32_bf16 v[20:23], v[164:167], v[240:243], v[20:23]
	v_mfma_f32_16x16x32_bf16 v[16:19], v[172:175], v[240:243], v[16:19]
	v_mfma_f32_16x16x32_bf16 v[4:7], v[164:167], v[248:251], v[4:7]
	v_mfma_f32_16x16x32_bf16 v[0:3], v[172:175], v[248:251], v[0:3]
	s_waitcnt vmcnt(0)
	s_barrier
	s_add_u32 vcc_lo, s26, 0x0
	s_addc_u32 vcc_hi, s27, 0
	s_add_i32 m0, s30, 0x10000
	s_nop 0
	global_load_lds_dwordx4 v130, vcc
	s_add_i32 m0, s30, 0x12000
	s_nop 0
	global_load_lds_dwordx4 v134, vcc
	s_add_u32 vcc_lo, vcc_lo, 0x58000
	s_addc_u32 vcc_hi, vcc_hi, 0
	s_add_i32 m0, s30, 0x11000
	s_nop 0
	global_load_lds_dwordx4 v130, vcc
	s_add_i32 m0, s30, 0x13000
	s_nop 0
	global_load_lds_dwordx4 v134, vcc
	s_add_u32 vcc_lo, vcc_lo, 0x108000
	s_addc_u32 vcc_hi, vcc_hi, 0
	s_add_i32 m0, s30, 0x14000
	s_nop 0
	global_load_lds_dwordx4 v130, vcc
	s_add_i32 m0, s30, 0x16000
	s_nop 0
	global_load_lds_dwordx4 v134, vcc
	s_add_u32 vcc_lo, vcc_lo, 0x58000
	s_addc_u32 vcc_hi, vcc_hi, 0
	s_add_i32 m0, s30, 0x15000
	s_nop 0
	global_load_lds_dwordx4 v130, vcc
	s_add_i32 m0, s30, 0x17000
	s_nop 0
	global_load_lds_dwordx4 v134, vcc
	ds_read_b128 v[144:147], v185 offset:32768
	ds_read_b128 v[148:151], v185 offset:33792
	ds_read_b128 v[152:155], v185 offset:34816
	ds_read_b128 v[156:159], v185 offset:35840
	ds_read_b128 v[160:163], v186 offset:32768
	ds_read_b128 v[164:167], v186 offset:33792
	ds_read_b128 v[168:171], v186 offset:34816
	ds_read_b128 v[172:175], v186 offset:35840
	ds_read_b128 v[176:179], v187 offset:32768
	ds_read_b128 v[190:193], v187 offset:33792
	ds_read_b128 v[194:197], v187 offset:34816
	ds_read_b128 v[198:201], v187 offset:35840
	ds_read_b128 v[202:205], v187 offset:36864
	ds_read_b128 v[206:209], v187 offset:37888
	ds_read_b128 v[210:213], v187 offset:38912
	ds_read_b128 v[214:217], v187 offset:39936
	ds_read_b128 v[220:223], v187 offset:49152
	ds_read_b128 v[224:227], v187 offset:50176
	ds_read_b128 v[228:231], v187 offset:51200
	ds_read_b128 v[232:235], v187 offset:52224
	ds_read_b128 v[236:239], v187 offset:53248
	ds_read_b128 v[240:243], v187 offset:54272
	ds_read_b128 v[244:247], v187 offset:55296
	ds_read_b128 v[248:251], v187 offset:56320
	s_nop 15
	s_nop 15
	s_waitcnt lgkmcnt(0)
	s_barrier
	v_mfma_f32_16x16x32_bf16 v[72:75], v[144:147], v[176:179], v[72:75]
	v_mfma_f32_16x16x32_bf16 v[76:79], v[152:155], v[176:179], v[76:79]
	v_mfma_f32_16x16x32_bf16 v[96:99], v[144:147], v[194:197], v[96:99]
	v_mfma_f32_16x16x32_bf16 v[100:103], v[152:155], v[194:197], v[100:103]
	v_mfma_f32_16x16x32_bf16 v[120:123], v[144:147], v[202:205], v[120:123]
	v_mfma_f32_16x16x32_bf16 v[124:127], v[152:155], v[202:205], v[124:127]
	v_mfma_f32_16x16x32_bf16 v[92:95], v[144:147], v[210:213], v[92:95]
	v_mfma_f32_16x16x32_bf16 v[84:87], v[152:155], v[210:213], v[84:87]
	v_mfma_f32_16x16x32_bf16 v[72:75], v[148:151], v[190:193], v[72:75]
	v_mfma_f32_16x16x32_bf16 v[76:79], v[156:159], v[190:193], v[76:79]
	v_mfma_f32_16x16x32_bf16 v[96:99], v[148:151], v[198:201], v[96:99]
	v_mfma_f32_16x16x32_bf16 v[100:103], v[156:159], v[198:201], v[100:103]
	v_mfma_f32_16x16x32_bf16 v[120:123], v[148:151], v[206:209], v[120:123]
	v_mfma_f32_16x16x32_bf16 v[124:127], v[156:159], v[206:209], v[124:127]
	v_mfma_f32_16x16x32_bf16 v[92:95], v[148:151], v[214:217], v[92:95]
	v_mfma_f32_16x16x32_bf16 v[84:87], v[156:159], v[214:217], v[84:87]
	v_mfma_f32_16x16x32_bf16 v[80:83], v[160:163], v[176:179], v[80:83]
	v_mfma_f32_16x16x32_bf16 v[88:91], v[168:171], v[176:179], v[88:91]
	v_mfma_f32_16x16x32_bf16 v[108:111], v[160:163], v[194:197], v[108:111]
	v_mfma_f32_16x16x32_bf16 v[112:115], v[168:171], v[194:197], v[112:115]
	v_mfma_f32_16x16x32_bf16 v[116:119], v[160:163], v[202:205], v[116:119]
	v_mfma_f32_16x16x32_bf16 v[104:107], v[168:171], v[202:205], v[104:107]
	v_mfma_f32_16x16x32_bf16 v[68:71], v[160:163], v[210:213], v[68:71]
	v_mfma_f32_16x16x32_bf16 v[64:67], v[168:171], v[210:213], v[64:67]
	v_mfma_f32_16x16x32_bf16 v[80:83], v[164:167], v[190:193], v[80:83]
	v_mfma_f32_16x16x32_bf16 v[88:91], v[172:175], v[190:193], v[88:91]
	v_mfma_f32_16x16x32_bf16 v[108:111], v[164:167], v[198:201], v[108:111]
	v_mfma_f32_16x16x32_bf16 v[112:115], v[172:175], v[198:201], v[112:115]
	v_mfma_f32_16x16x32_bf16 v[116:119], v[164:167], v[206:209], v[116:119]
	v_mfma_f32_16x16x32_bf16 v[104:107], v[172:175], v[206:209], v[104:107]
	v_mfma_f32_16x16x32_bf16 v[68:71], v[164:167], v[214:217], v[68:71]
	v_mfma_f32_16x16x32_bf16 v[64:67], v[172:175], v[214:217], v[64:67]
	v_mfma_f32_16x16x32_bf16 v[60:63], v[144:147], v[220:223], v[60:63]
	v_mfma_f32_16x16x32_bf16 v[56:59], v[152:155], v[220:223], v[56:59]
	v_mfma_f32_16x16x32_bf16 v[44:47], v[144:147], v[228:231], v[44:47]
	v_mfma_f32_16x16x32_bf16 v[40:43], v[152:155], v[228:231], v[40:43]
	v_mfma_f32_16x16x32_bf16 v[28:31], v[144:147], v[236:239], v[28:31]
	v_mfma_f32_16x16x32_bf16 v[24:27], v[152:155], v[236:239], v[24:27]
	v_mfma_f32_16x16x32_bf16 v[12:15], v[144:147], v[244:247], v[12:15]
	v_mfma_f32_16x16x32_bf16 v[8:11], v[152:155], v[244:247], v[8:11]
	v_mfma_f32_16x16x32_bf16 v[60:63], v[148:151], v[224:227], v[60:63]
	v_mfma_f32_16x16x32_bf16 v[56:59], v[156:159], v[224:227], v[56:59]
	v_mfma_f32_16x16x32_bf16 v[44:47], v[148:151], v[232:235], v[44:47]
	v_mfma_f32_16x16x32_bf16 v[40:43], v[156:159], v[232:235], v[40:43]
	v_mfma_f32_16x16x32_bf16 v[28:31], v[148:151], v[240:243], v[28:31]
	v_mfma_f32_16x16x32_bf16 v[24:27], v[156:159], v[240:243], v[24:27]
	v_mfma_f32_16x16x32_bf16 v[12:15], v[148:151], v[248:251], v[12:15]
	v_mfma_f32_16x16x32_bf16 v[8:11], v[156:159], v[248:251], v[8:11]
	v_mfma_f32_16x16x32_bf16 v[52:55], v[160:163], v[220:223], v[52:55]
	v_mfma_f32_16x16x32_bf16 v[48:51], v[168:171], v[220:223], v[48:51]
	v_mfma_f32_16x16x32_bf16 v[36:39], v[160:163], v[228:231], v[36:39]
	v_mfma_f32_16x16x32_bf16 v[32:35], v[168:171], v[228:231], v[32:35]
	v_mfma_f32_16x16x32_bf16 v[20:23], v[160:163], v[236:239], v[20:23]
	v_mfma_f32_16x16x32_bf16 v[16:19], v[168:171], v[236:239], v[16:19]
	v_mfma_f32_16x16x32_bf16 v[4:7], v[160:163], v[244:247], v[4:7]
	v_mfma_f32_16x16x32_bf16 v[0:3], v[168:171], v[244:247], v[0:3]
	v_mfma_f32_16x16x32_bf16 v[52:55], v[164:167], v[224:227], v[52:55]
	v_mfma_f32_16x16x32_bf16 v[48:51], v[172:175], v[224:227], v[48:51]
	v_mfma_f32_16x16x32_bf16 v[36:39], v[164:167], v[232:235], v[36:39]
	v_mfma_f32_16x16x32_bf16 v[32:35], v[172:175], v[232:235], v[32:35]
	v_mfma_f32_16x16x32_bf16 v[20:23], v[164:167], v[240:243], v[20:23]
	v_mfma_f32_16x16x32_bf16 v[16:19], v[172:175], v[240:243], v[16:19]
	v_mfma_f32_16x16x32_bf16 v[4:7], v[164:167], v[248:251], v[4:7]
	v_mfma_f32_16x16x32_bf16 v[0:3], v[172:175], v[248:251], v[0:3]
	s_waitcnt vmcnt(0)
	s_barrier
	s_add_i32 s56, s56, 2
	s_add_u32 s46, s46, 0x100
	s_addc_u32 s47, s47, 0
	s_cmpk_gt_u32 s56, 0x55
	s_mov_b64 s[22:23], s[24:25]
	s_cbranch_scc0 .LBB0_940
	s_branch .Lk64_done_p7
.Lk64_trail_p7:
	s_setprio 1
	s_add_u32 vcc_lo, s22, 0x80
	s_addc_u32 vcc_hi, s23, 0
	s_add_i32 m0, s30, 0xa000
	s_nop 0
	global_load_lds_dwordx4 v132, vcc
	s_add_u32 vcc_lo, vcc_lo, 0x58000
	s_addc_u32 vcc_hi, vcc_hi, 0
	s_add_i32 m0, s30, 0x9000
	s_nop 0
	global_load_lds_dwordx4 v128, vcc
	s_add_u32 vcc_lo, vcc_lo, 0x108000
	s_addc_u32 vcc_hi, vcc_hi, 0
	s_add_i32 m0, s30, 0xe000
	s_nop 0
	global_load_lds_dwordx4 v132, vcc
	s_add_u32 vcc_lo, vcc_lo, 0x58000
	s_addc_u32 vcc_hi, vcc_hi, 0
	s_add_i32 m0, s30, 0xd000
	s_nop 0
	global_load_lds_dwordx4 v128, vcc
	s_add_u32 vcc_lo, s28, 0x0
	s_addc_u32 vcc_hi, s29, 0
	s_mov_b32 m0, s30
	s_nop 0
	global_load_lds_dwordx4 v128, vcc
	s_sub_u32 vcc_lo, vcc_lo, 0x58000
	s_subb_u32 vcc_hi, vcc_hi, 0
	s_sub_i32 m0, s30, 0x1000
	s_nop 0
	global_load_lds_dwordx4 v128, vcc
	s_add_u32 vcc_lo, vcc_lo, 0x1b8000
	s_addc_u32 vcc_hi, vcc_hi, 0
	s_add_i32 m0, s30, 0x4000
	s_nop 0
	global_load_lds_dwordx4 v128, vcc
	s_sub_u32 vcc_lo, vcc_lo, 0x58000
	s_subb_u32 vcc_hi, vcc_hi, 0
	s_add_i32 m0, s30, 0x3000
	s_nop 0
	global_load_lds_dwordx4 v128, vcc
	ds_read_b128 v[144:147], v185 offset:0
	ds_read_b128 v[148:151], v185 offset:1024
	ds_read_b128 v[152:155], v185 offset:2048
	ds_read_b128 v[156:159], v185 offset:3072
	ds_read_b128 v[160:163], v186 offset:0
	ds_read_b128 v[164:167], v186 offset:1024
	ds_read_b128 v[168:171], v186 offset:2048
	ds_read_b128 v[172:175], v186 offset:3072
	ds_read_b128 v[176:179], v187 offset:0
	ds_read_b128 v[190:193], v187 offset:1024
	ds_read_b128 v[194:197], v187 offset:2048
	ds_read_b128 v[198:201], v187 offset:3072
	ds_read_b128 v[202:205], v187 offset:4096
	ds_read_b128 v[206:209], v187 offset:5120
	ds_read_b128 v[210:213], v187 offset:6144
	ds_read_b128 v[214:217], v187 offset:7168
	ds_read_b128 v[220:223], v187 offset:16384
	ds_read_b128 v[224:227], v187 offset:17408
	ds_read_b128 v[228:231], v187 offset:18432
	ds_read_b128 v[232:235], v187 offset:19456
	ds_read_b128 v[236:239], v187 offset:20480
	ds_read_b128 v[240:243], v187 offset:21504
	ds_read_b128 v[244:247], v187 offset:22528
	ds_read_b128 v[248:251], v187 offset:23552
	s_nop 15
	s_nop 15
	s_waitcnt lgkmcnt(0)
	s_barrier
	v_mfma_f32_16x16x32_bf16 v[72:75], v[144:147], v[176:179], v[72:75]
	v_mfma_f32_16x16x32_bf16 v[76:79], v[152:155], v[176:179], v[76:79]
	v_mfma_f32_16x16x32_bf16 v[96:99], v[144:147], v[194:197], v[96:99]
	v_mfma_f32_16x16x32_bf16 v[100:103], v[152:155], v[194:197], v[100:103]
	v_mfma_f32_16x16x32_bf16 v[120:123], v[144:147], v[202:205], v[120:123]
	v_mfma_f32_16x16x32_bf16 v[124:127], v[152:155], v[202:205], v[124:127]
	v_mfma_f32_16x16x32_bf16 v[92:95], v[144:147], v[210:213], v[92:95]
	v_mfma_f32_16x16x32_bf16 v[84:87], v[152:155], v[210:213], v[84:87]
	v_mfma_f32_16x16x32_bf16 v[72:75], v[148:151], v[190:193], v[72:75]
	v_mfma_f32_16x16x32_bf16 v[76:79], v[156:159], v[190:193], v[76:79]
	v_mfma_f32_16x16x32_bf16 v[96:99], v[148:151], v[198:201], v[96:99]
	v_mfma_f32_16x16x32_bf16 v[100:103], v[156:159], v[198:201], v[100:103]
	v_mfma_f32_16x16x32_bf16 v[120:123], v[148:151], v[206:209], v[120:123]
	v_mfma_f32_16x16x32_bf16 v[124:127], v[156:159], v[206:209], v[124:127]
	v_mfma_f32_16x16x32_bf16 v[92:95], v[148:151], v[214:217], v[92:95]
	v_mfma_f32_16x16x32_bf16 v[84:87], v[156:159], v[214:217], v[84:87]
	v_mfma_f32_16x16x32_bf16 v[80:83], v[160:163], v[176:179], v[80:83]
	v_mfma_f32_16x16x32_bf16 v[88:91], v[168:171], v[176:179], v[88:91]
	v_mfma_f32_16x16x32_bf16 v[108:111], v[160:163], v[194:197], v[108:111]
	v_mfma_f32_16x16x32_bf16 v[112:115], v[168:171], v[194:197], v[112:115]
	v_mfma_f32_16x16x32_bf16 v[116:119], v[160:163], v[202:205], v[116:119]
	v_mfma_f32_16x16x32_bf16 v[104:107], v[168:171], v[202:205], v[104:107]
	v_mfma_f32_16x16x32_bf16 v[68:71], v[160:163], v[210:213], v[68:71]
	v_mfma_f32_16x16x32_bf16 v[64:67], v[168:171], v[210:213], v[64:67]
	v_mfma_f32_16x16x32_bf16 v[80:83], v[164:167], v[190:193], v[80:83]
	v_mfma_f32_16x16x32_bf16 v[88:91], v[172:175], v[190:193], v[88:91]
	v_mfma_f32_16x16x32_bf16 v[108:111], v[164:167], v[198:201], v[108:111]
	v_mfma_f32_16x16x32_bf16 v[112:115], v[172:175], v[198:201], v[112:115]
	v_mfma_f32_16x16x32_bf16 v[116:119], v[164:167], v[206:209], v[116:119]
	v_mfma_f32_16x16x32_bf16 v[104:107], v[172:175], v[206:209], v[104:107]
	v_mfma_f32_16x16x32_bf16 v[68:71], v[164:167], v[214:217], v[68:71]
	v_mfma_f32_16x16x32_bf16 v[64:67], v[172:175], v[214:217], v[64:67]
	v_mfma_f32_16x16x32_bf16 v[60:63], v[144:147], v[220:223], v[60:63]
	v_mfma_f32_16x16x32_bf16 v[56:59], v[152:155], v[220:223], v[56:59]
	v_mfma_f32_16x16x32_bf16 v[44:47], v[144:147], v[228:231], v[44:47]
	v_mfma_f32_16x16x32_bf16 v[40:43], v[152:155], v[228:231], v[40:43]
	v_mfma_f32_16x16x32_bf16 v[28:31], v[144:147], v[236:239], v[28:31]
	v_mfma_f32_16x16x32_bf16 v[24:27], v[152:155], v[236:239], v[24:27]
	v_mfma_f32_16x16x32_bf16 v[12:15], v[144:147], v[244:247], v[12:15]
	v_mfma_f32_16x16x32_bf16 v[8:11], v[152:155], v[244:247], v[8:11]
	v_mfma_f32_16x16x32_bf16 v[60:63], v[148:151], v[224:227], v[60:63]
	v_mfma_f32_16x16x32_bf16 v[56:59], v[156:159], v[224:227], v[56:59]
	v_mfma_f32_16x16x32_bf16 v[44:47], v[148:151], v[232:235], v[44:47]
	v_mfma_f32_16x16x32_bf16 v[40:43], v[156:159], v[232:235], v[40:43]
	v_mfma_f32_16x16x32_bf16 v[28:31], v[148:151], v[240:243], v[28:31]
	v_mfma_f32_16x16x32_bf16 v[24:27], v[156:159], v[240:243], v[24:27]
	v_mfma_f32_16x16x32_bf16 v[12:15], v[148:151], v[248:251], v[12:15]
	v_mfma_f32_16x16x32_bf16 v[8:11], v[156:159], v[248:251], v[8:11]
	v_mfma_f32_16x16x32_bf16 v[52:55], v[160:163], v[220:223], v[52:55]
	v_mfma_f32_16x16x32_bf16 v[48:51], v[168:171], v[220:223], v[48:51]
	v_mfma_f32_16x16x32_bf16 v[36:39], v[160:163], v[228:231], v[36:39]
	v_mfma_f32_16x16x32_bf16 v[32:35], v[168:171], v[228:231], v[32:35]
	v_mfma_f32_16x16x32_bf16 v[20:23], v[160:163], v[236:239], v[20:23]
	v_mfma_f32_16x16x32_bf16 v[16:19], v[168:171], v[236:239], v[16:19]
	v_mfma_f32_16x16x32_bf16 v[4:7], v[160:163], v[244:247], v[4:7]
	v_mfma_f32_16x16x32_bf16 v[0:3], v[168:171], v[244:247], v[0:3]
	v_mfma_f32_16x16x32_bf16 v[52:55], v[164:167], v[224:227], v[52:55]
	v_mfma_f32_16x16x32_bf16 v[48:51], v[172:175], v[224:227], v[48:51]
	v_mfma_f32_16x16x32_bf16 v[36:39], v[164:167], v[232:235], v[36:39]
	v_mfma_f32_16x16x32_bf16 v[32:35], v[172:175], v[232:235], v[32:35]
	v_mfma_f32_16x16x32_bf16 v[20:23], v[164:167], v[240:243], v[20:23]
	v_mfma_f32_16x16x32_bf16 v[16:19], v[172:175], v[240:243], v[16:19]
	v_mfma_f32_16x16x32_bf16 v[4:7], v[164:167], v[248:251], v[4:7]
	v_mfma_f32_16x16x32_bf16 v[0:3], v[172:175], v[248:251], v[0:3]
	s_waitcnt vmcnt(0)
	s_barrier
	s_add_u32 vcc_lo, s28, 0x0
	s_addc_u32 vcc_hi, s29, 0
	s_add_i32 m0, s30, 0x2000
	s_nop 0
	global_load_lds_dwordx4 v132, vcc
	s_add_u32 vcc_lo, vcc_lo, 0x58000
	s_addc_u32 vcc_hi, vcc_hi, 0
	s_add_i32 m0, s30, 0x1000
	s_nop 0
	global_load_lds_dwordx4 v128, vcc
	s_add_u32 vcc_lo, vcc_lo, 0x108000
	s_addc_u32 vcc_hi, vcc_hi, 0
	s_add_i32 m0, s30, 0x6000
	s_nop 0
	global_load_lds_dwordx4 v132, vcc
	s_add_u32 vcc_lo, vcc_lo, 0x58000
	s_addc_u32 vcc_hi, vcc_hi, 0
	s_add_i32 m0, s30, 0x5000
	s_nop 0
	global_load_lds_dwordx4 v128, vcc
	s_add_u32 vcc_lo, s28, 0x80
	s_addc_u32 vcc_hi, s29, 0
	s_add_i32 m0, s30, 0x8000
	s_nop 0
	global_load_lds_dwordx4 v128, vcc
	s_sub_u32 vcc_lo, vcc_lo, 0x58000
	s_subb_u32 vcc_hi, vcc_hi, 0
	s_add_i32 m0, s30, 0x7000
	s_nop 0
	global_load_lds_dwordx4 v128, vcc
	s_add_u32 vcc_lo, vcc_lo, 0x1b8000
	s_addc_u32 vcc_hi, vcc_hi, 0
	s_add_i32 m0, s30, 0xc000
	s_nop 0
	global_load_lds_dwordx4 v128, vcc
	s_sub_u32 vcc_lo, vcc_lo, 0x58000
	s_subb_u32 vcc_hi, vcc_hi, 0
	s_add_i32 m0, s30, 0xb000
	s_nop 0
	global_load_lds_dwordx4 v128, vcc
	ds_read_b128 v[144:147], v185 offset:32768
	ds_read_b128 v[148:151], v185 offset:33792
	ds_read_b128 v[152:155], v185 offset:34816
	ds_read_b128 v[156:159], v185 offset:35840
	ds_read_b128 v[160:163], v186 offset:32768
	ds_read_b128 v[164:167], v186 offset:33792
	ds_read_b128 v[168:171], v186 offset:34816
	ds_read_b128 v[172:175], v186 offset:35840
	ds_read_b128 v[176:179], v187 offset:32768
	ds_read_b128 v[190:193], v187 offset:33792
	ds_read_b128 v[194:197], v187 offset:34816
	ds_read_b128 v[198:201], v187 offset:35840
	ds_read_b128 v[202:205], v187 offset:36864
	ds_read_b128 v[206:209], v187 offset:37888
	ds_read_b128 v[210:213], v187 offset:38912
	ds_read_b128 v[214:217], v187 offset:39936
	ds_read_b128 v[220:223], v187 offset:49152
	ds_read_b128 v[224:227], v187 offset:50176
	ds_read_b128 v[228:231], v187 offset:51200
	ds_read_b128 v[232:235], v187 offset:52224
	ds_read_b128 v[236:239], v187 offset:53248
	ds_read_b128 v[240:243], v187 offset:54272
	ds_read_b128 v[244:247], v187 offset:55296
	ds_read_b128 v[248:251], v187 offset:56320
	s_nop 15
	s_nop 15
	s_waitcnt lgkmcnt(0)
	s_barrier
	v_mfma_f32_16x16x32_bf16 v[72:75], v[144:147], v[176:179], v[72:75]
	v_mfma_f32_16x16x32_bf16 v[76:79], v[152:155], v[176:179], v[76:79]
	v_mfma_f32_16x16x32_bf16 v[96:99], v[144:147], v[194:197], v[96:99]
	v_mfma_f32_16x16x32_bf16 v[100:103], v[152:155], v[194:197], v[100:103]
	v_mfma_f32_16x16x32_bf16 v[120:123], v[144:147], v[202:205], v[120:123]
	v_mfma_f32_16x16x32_bf16 v[124:127], v[152:155], v[202:205], v[124:127]
	v_mfma_f32_16x16x32_bf16 v[92:95], v[144:147], v[210:213], v[92:95]
	v_mfma_f32_16x16x32_bf16 v[84:87], v[152:155], v[210:213], v[84:87]
	v_mfma_f32_16x16x32_bf16 v[72:75], v[148:151], v[190:193], v[72:75]
	v_mfma_f32_16x16x32_bf16 v[76:79], v[156:159], v[190:193], v[76:79]
	v_mfma_f32_16x16x32_bf16 v[96:99], v[148:151], v[198:201], v[96:99]
	v_mfma_f32_16x16x32_bf16 v[100:103], v[156:159], v[198:201], v[100:103]
	v_mfma_f32_16x16x32_bf16 v[120:123], v[148:151], v[206:209], v[120:123]
	v_mfma_f32_16x16x32_bf16 v[124:127], v[156:159], v[206:209], v[124:127]
	v_mfma_f32_16x16x32_bf16 v[92:95], v[148:151], v[214:217], v[92:95]
	v_mfma_f32_16x16x32_bf16 v[84:87], v[156:159], v[214:217], v[84:87]
	v_mfma_f32_16x16x32_bf16 v[80:83], v[160:163], v[176:179], v[80:83]
	v_mfma_f32_16x16x32_bf16 v[88:91], v[168:171], v[176:179], v[88:91]
	v_mfma_f32_16x16x32_bf16 v[108:111], v[160:163], v[194:197], v[108:111]
	v_mfma_f32_16x16x32_bf16 v[112:115], v[168:171], v[194:197], v[112:115]
	v_mfma_f32_16x16x32_bf16 v[116:119], v[160:163], v[202:205], v[116:119]
	v_mfma_f32_16x16x32_bf16 v[104:107], v[168:171], v[202:205], v[104:107]
	v_mfma_f32_16x16x32_bf16 v[68:71], v[160:163], v[210:213], v[68:71]
	v_mfma_f32_16x16x32_bf16 v[64:67], v[168:171], v[210:213], v[64:67]
	v_mfma_f32_16x16x32_bf16 v[80:83], v[164:167], v[190:193], v[80:83]
	v_mfma_f32_16x16x32_bf16 v[88:91], v[172:175], v[190:193], v[88:91]
	v_mfma_f32_16x16x32_bf16 v[108:111], v[164:167], v[198:201], v[108:111]
	v_mfma_f32_16x16x32_bf16 v[112:115], v[172:175], v[198:201], v[112:115]
	v_mfma_f32_16x16x32_bf16 v[116:119], v[164:167], v[206:209], v[116:119]
	v_mfma_f32_16x16x32_bf16 v[104:107], v[172:175], v[206:209], v[104:107]
	v_mfma_f32_16x16x32_bf16 v[68:71], v[164:167], v[214:217], v[68:71]
	v_mfma_f32_16x16x32_bf16 v[64:67], v[172:175], v[214:217], v[64:67]
	v_mfma_f32_16x16x32_bf16 v[60:63], v[144:147], v[220:223], v[60:63]
	v_mfma_f32_16x16x32_bf16 v[56:59], v[152:155], v[220:223], v[56:59]
	v_mfma_f32_16x16x32_bf16 v[44:47], v[144:147], v[228:231], v[44:47]
	v_mfma_f32_16x16x32_bf16 v[40:43], v[152:155], v[228:231], v[40:43]
	v_mfma_f32_16x16x32_bf16 v[28:31], v[144:147], v[236:239], v[28:31]
	v_mfma_f32_16x16x32_bf16 v[24:27], v[152:155], v[236:239], v[24:27]
	v_mfma_f32_16x16x32_bf16 v[12:15], v[144:147], v[244:247], v[12:15]
	v_mfma_f32_16x16x32_bf16 v[8:11], v[152:155], v[244:247], v[8:11]
	v_mfma_f32_16x16x32_bf16 v[60:63], v[148:151], v[224:227], v[60:63]
	v_mfma_f32_16x16x32_bf16 v[56:59], v[156:159], v[224:227], v[56:59]
	v_mfma_f32_16x16x32_bf16 v[44:47], v[148:151], v[232:235], v[44:47]
	v_mfma_f32_16x16x32_bf16 v[40:43], v[156:159], v[232:235], v[40:43]
	v_mfma_f32_16x16x32_bf16 v[28:31], v[148:151], v[240:243], v[28:31]
	v_mfma_f32_16x16x32_bf16 v[24:27], v[156:159], v[240:243], v[24:27]
	v_mfma_f32_16x16x32_bf16 v[12:15], v[148:151], v[248:251], v[12:15]
	v_mfma_f32_16x16x32_bf16 v[8:11], v[156:159], v[248:251], v[8:11]
	v_mfma_f32_16x16x32_bf16 v[52:55], v[160:163], v[220:223], v[52:55]
	v_mfma_f32_16x16x32_bf16 v[48:51], v[168:171], v[220:223], v[48:51]
	v_mfma_f32_16x16x32_bf16 v[36:39], v[160:163], v[228:231], v[36:39]
	v_mfma_f32_16x16x32_bf16 v[32:35], v[168:171], v[228:231], v[32:35]
	v_mfma_f32_16x16x32_bf16 v[20:23], v[160:163], v[236:239], v[20:23]
	v_mfma_f32_16x16x32_bf16 v[16:19], v[168:171], v[236:239], v[16:19]
	v_mfma_f32_16x16x32_bf16 v[4:7], v[160:163], v[244:247], v[4:7]
	v_mfma_f32_16x16x32_bf16 v[0:3], v[168:171], v[244:247], v[0:3]
	v_mfma_f32_16x16x32_bf16 v[52:55], v[164:167], v[224:227], v[52:55]
	v_mfma_f32_16x16x32_bf16 v[48:51], v[172:175], v[224:227], v[48:51]
	v_mfma_f32_16x16x32_bf16 v[36:39], v[164:167], v[232:235], v[36:39]
	v_mfma_f32_16x16x32_bf16 v[32:35], v[172:175], v[232:235], v[32:35]
	v_mfma_f32_16x16x32_bf16 v[20:23], v[164:167], v[240:243], v[20:23]
	v_mfma_f32_16x16x32_bf16 v[16:19], v[172:175], v[240:243], v[16:19]
	v_mfma_f32_16x16x32_bf16 v[4:7], v[164:167], v[248:251], v[4:7]
	v_mfma_f32_16x16x32_bf16 v[0:3], v[172:175], v[248:251], v[0:3]
	s_waitcnt vmcnt(0)
	s_barrier
	s_add_i32 s56, s56, 2
	s_add_u32 s46, s46, 0x100
	s_addc_u32 s47, s47, 0
	s_cmpk_gt_u32 s56, 0x55
	s_mov_b64 s[22:23], s[24:25]
	s_cbranch_scc0 .LBB0_940
.Lk64_done_p7:
	s_setprio 0
	s_and_b64 vcc, exec, s[12:13]
	s_cbranch_vccz .LBB0_943
	s_barrier
